# prologue adaLN GEMV: silu evaluated once per (b,k) pair across lanes + readlane broadcast; pool linear as a single fmac chain with 12-deep LDS prefetch
# speedup vs baseline: 1.0222x; 1.0131x over previous
; __device__ __forceinline__ void p0a_prologue(const Params& a, LAS unsigned char* lds) {
;     ...
;     for (int bb = blockIdx.x; bb < 96; bb += G) {
;         float accb[NBATCH];
; #pragma unroll
;         for (int b = 0; b < NBATCH; ++b) accb[b] = 0.f;
;         const float* wa = a.in[I_WADA] + bb * 64 + lane;
;         for (int k0 = wave * 128; k0 < wave * 128 + 128; k0 += 16) {
;             float w[16];
; #pragma unroll
;             for (int kk = 0; kk < 16; ++kk) w[kk] = wa[(size_t)(k0 + kk) * 6144];
; #pragma unroll
;             for (int kk = 0; kk < 16; ++kk) {
; #pragma unroll
;                 for (int b = 0; b < NBATCH; ++b) { const float c = (b < 8) ? a.in[I_CP][b * DM + k0 + kk] : a.in[I_CS][k0 + kk]; accb[b] += (c / (1.0f + __expf(-c))) * w[kk]; } }
;         }
.LBB0_163:
	s_ashr_i32 s11, s10, 31
	v_lshl_add_u64 v[114:115], s[10:11], 2, v[112:113]
	s_mov_b64 s[20:21], s[42:43]
	s_mov_b64 s[44:45], s[40:41]
	s_mov_b32 s11, s2
	v_mov_b32_e32 v26, 0
	v_mov_b32_e32 v27, v111
	v_mov_b32_e32 v58, 0
	v_mov_b32_e32 v59, v111
	v_mov_b32_e32 v82, 0
	v_mov_b32_e32 v83, v111
	v_mov_b32_e32 v118, 0
	v_mov_b32_e32 v119, v111
	v_mov_b32_e32 v117, 0
	v_mbcnt_lo_u32_b32 v170, -1, 0
	v_mbcnt_hi_u32_b32 v170, -1, v170
	v_and_b32_e32 v173, 15, v170
	v_lshlrev_b32_e32 v173, 2, v173
	v_lshrrev_b32_e32 v171, 4, v170
	v_lshl_or_b32 v171, v171, 12, v173
	v_add_u32_e32 v172, 0x4000, v171
.LBB0_164:
	v_add_co_u32_e32 v2, vcc, 0xfffa6000, v114
	s_add_u32 s72, s20, s16
	s_nop 0
	v_addc_co_u32_e32 v3, vcc, -1, v115, vcc
	global_load_dword v144, v[2:3], off
	v_add_co_u32_e32 v2, vcc, 0xfffac000, v114
	s_addc_u32 s73, s21, s17
	s_nop 0
	v_addc_co_u32_e32 v3, vcc, -1, v115, vcc
	global_load_dword v142, v[2:3], off
	v_add_co_u32_e32 v2, vcc, 0xfffb2000, v114
	s_add_u32 s58, s44, s16
	s_nop 0
	v_addc_co_u32_e32 v3, vcc, -1, v115, vcc
	global_load_dword v140, v[2:3], off
	v_add_co_u32_e32 v2, vcc, 0xfffb8000, v114
	s_addc_u32 s59, s45, s17
	s_nop 0
	v_addc_co_u32_e32 v3, vcc, -1, v115, vcc
	global_load_dword v138, v[2:3], off
	v_add_co_u32_e32 v2, vcc, 0xfffbe000, v114
	s_add_u32 s70, s58, 0x1000
	s_nop 0
	v_addc_co_u32_e32 v3, vcc, -1, v115, vcc
	global_load_dword v130, v[2:3], off
	v_add_co_u32_e32 v2, vcc, 0xfffc4000, v114
	s_addc_u32 s71, s59, 0
	s_nop 0
	v_addc_co_u32_e32 v3, vcc, -1, v115, vcc
	global_load_dword v126, v[2:3], off
	v_add_co_u32_e32 v2, vcc, 0xfffca000, v114
	s_add_u32 s68, s58, 0x2000
	s_nop 0
	v_addc_co_u32_e32 v3, vcc, -1, v115, vcc
	global_load_dword v128, v[2:3], off
	v_add_co_u32_e32 v2, vcc, 0xfffd0000, v114
	s_addc_u32 s69, s59, 0
	s_nop 0
	v_addc_co_u32_e32 v3, vcc, -1, v115, vcc
	global_load_dword v129, v[2:3], off
	v_add_co_u32_e32 v2, vcc, 0xfffd6000, v114
	s_add_u32 s66, s58, 0x3000
	s_nop 0
	v_addc_co_u32_e32 v3, vcc, -1, v115, vcc
	global_load_dword v124, v[2:3], off
	v_add_co_u32_e32 v2, vcc, 0xfffdc000, v114
	s_addc_u32 s67, s59, 0
	s_nop 0
	v_addc_co_u32_e32 v3, vcc, -1, v115, vcc
	global_load_dword v125, v[2:3], off
	v_add_co_u32_e32 v2, vcc, 0xfffe2000, v114
	s_add_u32 s64, s58, 0x4000
	s_nop 0
	v_addc_co_u32_e32 v3, vcc, -1, v115, vcc
	global_load_dword v122, v[2:3], off
	v_add_co_u32_e32 v2, vcc, 0xfffe8000, v114
	s_addc_u32 s65, s59, 0
	s_nop 0
	v_addc_co_u32_e32 v3, vcc, -1, v115, vcc
	global_load_dword v123, v[2:3], off
	v_add_co_u32_e32 v2, vcc, 0xfffee000, v114
	s_add_u32 s62, s58, 0x5000
	s_nop 0
	v_addc_co_u32_e32 v3, vcc, -1, v115, vcc
	global_load_dword v120, v[2:3], off
	v_add_co_u32_e32 v2, vcc, 0xffff4000, v114
	s_addc_u32 s63, s59, 0
	s_nop 0
	v_addc_co_u32_e32 v3, vcc, -1, v115, vcc
	global_load_dword v121, v[2:3], off
	v_add_co_u32_e32 v2, vcc, 0xffffa000, v114
	s_add_u32 s60, s58, 0x6000
	s_nop 0
	v_addc_co_u32_e32 v3, vcc, -1, v115, vcc
	global_load_dword v116, v[2:3], off
	global_load_dword v110, v[114:115], off
	global_load_dword v174, v171, s[58:59]
	global_load_dword v175, v172, s[58:59]
	global_load_dword v176, v173, s[72:73]
	s_add_i32 s11, s11, 16
	s_add_u32 s44, s44, 64
	s_addc_u32 s45, s45, 0
	s_add_u32 s20, s20, 64
	s_addc_u32 s21, s21, 0
	v_lshl_add_u64 v[114:115], v[114:115], 0, s[18:19]
	s_waitcnt vmcnt(0)
	v_mul_f32_e32 v177, 0xbfb8aa3b, v174
	v_exp_f32_e32 v177, v177
	s_nop 0
	v_add_f32_e32 v177, 1.0, v177
	v_div_scale_f32 v178, s[14:15], v177, v177, v174
	v_rcp_f32_e32 v179, v178
	s_nop 0
	v_fma_f32 v180, -v178, v179, 1.0
	v_fmac_f32_e32 v179, v180, v179
	v_div_scale_f32 v180, vcc, v174, v177, v174
	v_mul_f32_e32 v181, v180, v179
	v_fma_f32 v182, -v178, v181, v180
	v_fmac_f32_e32 v181, v182, v179
	v_fma_f32 v178, -v178, v181, v180
	v_div_fmas_f32 v178, v178, v179, v181
	v_div_fixup_f32 v174, v178, v177, v174
	v_mul_f32_e32 v177, 0xbfb8aa3b, v175
	v_exp_f32_e32 v177, v177
	s_nop 0
	v_add_f32_e32 v177, 1.0, v177
	v_div_scale_f32 v178, s[14:15], v177, v177, v175
	v_rcp_f32_e32 v179, v178
	s_nop 0
	v_fma_f32 v180, -v178, v179, 1.0
	v_fmac_f32_e32 v179, v180, v179
	v_div_scale_f32 v180, vcc, v175, v177, v175
	v_mul_f32_e32 v181, v180, v179
	v_fma_f32 v182, -v178, v181, v180
	v_fmac_f32_e32 v181, v182, v179
	v_fma_f32 v178, -v178, v181, v180
	v_div_fmas_f32 v178, v178, v179, v181
	v_div_fixup_f32 v175, v178, v177, v175
	v_mul_f32_e32 v177, 0xbfb8aa3b, v176
	v_exp_f32_e32 v177, v177
	s_nop 0
	v_add_f32_e32 v177, 1.0, v177
	v_div_scale_f32 v178, s[14:15], v177, v177, v176
	v_rcp_f32_e32 v179, v178
	s_nop 0
	v_fma_f32 v180, -v178, v179, 1.0
	v_fmac_f32_e32 v179, v180, v179
	v_div_scale_f32 v180, vcc, v176, v177, v176
	v_mul_f32_e32 v181, v180, v179
	v_fma_f32 v182, -v178, v181, v180
	v_fmac_f32_e32 v181, v182, v179
	v_fma_f32 v178, -v178, v181, v180
	v_div_fmas_f32 v178, v178, v179, v181
	v_div_fixup_f32 v176, v178, v177, v176
	v_readlane_b32 s60, v174, 0
	v_readlane_b32 s61, v174, 16
	v_readlane_b32 s62, v174, 32
	v_readlane_b32 s63, v174, 48
	v_readlane_b32 s64, v175, 0
	v_readlane_b32 s65, v175, 16
	v_readlane_b32 s66, v175, 32
	v_readlane_b32 s67, v175, 48
	v_readlane_b32 s68, v176, 0
	v_fmac_f32_e32 v26, s60, v144
	v_fmac_f32_e32 v27, s61, v144
	v_fmac_f32_e32 v58, s62, v144
	v_fmac_f32_e32 v59, s63, v144
	v_fmac_f32_e32 v82, s64, v144
	v_fmac_f32_e32 v83, s65, v144
	v_fmac_f32_e32 v118, s66, v144
	v_fmac_f32_e32 v119, s67, v144
	v_fmac_f32_e32 v117, s68, v144
	v_readlane_b32 s60, v174, 1
	v_readlane_b32 s61, v174, 17
	v_readlane_b32 s62, v174, 33
	v_readlane_b32 s63, v174, 49
	v_readlane_b32 s64, v175, 1
	v_readlane_b32 s65, v175, 17
	v_readlane_b32 s66, v175, 33
; __device__ __forceinline__ void p0a_prologue(const Params& a, LAS unsigned char* lds) {
;     ...
;         for (int k0 = wave * 128; k0 < wave * 128 + 128; k0 += 16) {
;             float w[16];
; #pragma unroll
;             for (int kk = 0; kk < 16; ++kk) w[kk] = wa[(size_t)(k0 + kk) * 6144];
; #pragma unroll
;             for (int kk = 0; kk < 16; ++kk) {
; #pragma unroll
;                 for (int b = 0; b < NBATCH; ++b) { const float c = (b < 8) ? a.in[I_CP][b * DM + k0 + kk] : a.in[I_CS][k0 + kk]; accb[b] += (c / (1.0f + __expf(-c))) * w[kk]; } }
;         }
	v_readlane_b32 s67, v175, 49
	v_readlane_b32 s68, v176, 1
	v_fmac_f32_e32 v26, s60, v142
	v_fmac_f32_e32 v27, s61, v142
	v_fmac_f32_e32 v58, s62, v142
	v_fmac_f32_e32 v59, s63, v142
	v_fmac_f32_e32 v82, s64, v142
	v_fmac_f32_e32 v83, s65, v142
	v_fmac_f32_e32 v118, s66, v142
	v_fmac_f32_e32 v119, s67, v142
	v_fmac_f32_e32 v117, s68, v142
	v_readlane_b32 s60, v174, 2
	v_readlane_b32 s61, v174, 18
	v_readlane_b32 s62, v174, 34
	v_readlane_b32 s63, v174, 50
	v_readlane_b32 s64, v175, 2
	v_readlane_b32 s65, v175, 18
	v_readlane_b32 s66, v175, 34
	v_readlane_b32 s67, v175, 50
	v_readlane_b32 s68, v176, 2
	v_fmac_f32_e32 v26, s60, v140
	v_fmac_f32_e32 v27, s61, v140
	v_fmac_f32_e32 v58, s62, v140
	v_fmac_f32_e32 v59, s63, v140
	v_fmac_f32_e32 v82, s64, v140
	v_fmac_f32_e32 v83, s65, v140
	v_fmac_f32_e32 v118, s66, v140
	v_fmac_f32_e32 v119, s67, v140
	v_fmac_f32_e32 v117, s68, v140
	v_readlane_b32 s60, v174, 3
	v_readlane_b32 s61, v174, 19
	v_readlane_b32 s62, v174, 35
	v_readlane_b32 s63, v174, 51
	v_readlane_b32 s64, v175, 3
	v_readlane_b32 s65, v175, 19
	v_readlane_b32 s66, v175, 35
	v_readlane_b32 s67, v175, 51
	v_readlane_b32 s68, v176, 3
	v_fmac_f32_e32 v26, s60, v138
	v_fmac_f32_e32 v27, s61, v138
	v_fmac_f32_e32 v58, s62, v138
	v_fmac_f32_e32 v59, s63, v138
	v_fmac_f32_e32 v82, s64, v138
	v_fmac_f32_e32 v83, s65, v138
	v_fmac_f32_e32 v118, s66, v138
	v_fmac_f32_e32 v119, s67, v138
	v_fmac_f32_e32 v117, s68, v138
	v_readlane_b32 s60, v174, 4
	v_readlane_b32 s61, v174, 20
	v_readlane_b32 s62, v174, 36
	v_readlane_b32 s63, v174, 52
	v_readlane_b32 s64, v175, 4
	v_readlane_b32 s65, v175, 20
	v_readlane_b32 s66, v175, 36
	v_readlane_b32 s67, v175, 52
	v_readlane_b32 s68, v176, 4
	v_fmac_f32_e32 v26, s60, v130
	v_fmac_f32_e32 v27, s61, v130
	v_fmac_f32_e32 v58, s62, v130
	v_fmac_f32_e32 v59, s63, v130
	v_fmac_f32_e32 v82, s64, v130
	v_fmac_f32_e32 v83, s65, v130
	v_fmac_f32_e32 v118, s66, v130
	v_fmac_f32_e32 v119, s67, v130
	v_fmac_f32_e32 v117, s68, v130
	v_readlane_b32 s60, v174, 5
	v_readlane_b32 s61, v174, 21
	v_readlane_b32 s62, v174, 37
	v_readlane_b32 s63, v174, 53
	v_readlane_b32 s64, v175, 5
	v_readlane_b32 s65, v175, 21
	v_readlane_b32 s66, v175, 37
	v_readlane_b32 s67, v175, 53
	v_readlane_b32 s68, v176, 5
	v_fmac_f32_e32 v26, s60, v126
	v_fmac_f32_e32 v27, s61, v126
	v_fmac_f32_e32 v58, s62, v126
	v_fmac_f32_e32 v59, s63, v126
	v_fmac_f32_e32 v82, s64, v126
	v_fmac_f32_e32 v83, s65, v126
	v_fmac_f32_e32 v118, s66, v126
	v_fmac_f32_e32 v119, s67, v126
	v_fmac_f32_e32 v117, s68, v126
	v_readlane_b32 s60, v174, 6
	v_readlane_b32 s61, v174, 22
	v_readlane_b32 s62, v174, 38
	v_readlane_b32 s63, v174, 54
	v_readlane_b32 s64, v175, 6
	v_readlane_b32 s65, v175, 22
	v_readlane_b32 s66, v175, 38
	v_readlane_b32 s67, v175, 54
	v_readlane_b32 s68, v176, 6
	v_fmac_f32_e32 v26, s60, v128
	v_fmac_f32_e32 v27, s61, v128
	v_fmac_f32_e32 v58, s62, v128
	v_fmac_f32_e32 v59, s63, v128
	v_fmac_f32_e32 v82, s64, v128
	v_fmac_f32_e32 v83, s65, v128
	v_fmac_f32_e32 v118, s66, v128
	v_fmac_f32_e32 v119, s67, v128
	v_fmac_f32_e32 v117, s68, v128
	v_readlane_b32 s60, v174, 7
	v_readlane_b32 s61, v174, 23
	v_readlane_b32 s62, v174, 39
	v_readlane_b32 s63, v174, 55
	v_readlane_b32 s64, v175, 7
	v_readlane_b32 s65, v175, 23
	v_readlane_b32 s66, v175, 39
	v_readlane_b32 s67, v175, 55
	v_readlane_b32 s68, v176, 7
	v_fmac_f32_e32 v26, s60, v129
	v_fmac_f32_e32 v27, s61, v129
	v_fmac_f32_e32 v58, s62, v129
	v_fmac_f32_e32 v59, s63, v129
	v_fmac_f32_e32 v82, s64, v129
	v_fmac_f32_e32 v83, s65, v129
	v_fmac_f32_e32 v118, s66, v129
	v_fmac_f32_e32 v119, s67, v129
	v_fmac_f32_e32 v117, s68, v129
	v_readlane_b32 s60, v174, 8
	v_readlane_b32 s61, v174, 24
	v_readlane_b32 s62, v174, 40
	v_readlane_b32 s63, v174, 56
	v_readlane_b32 s64, v175, 8
	v_readlane_b32 s65, v175, 24
	v_readlane_b32 s66, v175, 40
	v_readlane_b32 s67, v175, 56
	v_readlane_b32 s68, v176, 8
	v_fmac_f32_e32 v26, s60, v124
	v_fmac_f32_e32 v27, s61, v124
	v_fmac_f32_e32 v58, s62, v124
	v_fmac_f32_e32 v59, s63, v124
	v_fmac_f32_e32 v82, s64, v124
	v_fmac_f32_e32 v83, s65, v124
	v_fmac_f32_e32 v118, s66, v124
	v_fmac_f32_e32 v119, s67, v124
	v_fmac_f32_e32 v117, s68, v124
	v_readlane_b32 s60, v174, 9
	v_readlane_b32 s61, v174, 25
	v_readlane_b32 s62, v174, 41
	v_readlane_b32 s63, v174, 57
; #define LAS __attribute__((address_space(3)))
; __device__ __forceinline__ void p0a_prologue(const Params& a, LAS unsigned char* lds) {
;     ...
;         for (int k0 = wave * 128; k0 < wave * 128 + 128; k0 += 16) {
;             float w[16];
; #pragma unroll
;             for (int kk = 0; kk < 16; ++kk) w[kk] = wa[(size_t)(k0 + kk) * 6144];
; #pragma unroll
;             for (int kk = 0; kk < 16; ++kk) {
; #pragma unroll
;                 for (int b = 0; b < NBATCH; ++b) { const float c = (b < 8) ? a.in[I_CP][b * DM + k0 + kk] : a.in[I_CS][k0 + kk]; accb[b] += (c / (1.0f + __expf(-c))) * w[kk]; } }
;         }
;         LAS float* red = (LAS float*)lds;
; #pragma unroll
;         for (int b = 0; b < NBATCH; ++b) red[(wave * NBATCH + b) * 64 + lane] = accb[b];
;         __syncthreads();
;         for (int idx = tid; idx < NBATCH * 64; idx += NTHREADS) { const int b = idx >> 6, l = idx & 63; float s = a.in[I_BADA][bb * 64 + l];
; #pragma unroll
;             for (int w = 0; w < 8; ++w) s += red[(w * NBATCH + b) * 64 + l];
;             ((float*)(ws + WS_MOD))[b * 6144 + bb * 64 + l] = s; }
;         __syncthreads();
	v_readlane_b32 s64, v175, 9
	v_readlane_b32 s65, v175, 25
	v_readlane_b32 s66, v175, 41
	v_readlane_b32 s67, v175, 57
	v_readlane_b32 s68, v176, 9
	v_fmac_f32_e32 v26, s60, v125
	v_fmac_f32_e32 v27, s61, v125
	v_fmac_f32_e32 v58, s62, v125
	v_fmac_f32_e32 v59, s63, v125
	v_fmac_f32_e32 v82, s64, v125
	v_fmac_f32_e32 v83, s65, v125
	v_fmac_f32_e32 v118, s66, v125
	v_fmac_f32_e32 v119, s67, v125
	v_fmac_f32_e32 v117, s68, v125
	v_readlane_b32 s60, v174, 10
	v_readlane_b32 s61, v174, 26
	v_readlane_b32 s62, v174, 42
	v_readlane_b32 s63, v174, 58
	v_readlane_b32 s64, v175, 10
	v_readlane_b32 s65, v175, 26
	v_readlane_b32 s66, v175, 42
	v_readlane_b32 s67, v175, 58
	v_readlane_b32 s68, v176, 10
	v_fmac_f32_e32 v26, s60, v122
	v_fmac_f32_e32 v27, s61, v122
	v_fmac_f32_e32 v58, s62, v122
	v_fmac_f32_e32 v59, s63, v122
	v_fmac_f32_e32 v82, s64, v122
	v_fmac_f32_e32 v83, s65, v122
	v_fmac_f32_e32 v118, s66, v122
	v_fmac_f32_e32 v119, s67, v122
	v_fmac_f32_e32 v117, s68, v122
	v_readlane_b32 s60, v174, 11
	v_readlane_b32 s61, v174, 27
	v_readlane_b32 s62, v174, 43
	v_readlane_b32 s63, v174, 59
	v_readlane_b32 s64, v175, 11
	v_readlane_b32 s65, v175, 27
	v_readlane_b32 s66, v175, 43
	v_readlane_b32 s67, v175, 59
	v_readlane_b32 s68, v176, 11
	v_fmac_f32_e32 v26, s60, v123
	v_fmac_f32_e32 v27, s61, v123
	v_fmac_f32_e32 v58, s62, v123
	v_fmac_f32_e32 v59, s63, v123
	v_fmac_f32_e32 v82, s64, v123
	v_fmac_f32_e32 v83, s65, v123
	v_fmac_f32_e32 v118, s66, v123
	v_fmac_f32_e32 v119, s67, v123
	v_fmac_f32_e32 v117, s68, v123
	v_readlane_b32 s60, v174, 12
	v_readlane_b32 s61, v174, 28
	v_readlane_b32 s62, v174, 44
	v_readlane_b32 s63, v174, 60
	v_readlane_b32 s64, v175, 12
	v_readlane_b32 s65, v175, 28
	v_readlane_b32 s66, v175, 44
	v_readlane_b32 s67, v175, 60
	v_readlane_b32 s68, v176, 12
	v_fmac_f32_e32 v26, s60, v120
	v_fmac_f32_e32 v27, s61, v120
	v_fmac_f32_e32 v58, s62, v120
	v_fmac_f32_e32 v59, s63, v120
	v_fmac_f32_e32 v82, s64, v120
	v_fmac_f32_e32 v83, s65, v120
	v_fmac_f32_e32 v118, s66, v120
	v_fmac_f32_e32 v119, s67, v120
	v_fmac_f32_e32 v117, s68, v120
	v_readlane_b32 s60, v174, 13
	v_readlane_b32 s61, v174, 29
	v_readlane_b32 s62, v174, 45
	v_readlane_b32 s63, v174, 61
	v_readlane_b32 s64, v175, 13
	v_readlane_b32 s65, v175, 29
	v_readlane_b32 s66, v175, 45
	v_readlane_b32 s67, v175, 61
	v_readlane_b32 s68, v176, 13
	v_fmac_f32_e32 v26, s60, v121
	v_fmac_f32_e32 v27, s61, v121
	v_fmac_f32_e32 v58, s62, v121
	v_fmac_f32_e32 v59, s63, v121
	v_fmac_f32_e32 v82, s64, v121
	v_fmac_f32_e32 v83, s65, v121
	v_fmac_f32_e32 v118, s66, v121
	v_fmac_f32_e32 v119, s67, v121
	v_fmac_f32_e32 v117, s68, v121
	v_readlane_b32 s60, v174, 14
	v_readlane_b32 s61, v174, 30
	v_readlane_b32 s62, v174, 46
	v_readlane_b32 s63, v174, 62
	v_readlane_b32 s64, v175, 14
	v_readlane_b32 s65, v175, 30
	v_readlane_b32 s66, v175, 46
	v_readlane_b32 s67, v175, 62
	v_readlane_b32 s68, v176, 14
	v_fmac_f32_e32 v26, s60, v116
	v_fmac_f32_e32 v27, s61, v116
	v_fmac_f32_e32 v58, s62, v116
	v_fmac_f32_e32 v59, s63, v116
	v_fmac_f32_e32 v82, s64, v116
	v_fmac_f32_e32 v83, s65, v116
	v_fmac_f32_e32 v118, s66, v116
	v_fmac_f32_e32 v119, s67, v116
	v_fmac_f32_e32 v117, s68, v116
	v_readlane_b32 s60, v174, 15
	v_readlane_b32 s61, v174, 31
	v_readlane_b32 s62, v174, 47
	v_readlane_b32 s63, v174, 63
	v_readlane_b32 s64, v175, 15
	v_readlane_b32 s65, v175, 31
	v_readlane_b32 s66, v175, 47
	v_readlane_b32 s67, v175, 63
	v_readlane_b32 s68, v176, 15
	v_fmac_f32_e32 v26, s60, v110
	v_fmac_f32_e32 v27, s61, v110
	v_fmac_f32_e32 v58, s62, v110
	v_fmac_f32_e32 v59, s63, v110
	v_fmac_f32_e32 v82, s64, v110
	v_fmac_f32_e32 v83, s65, v110
	v_fmac_f32_e32 v118, s66, v110
	v_fmac_f32_e32 v119, s67, v110
	v_fmac_f32_e32 v117, s68, v110
	s_cmp_ge_u32 s11, s4
	s_cbranch_scc0 .LBB0_164
	ds_write2st64_b32 v153, v26, v27 offset1:1
	ds_write2st64_b32 v153, v58, v59 offset0:2 offset1:3
	ds_write2st64_b32 v153, v82, v83 offset0:4 offset1:5
	ds_write2st64_b32 v153, v118, v119 offset0:6 offset1:7
	ds_write_b32 v153, v117 offset:2048
	s_waitcnt lgkmcnt(0)
	s_barrier
	s_and_saveexec_b64 s[20:21], s[0:1]
	s_cbranch_execz .LBB0_162
	v_lshl_or_b32 v2, s3, 6, v1
	v_ashrrev_i32_e32 v3, 31, v2
	v_lshl_add_u64 v[2:3], v[2:3], 2, s[46:47]
	s_mov_b64 s[44:45], 0
	v_mov_b32_e32 v6, v143
	v_mov_b32_e32 v4, v141
	v_mov_b32_e32 v7, v127

; #define LAS __attribute__((address_space(3)))
; __device__ __forceinline__ void pool_phase(const Params& a, LAS unsigned char* lds) {
;     ...
;         float o[32];
; #pragma unroll
;         for (int tt = 0; tt < 32; ++tt) { const int tl = half * 32 + tt; float acc = 0.f;
; #pragma unroll
;             for (int c4 = 0; c4 < 16; ++c4) { const f32x4 pv = *(const LAS f32x4*)(ps + tl * 256 + g * 64 + c4 * 4);
;                 acc += pv[0] * wreg[4 * c4] + pv[1] * wreg[4 * c4 + 1] + pv[2] * wreg[4 * c4 + 2] + pv[3] * wreg[4 * c4 + 3]; }
;             o[tt] = acc * pscale; const float s = wave_sum_valu(o[tt] * o[tt]);
;             if (lane == 0) ssl[g * 64 + tl] = s; }
.LBB0_647:
	v_mov_b32_e32 v104, s14
	s_waitcnt lgkmcnt(0)
	s_barrier
	ds_read_b128 v[156:159], v104
	ds_read_b128 v[160:163], v104 offset:16
	ds_read_b128 v[164:167], v104 offset:32
	ds_read_b128 v[168:171], v104 offset:48
	ds_read_b128 v[172:175], v104 offset:64
	ds_read_b128 v[176:179], v104 offset:80
	ds_read_b128 v[180:183], v104 offset:96
	ds_read_b128 v[184:187], v104 offset:112
	ds_read_b128 v[188:191], v104 offset:128
	ds_read_b128 v[192:195], v104 offset:144
	ds_read_b128 v[196:199], v104 offset:160
	ds_read_b128 v[200:203], v104 offset:176
	s_waitcnt lgkmcnt(11)
	v_mul_f32_e32 v220, v15, v157
	v_fmac_f32_e32 v220, v14, v156
	v_fmac_f32_e32 v220, v16, v158
	v_fmac_f32_e32 v220, v17, v159
	ds_read_b128 v[204:207], v104 offset:192
	s_waitcnt lgkmcnt(11)
	v_fmac_f32_e32 v220, v19, v161
	v_fmac_f32_e32 v220, v18, v160
	v_fmac_f32_e32 v220, v20, v162
	v_fmac_f32_e32 v220, v21, v163
	ds_read_b128 v[208:211], v104 offset:208
	s_waitcnt lgkmcnt(11)
	v_fmac_f32_e32 v220, v23, v165
	v_fmac_f32_e32 v220, v22, v164
	v_fmac_f32_e32 v220, v24, v166
	v_fmac_f32_e32 v220, v25, v167
	ds_read_b128 v[212:215], v104 offset:224
	s_waitcnt lgkmcnt(11)
	v_fmac_f32_e32 v220, v27, v169
	v_fmac_f32_e32 v220, v26, v168
	v_fmac_f32_e32 v220, v28, v170
	v_fmac_f32_e32 v220, v29, v171
	ds_read_b128 v[216:219], v104 offset:240
	s_waitcnt lgkmcnt(11)
	v_fmac_f32_e32 v220, v31, v173
	v_fmac_f32_e32 v220, v30, v172
	v_fmac_f32_e32 v220, v32, v174
	v_fmac_f32_e32 v220, v33, v175
	ds_read_b128 v[156:159], v104 offset:1024
	s_waitcnt lgkmcnt(11)
	v_fmac_f32_e32 v220, v35, v177
	v_fmac_f32_e32 v220, v34, v176
	v_fmac_f32_e32 v220, v36, v178
	v_fmac_f32_e32 v220, v37, v179
	ds_read_b128 v[160:163], v104 offset:1040
	s_waitcnt lgkmcnt(11)
	v_fmac_f32_e32 v220, v39, v181
	v_fmac_f32_e32 v220, v38, v180
	v_fmac_f32_e32 v220, v40, v182
	v_fmac_f32_e32 v220, v41, v183
	ds_read_b128 v[164:167], v104 offset:1056
	s_waitcnt lgkmcnt(11)
	v_fmac_f32_e32 v220, v43, v185
	v_fmac_f32_e32 v220, v42, v184
	v_fmac_f32_e32 v220, v44, v186
	v_fmac_f32_e32 v220, v45, v187
	ds_read_b128 v[168:171], v104 offset:1072
	s_waitcnt lgkmcnt(11)
	v_fmac_f32_e32 v220, v47, v189
	v_fmac_f32_e32 v220, v46, v188
	v_fmac_f32_e32 v220, v48, v190
	v_fmac_f32_e32 v220, v49, v191
	ds_read_b128 v[172:175], v104 offset:1088
	s_waitcnt lgkmcnt(11)
	v_fmac_f32_e32 v220, v51, v193
	v_fmac_f32_e32 v220, v50, v192
	v_fmac_f32_e32 v220, v52, v194
	v_fmac_f32_e32 v220, v53, v195
	ds_read_b128 v[176:179], v104 offset:1104
	s_waitcnt lgkmcnt(11)
	v_fmac_f32_e32 v220, v55, v197
	v_fmac_f32_e32 v220, v54, v196
	v_fmac_f32_e32 v220, v56, v198
	v_fmac_f32_e32 v220, v57, v199
	ds_read_b128 v[180:183], v104 offset:1120
	s_waitcnt lgkmcnt(11)
	v_fmac_f32_e32 v220, v59, v201
	v_fmac_f32_e32 v220, v58, v200
	v_fmac_f32_e32 v220, v60, v202
	v_fmac_f32_e32 v220, v61, v203
	ds_read_b128 v[184:187], v104 offset:1136
	s_waitcnt lgkmcnt(11)
	v_fmac_f32_e32 v220, v63, v205
	v_fmac_f32_e32 v220, v62, v204
	v_fmac_f32_e32 v220, v64, v206
	v_fmac_f32_e32 v220, v65, v207
	ds_read_b128 v[188:191], v104 offset:1152
	s_waitcnt lgkmcnt(11)
	v_fmac_f32_e32 v220, v67, v209
	v_fmac_f32_e32 v220, v66, v208
	v_fmac_f32_e32 v220, v68, v210
	v_fmac_f32_e32 v220, v69, v211
	ds_read_b128 v[192:195], v104 offset:1168
	s_waitcnt lgkmcnt(11)
	v_fmac_f32_e32 v220, v71, v213
	v_fmac_f32_e32 v220, v70, v212
	v_fmac_f32_e32 v220, v72, v214
	v_fmac_f32_e32 v220, v73, v215
	ds_read_b128 v[196:199], v104 offset:1184
	s_waitcnt lgkmcnt(11)
	v_fmac_f32_e32 v220, v75, v217
	v_fmac_f32_e32 v220, v74, v216
	v_fmac_f32_e32 v220, v76, v218
	v_fmac_f32_e32 v220, v77, v219
	ds_read_b128 v[200:203], v104 offset:1200
	v_mul_f32_e32 v119, v78, v220
	v_mul_f32_e32 v6, v119, v119
	s_nop 1
	v_mov_b32_dpp v6, v6 quad_perm:[1,0,3,2] row_mask:0xf bank_mask:0xf bound_ctrl:1
	v_fmac_f32_e32 v6, v119, v119
	s_nop 1
	v_add_f32_dpp v6, v6, v6 quad_perm:[2,3,0,1] row_mask:0xf bank_mask:0xf bound_ctrl:1
	s_nop 1
	v_add_f32_dpp v6, v6, v6 row_half_mirror row_mask:0xf bank_mask:0xf bound_ctrl:1
	s_nop 1
	v_add_f32_dpp v6, v6, v6 row_mirror row_mask:0xf bank_mask:0xf bound_ctrl:1
	v_mov_b32_e32 v7, v6
	s_nop 1
	v_permlane16_swap_b32_e32 v6, v7
	v_add_f32_e32 v6, v6, v7
	v_mov_b32_e32 v7, v6
	s_nop 1
	v_permlane32_swap_b32_e32 v6, v7
	s_and_saveexec_b64 s[2:3], s[0:1]
	v_add_f32_e32 v6, v6, v7
	v_mov_b32_e32 v7, s17
	ds_write_b32 v7, v6
	s_or_b64 exec, exec, s[2:3]
	v_mov_b32_e32 v104, s15
	s_waitcnt lgkmcnt(12)
	v_mul_f32_e32 v220, v15, v157
	v_fmac_f32_e32 v220, v14, v156
	v_fmac_f32_e32 v220, v16, v158
	v_fmac_f32_e32 v220, v17, v159
	ds_read_b128 v[204:207], v104 offset:192
	s_waitcnt lgkmcnt(12)
	v_fmac_f32_e32 v220, v19, v161
	v_fmac_f32_e32 v220, v18, v160
	v_fmac_f32_e32 v220, v20, v162
	v_fmac_f32_e32 v220, v21, v163
	ds_read_b128 v[208:211], v104 offset:208
	s_waitcnt lgkmcnt(12)
	v_fmac_f32_e32 v220, v23, v165
	v_fmac_f32_e32 v220, v22, v164
	v_fmac_f32_e32 v220, v24, v166
	v_fmac_f32_e32 v220, v25, v167
	ds_read_b128 v[212:215], v104 offset:224
	s_waitcnt lgkmcnt(12)
	v_fmac_f32_e32 v220, v27, v169
	v_fmac_f32_e32 v220, v26, v168
	v_fmac_f32_e32 v220, v28, v170
	v_fmac_f32_e32 v220, v29, v171
	ds_read_b128 v[216:219], v104 offset:240
	s_waitcnt lgkmcnt(12)
	v_fmac_f32_e32 v220, v31, v173
	v_fmac_f32_e32 v220, v30, v172
	v_fmac_f32_e32 v220, v32, v174
	v_fmac_f32_e32 v220, v33, v175
	ds_read_b128 v[156:159], v104 offset:1024
	s_waitcnt lgkmcnt(12)
	v_fmac_f32_e32 v220, v35, v177
	v_fmac_f32_e32 v220, v34, v176
	v_fmac_f32_e32 v220, v36, v178
	v_fmac_f32_e32 v220, v37, v179
	ds_read_b128 v[160:163], v104 offset:1040
	s_waitcnt lgkmcnt(12)
; #define LAS __attribute__((address_space(3)))
; __device__ __forceinline__ void pool_phase(const Params& a, LAS unsigned char* lds) {
;     ...
;         float o[32];
; #pragma unroll
;         for (int tt = 0; tt < 32; ++tt) { const int tl = half * 32 + tt; float acc = 0.f;
; #pragma unroll
;             for (int c4 = 0; c4 < 16; ++c4) { const f32x4 pv = *(const LAS f32x4*)(ps + tl * 256 + g * 64 + c4 * 4);
;                 acc += pv[0] * wreg[4 * c4] + pv[1] * wreg[4 * c4 + 1] + pv[2] * wreg[4 * c4 + 2] + pv[3] * wreg[4 * c4 + 3]; }
;             o[tt] = acc * pscale; const float s = wave_sum_valu(o[tt] * o[tt]);
;             if (lane == 0) ssl[g * 64 + tl] = s; }
	v_fmac_f32_e32 v220, v39, v181
	v_fmac_f32_e32 v220, v38, v180
	v_fmac_f32_e32 v220, v40, v182
	v_fmac_f32_e32 v220, v41, v183
	ds_read_b128 v[164:167], v104 offset:1056
	s_waitcnt lgkmcnt(12)
	v_fmac_f32_e32 v220, v43, v185
	v_fmac_f32_e32 v220, v42, v184
	v_fmac_f32_e32 v220, v44, v186
	v_fmac_f32_e32 v220, v45, v187
	ds_read_b128 v[168:171], v104 offset:1072
	s_waitcnt lgkmcnt(12)
	v_fmac_f32_e32 v220, v47, v189
	v_fmac_f32_e32 v220, v46, v188
	v_fmac_f32_e32 v220, v48, v190
	v_fmac_f32_e32 v220, v49, v191
	ds_read_b128 v[172:175], v104 offset:1088
	s_waitcnt lgkmcnt(12)
	v_fmac_f32_e32 v220, v51, v193
	v_fmac_f32_e32 v220, v50, v192
	v_fmac_f32_e32 v220, v52, v194
	v_fmac_f32_e32 v220, v53, v195
	ds_read_b128 v[176:179], v104 offset:1104
	s_waitcnt lgkmcnt(12)
	v_fmac_f32_e32 v220, v55, v197
	v_fmac_f32_e32 v220, v54, v196
	v_fmac_f32_e32 v220, v56, v198
	v_fmac_f32_e32 v220, v57, v199
	ds_read_b128 v[180:183], v104 offset:1120
	s_waitcnt lgkmcnt(12)
	v_fmac_f32_e32 v220, v59, v201
	v_fmac_f32_e32 v220, v58, v200
	v_fmac_f32_e32 v220, v60, v202
	v_fmac_f32_e32 v220, v61, v203
	ds_read_b128 v[184:187], v104 offset:1136
	s_waitcnt lgkmcnt(11)
	v_fmac_f32_e32 v220, v63, v205
	v_fmac_f32_e32 v220, v62, v204
	v_fmac_f32_e32 v220, v64, v206
	v_fmac_f32_e32 v220, v65, v207
	ds_read_b128 v[188:191], v104 offset:1152
	s_waitcnt lgkmcnt(11)
	v_fmac_f32_e32 v220, v67, v209
	v_fmac_f32_e32 v220, v66, v208
	v_fmac_f32_e32 v220, v68, v210
	v_fmac_f32_e32 v220, v69, v211
	ds_read_b128 v[192:195], v104 offset:1168
	s_waitcnt lgkmcnt(11)
	v_fmac_f32_e32 v220, v71, v213
	v_fmac_f32_e32 v220, v70, v212
	v_fmac_f32_e32 v220, v72, v214
	v_fmac_f32_e32 v220, v73, v215
	ds_read_b128 v[196:199], v104 offset:1184
	s_waitcnt lgkmcnt(11)
	v_fmac_f32_e32 v220, v75, v217
	v_fmac_f32_e32 v220, v74, v216
	v_fmac_f32_e32 v220, v76, v218
	v_fmac_f32_e32 v220, v77, v219
	ds_read_b128 v[200:203], v104 offset:1200
	v_mul_f32_e32 v118, v78, v220
	v_mul_f32_e32 v6, v118, v118
	s_nop 1
	v_mov_b32_dpp v6, v6 quad_perm:[1,0,3,2] row_mask:0xf bank_mask:0xf bound_ctrl:1
	v_fmac_f32_e32 v6, v118, v118
	s_nop 1
	v_add_f32_dpp v6, v6, v6 quad_perm:[2,3,0,1] row_mask:0xf bank_mask:0xf bound_ctrl:1
	s_nop 1
	v_add_f32_dpp v6, v6, v6 row_half_mirror row_mask:0xf bank_mask:0xf bound_ctrl:1
	s_nop 1
	v_add_f32_dpp v6, v6, v6 row_mirror row_mask:0xf bank_mask:0xf bound_ctrl:1
	v_mov_b32_e32 v7, v6
	s_nop 1
	v_permlane16_swap_b32_e32 v6, v7
	v_add_f32_e32 v6, v6, v7
	v_mov_b32_e32 v7, v6
	s_nop 1
	v_permlane32_swap_b32_e32 v6, v7
	s_and_saveexec_b64 s[2:3], s[0:1]
	v_add_f32_e32 v6, v6, v7
	v_mov_b32_e32 v7, s17
	ds_write_b32 v7, v6 offset:4
	s_or_b64 exec, exec, s[2:3]
	v_mov_b32_e32 v104, s22
	s_waitcnt lgkmcnt(12)
	v_mul_f32_e32 v220, v15, v157
	v_fmac_f32_e32 v220, v14, v156
	v_fmac_f32_e32 v220, v16, v158
	v_fmac_f32_e32 v220, v17, v159
	ds_read_b128 v[204:207], v104 offset:192
	s_waitcnt lgkmcnt(12)
	v_fmac_f32_e32 v220, v19, v161
	v_fmac_f32_e32 v220, v18, v160
	v_fmac_f32_e32 v220, v20, v162
	v_fmac_f32_e32 v220, v21, v163
	ds_read_b128 v[208:211], v104 offset:208
	s_waitcnt lgkmcnt(12)
	v_fmac_f32_e32 v220, v23, v165
	v_fmac_f32_e32 v220, v22, v164
	v_fmac_f32_e32 v220, v24, v166
	v_fmac_f32_e32 v220, v25, v167
	ds_read_b128 v[212:215], v104 offset:224
	s_waitcnt lgkmcnt(12)
	v_fmac_f32_e32 v220, v27, v169
	v_fmac_f32_e32 v220, v26, v168
	v_fmac_f32_e32 v220, v28, v170
	v_fmac_f32_e32 v220, v29, v171
	ds_read_b128 v[216:219], v104 offset:240
	s_waitcnt lgkmcnt(12)
	v_fmac_f32_e32 v220, v31, v173
	v_fmac_f32_e32 v220, v30, v172
	v_fmac_f32_e32 v220, v32, v174
	v_fmac_f32_e32 v220, v33, v175
	ds_read_b128 v[156:159], v104 offset:1024
	s_waitcnt lgkmcnt(12)
	v_fmac_f32_e32 v220, v35, v177
	v_fmac_f32_e32 v220, v34, v176
	v_fmac_f32_e32 v220, v36, v178
	v_fmac_f32_e32 v220, v37, v179
	ds_read_b128 v[160:163], v104 offset:1040
	s_waitcnt lgkmcnt(12)
	v_fmac_f32_e32 v220, v39, v181
	v_fmac_f32_e32 v220, v38, v180
	v_fmac_f32_e32 v220, v40, v182
	v_fmac_f32_e32 v220, v41, v183
	ds_read_b128 v[164:167], v104 offset:1056
	s_waitcnt lgkmcnt(12)
	v_fmac_f32_e32 v220, v43, v185
	v_fmac_f32_e32 v220, v42, v184
	v_fmac_f32_e32 v220, v44, v186
	v_fmac_f32_e32 v220, v45, v187
	ds_read_b128 v[168:171], v104 offset:1072
	s_waitcnt lgkmcnt(12)
	v_fmac_f32_e32 v220, v47, v189
	v_fmac_f32_e32 v220, v46, v188
	v_fmac_f32_e32 v220, v48, v190
	v_fmac_f32_e32 v220, v49, v191
	ds_read_b128 v[172:175], v104 offset:1088
	s_waitcnt lgkmcnt(12)
	v_fmac_f32_e32 v220, v51, v193
	v_fmac_f32_e32 v220, v50, v192
	v_fmac_f32_e32 v220, v52, v194
	v_fmac_f32_e32 v220, v53, v195
	ds_read_b128 v[176:179], v104 offset:1104
	s_waitcnt lgkmcnt(12)
	v_fmac_f32_e32 v220, v55, v197
	v_fmac_f32_e32 v220, v54, v196
	v_fmac_f32_e32 v220, v56, v198
	v_fmac_f32_e32 v220, v57, v199
	ds_read_b128 v[180:183], v104 offset:1120
	s_waitcnt lgkmcnt(12)
	v_fmac_f32_e32 v220, v59, v201
	v_fmac_f32_e32 v220, v58, v200
	v_fmac_f32_e32 v220, v60, v202
	v_fmac_f32_e32 v220, v61, v203
	ds_read_b128 v[184:187], v104 offset:1136
	s_waitcnt lgkmcnt(11)
	v_fmac_f32_e32 v220, v63, v205
	v_fmac_f32_e32 v220, v62, v204
	v_fmac_f32_e32 v220, v64, v206
	v_fmac_f32_e32 v220, v65, v207
	ds_read_b128 v[188:191], v104 offset:1152
	s_waitcnt lgkmcnt(11)
	v_fmac_f32_e32 v220, v67, v209
	v_fmac_f32_e32 v220, v66, v208
	v_fmac_f32_e32 v220, v68, v210
	v_fmac_f32_e32 v220, v69, v211
	ds_read_b128 v[192:195], v104 offset:1168
	s_waitcnt lgkmcnt(11)
	v_fmac_f32_e32 v220, v71, v213
	v_fmac_f32_e32 v220, v70, v212
	v_fmac_f32_e32 v220, v72, v214
	v_fmac_f32_e32 v220, v73, v215
	ds_read_b128 v[196:199], v104 offset:1184
	s_waitcnt lgkmcnt(11)
; #define LAS __attribute__((address_space(3)))
; __device__ __forceinline__ void pool_phase(const Params& a, LAS unsigned char* lds) {
;     ...
;         float o[32];
; #pragma unroll
;         for (int tt = 0; tt < 32; ++tt) { const int tl = half * 32 + tt; float acc = 0.f;
; #pragma unroll
;             for (int c4 = 0; c4 < 16; ++c4) { const f32x4 pv = *(const LAS f32x4*)(ps + tl * 256 + g * 64 + c4 * 4);
;                 acc += pv[0] * wreg[4 * c4] + pv[1] * wreg[4 * c4 + 1] + pv[2] * wreg[4 * c4 + 2] + pv[3] * wreg[4 * c4 + 3]; }
;             o[tt] = acc * pscale; const float s = wave_sum_valu(o[tt] * o[tt]);
;             if (lane == 0) ssl[g * 64 + tl] = s; }
	v_fmac_f32_e32 v220, v75, v217
	v_fmac_f32_e32 v220, v74, v216
	v_fmac_f32_e32 v220, v76, v218
	v_fmac_f32_e32 v220, v77, v219
	ds_read_b128 v[200:203], v104 offset:1200
	v_mul_f32_e32 v117, v78, v220
	v_mul_f32_e32 v6, v117, v117
	s_nop 1
	v_mov_b32_dpp v6, v6 quad_perm:[1,0,3,2] row_mask:0xf bank_mask:0xf bound_ctrl:1
	v_fmac_f32_e32 v6, v117, v117
	s_nop 1
	v_add_f32_dpp v6, v6, v6 quad_perm:[2,3,0,1] row_mask:0xf bank_mask:0xf bound_ctrl:1
	s_nop 1
	v_add_f32_dpp v6, v6, v6 row_half_mirror row_mask:0xf bank_mask:0xf bound_ctrl:1
	s_nop 1
	v_add_f32_dpp v6, v6, v6 row_mirror row_mask:0xf bank_mask:0xf bound_ctrl:1
	v_mov_b32_e32 v7, v6
	s_nop 1
	v_permlane16_swap_b32_e32 v6, v7
	v_add_f32_e32 v6, v6, v7
	v_mov_b32_e32 v7, v6
	s_nop 1
	v_permlane32_swap_b32_e32 v6, v7
	s_and_saveexec_b64 s[2:3], s[0:1]
	v_add_f32_e32 v6, v6, v7
	v_mov_b32_e32 v7, s17
	ds_write_b32 v7, v6 offset:8
	s_or_b64 exec, exec, s[2:3]
	v_mov_b32_e32 v104, s23
	s_waitcnt lgkmcnt(12)
	v_mul_f32_e32 v220, v15, v157
	v_fmac_f32_e32 v220, v14, v156
	v_fmac_f32_e32 v220, v16, v158
	v_fmac_f32_e32 v220, v17, v159
	ds_read_b128 v[204:207], v104 offset:192
	s_waitcnt lgkmcnt(12)
	v_fmac_f32_e32 v220, v19, v161
	v_fmac_f32_e32 v220, v18, v160
	v_fmac_f32_e32 v220, v20, v162
	v_fmac_f32_e32 v220, v21, v163
	ds_read_b128 v[208:211], v104 offset:208
	s_waitcnt lgkmcnt(12)
	v_fmac_f32_e32 v220, v23, v165
	v_fmac_f32_e32 v220, v22, v164
	v_fmac_f32_e32 v220, v24, v166
	v_fmac_f32_e32 v220, v25, v167
	ds_read_b128 v[212:215], v104 offset:224
	s_waitcnt lgkmcnt(12)
	v_fmac_f32_e32 v220, v27, v169
	v_fmac_f32_e32 v220, v26, v168
	v_fmac_f32_e32 v220, v28, v170
	v_fmac_f32_e32 v220, v29, v171
	ds_read_b128 v[216:219], v104 offset:240
	s_waitcnt lgkmcnt(12)
	v_fmac_f32_e32 v220, v31, v173
	v_fmac_f32_e32 v220, v30, v172
	v_fmac_f32_e32 v220, v32, v174
	v_fmac_f32_e32 v220, v33, v175
	ds_read_b128 v[156:159], v104 offset:1024
	s_waitcnt lgkmcnt(12)
	v_fmac_f32_e32 v220, v35, v177
	v_fmac_f32_e32 v220, v34, v176
	v_fmac_f32_e32 v220, v36, v178
	v_fmac_f32_e32 v220, v37, v179
	ds_read_b128 v[160:163], v104 offset:1040
	s_waitcnt lgkmcnt(12)
	v_fmac_f32_e32 v220, v39, v181
	v_fmac_f32_e32 v220, v38, v180
	v_fmac_f32_e32 v220, v40, v182
	v_fmac_f32_e32 v220, v41, v183
	ds_read_b128 v[164:167], v104 offset:1056
	s_waitcnt lgkmcnt(12)
	v_fmac_f32_e32 v220, v43, v185
	v_fmac_f32_e32 v220, v42, v184
	v_fmac_f32_e32 v220, v44, v186
	v_fmac_f32_e32 v220, v45, v187
	ds_read_b128 v[168:171], v104 offset:1072
	s_waitcnt lgkmcnt(12)
	v_fmac_f32_e32 v220, v47, v189
	v_fmac_f32_e32 v220, v46, v188
	v_fmac_f32_e32 v220, v48, v190
	v_fmac_f32_e32 v220, v49, v191
	ds_read_b128 v[172:175], v104 offset:1088
	s_waitcnt lgkmcnt(12)
	v_fmac_f32_e32 v220, v51, v193
	v_fmac_f32_e32 v220, v50, v192
	v_fmac_f32_e32 v220, v52, v194
	v_fmac_f32_e32 v220, v53, v195
	ds_read_b128 v[176:179], v104 offset:1104
	s_waitcnt lgkmcnt(12)
	v_fmac_f32_e32 v220, v55, v197
	v_fmac_f32_e32 v220, v54, v196
	v_fmac_f32_e32 v220, v56, v198
	v_fmac_f32_e32 v220, v57, v199
	ds_read_b128 v[180:183], v104 offset:1120
	s_waitcnt lgkmcnt(12)
	v_fmac_f32_e32 v220, v59, v201
	v_fmac_f32_e32 v220, v58, v200
	v_fmac_f32_e32 v220, v60, v202
	v_fmac_f32_e32 v220, v61, v203
	ds_read_b128 v[184:187], v104 offset:1136
	s_waitcnt lgkmcnt(11)
	v_fmac_f32_e32 v220, v63, v205
	v_fmac_f32_e32 v220, v62, v204
	v_fmac_f32_e32 v220, v64, v206
	v_fmac_f32_e32 v220, v65, v207
	ds_read_b128 v[188:191], v104 offset:1152
	s_waitcnt lgkmcnt(11)
	v_fmac_f32_e32 v220, v67, v209
	v_fmac_f32_e32 v220, v66, v208
	v_fmac_f32_e32 v220, v68, v210
	v_fmac_f32_e32 v220, v69, v211
	ds_read_b128 v[192:195], v104 offset:1168
	s_waitcnt lgkmcnt(11)
	v_fmac_f32_e32 v220, v71, v213
	v_fmac_f32_e32 v220, v70, v212
	v_fmac_f32_e32 v220, v72, v214
	v_fmac_f32_e32 v220, v73, v215
	ds_read_b128 v[196:199], v104 offset:1184
	s_waitcnt lgkmcnt(11)
	v_fmac_f32_e32 v220, v75, v217
	v_fmac_f32_e32 v220, v74, v216
	v_fmac_f32_e32 v220, v76, v218
	v_fmac_f32_e32 v220, v77, v219
	ds_read_b128 v[200:203], v104 offset:1200
	v_mul_f32_e32 v116, v78, v220
	v_mul_f32_e32 v6, v116, v116
	s_nop 1
	v_mov_b32_dpp v6, v6 quad_perm:[1,0,3,2] row_mask:0xf bank_mask:0xf bound_ctrl:1
	v_fmac_f32_e32 v6, v116, v116
	s_nop 1
	v_add_f32_dpp v6, v6, v6 quad_perm:[2,3,0,1] row_mask:0xf bank_mask:0xf bound_ctrl:1
	s_nop 1
	v_add_f32_dpp v6, v6, v6 row_half_mirror row_mask:0xf bank_mask:0xf bound_ctrl:1
	s_nop 1
	v_add_f32_dpp v6, v6, v6 row_mirror row_mask:0xf bank_mask:0xf bound_ctrl:1
	v_mov_b32_e32 v7, v6
	s_nop 1
	v_permlane16_swap_b32_e32 v6, v7
	v_add_f32_e32 v6, v6, v7
	v_mov_b32_e32 v7, v6
	s_nop 1
	v_permlane32_swap_b32_e32 v6, v7
	s_and_saveexec_b64 s[2:3], s[0:1]
	v_add_f32_e32 v6, v6, v7
	v_mov_b32_e32 v7, s17
	ds_write_b32 v7, v6 offset:12
	s_or_b64 exec, exec, s[2:3]
	v_mov_b32_e32 v104, s6
	s_waitcnt lgkmcnt(12)
	v_mul_f32_e32 v220, v15, v157
	v_fmac_f32_e32 v220, v14, v156
	v_fmac_f32_e32 v220, v16, v158
	v_fmac_f32_e32 v220, v17, v159
	ds_read_b128 v[204:207], v104 offset:192
	s_waitcnt lgkmcnt(12)
	v_fmac_f32_e32 v220, v19, v161
	v_fmac_f32_e32 v220, v18, v160
	v_fmac_f32_e32 v220, v20, v162
	v_fmac_f32_e32 v220, v21, v163
	ds_read_b128 v[208:211], v104 offset:208
	s_waitcnt lgkmcnt(12)
	v_fmac_f32_e32 v220, v23, v165
	v_fmac_f32_e32 v220, v22, v164
	v_fmac_f32_e32 v220, v24, v166
	v_fmac_f32_e32 v220, v25, v167
	ds_read_b128 v[212:215], v104 offset:224
	s_waitcnt lgkmcnt(12)
	v_fmac_f32_e32 v220, v27, v169
	v_fmac_f32_e32 v220, v26, v168
	v_fmac_f32_e32 v220, v28, v170
	v_fmac_f32_e32 v220, v29, v171
	ds_read_b128 v[216:219], v104 offset:240
	s_waitcnt lgkmcnt(12)
; #define LAS __attribute__((address_space(3)))
; __device__ __forceinline__ void pool_phase(const Params& a, LAS unsigned char* lds) {
;     ...
;         float o[32];
; #pragma unroll
;         for (int tt = 0; tt < 32; ++tt) { const int tl = half * 32 + tt; float acc = 0.f;
; #pragma unroll
;             for (int c4 = 0; c4 < 16; ++c4) { const f32x4 pv = *(const LAS f32x4*)(ps + tl * 256 + g * 64 + c4 * 4);
;                 acc += pv[0] * wreg[4 * c4] + pv[1] * wreg[4 * c4 + 1] + pv[2] * wreg[4 * c4 + 2] + pv[3] * wreg[4 * c4 + 3]; }
;             o[tt] = acc * pscale; const float s = wave_sum_valu(o[tt] * o[tt]);
;             if (lane == 0) ssl[g * 64 + tl] = s; }
	v_fmac_f32_e32 v220, v31, v173
	v_fmac_f32_e32 v220, v30, v172
	v_fmac_f32_e32 v220, v32, v174
	v_fmac_f32_e32 v220, v33, v175
	ds_read_b128 v[156:159], v104 offset:1024
	s_waitcnt lgkmcnt(12)
	v_fmac_f32_e32 v220, v35, v177
	v_fmac_f32_e32 v220, v34, v176
	v_fmac_f32_e32 v220, v36, v178
	v_fmac_f32_e32 v220, v37, v179
	ds_read_b128 v[160:163], v104 offset:1040
	s_waitcnt lgkmcnt(12)
	v_fmac_f32_e32 v220, v39, v181
	v_fmac_f32_e32 v220, v38, v180
	v_fmac_f32_e32 v220, v40, v182
	v_fmac_f32_e32 v220, v41, v183
	ds_read_b128 v[164:167], v104 offset:1056
	s_waitcnt lgkmcnt(12)
	v_fmac_f32_e32 v220, v43, v185
	v_fmac_f32_e32 v220, v42, v184
	v_fmac_f32_e32 v220, v44, v186
	v_fmac_f32_e32 v220, v45, v187
	ds_read_b128 v[168:171], v104 offset:1072
	s_waitcnt lgkmcnt(12)
	v_fmac_f32_e32 v220, v47, v189
	v_fmac_f32_e32 v220, v46, v188
	v_fmac_f32_e32 v220, v48, v190
	v_fmac_f32_e32 v220, v49, v191
	ds_read_b128 v[172:175], v104 offset:1088
	s_waitcnt lgkmcnt(12)
	v_fmac_f32_e32 v220, v51, v193
	v_fmac_f32_e32 v220, v50, v192
	v_fmac_f32_e32 v220, v52, v194
	v_fmac_f32_e32 v220, v53, v195
	ds_read_b128 v[176:179], v104 offset:1104
	s_waitcnt lgkmcnt(12)
	v_fmac_f32_e32 v220, v55, v197
	v_fmac_f32_e32 v220, v54, v196
	v_fmac_f32_e32 v220, v56, v198
	v_fmac_f32_e32 v220, v57, v199
	ds_read_b128 v[180:183], v104 offset:1120
	s_waitcnt lgkmcnt(12)
	v_fmac_f32_e32 v220, v59, v201
	v_fmac_f32_e32 v220, v58, v200
	v_fmac_f32_e32 v220, v60, v202
	v_fmac_f32_e32 v220, v61, v203
	ds_read_b128 v[184:187], v104 offset:1136
	s_waitcnt lgkmcnt(11)
	v_fmac_f32_e32 v220, v63, v205
	v_fmac_f32_e32 v220, v62, v204
	v_fmac_f32_e32 v220, v64, v206
	v_fmac_f32_e32 v220, v65, v207
	ds_read_b128 v[188:191], v104 offset:1152
	s_waitcnt lgkmcnt(11)
	v_fmac_f32_e32 v220, v67, v209
	v_fmac_f32_e32 v220, v66, v208
	v_fmac_f32_e32 v220, v68, v210
	v_fmac_f32_e32 v220, v69, v211
	ds_read_b128 v[192:195], v104 offset:1168
	s_waitcnt lgkmcnt(11)
	v_fmac_f32_e32 v220, v71, v213
	v_fmac_f32_e32 v220, v70, v212
	v_fmac_f32_e32 v220, v72, v214
	v_fmac_f32_e32 v220, v73, v215
	ds_read_b128 v[196:199], v104 offset:1184
	s_waitcnt lgkmcnt(11)
	v_fmac_f32_e32 v220, v75, v217
	v_fmac_f32_e32 v220, v74, v216
	v_fmac_f32_e32 v220, v76, v218
	v_fmac_f32_e32 v220, v77, v219
	ds_read_b128 v[200:203], v104 offset:1200
	v_mul_f32_e32 v115, v78, v220
	v_mul_f32_e32 v6, v115, v115
	s_nop 1
	v_mov_b32_dpp v6, v6 quad_perm:[1,0,3,2] row_mask:0xf bank_mask:0xf bound_ctrl:1
	v_fmac_f32_e32 v6, v115, v115
	s_nop 1
	v_add_f32_dpp v6, v6, v6 quad_perm:[2,3,0,1] row_mask:0xf bank_mask:0xf bound_ctrl:1
	s_nop 1
	v_add_f32_dpp v6, v6, v6 row_half_mirror row_mask:0xf bank_mask:0xf bound_ctrl:1
	s_nop 1
	v_add_f32_dpp v6, v6, v6 row_mirror row_mask:0xf bank_mask:0xf bound_ctrl:1
	v_mov_b32_e32 v7, v6
	s_nop 1
	v_permlane16_swap_b32_e32 v6, v7
	v_add_f32_e32 v6, v6, v7
	v_mov_b32_e32 v7, v6
	s_nop 1
	v_permlane32_swap_b32_e32 v6, v7
	s_and_saveexec_b64 s[2:3], s[0:1]
	v_add_f32_e32 v6, v6, v7
	v_mov_b32_e32 v7, s17
	ds_write_b32 v7, v6 offset:16
	s_or_b64 exec, exec, s[2:3]
	v_mov_b32_e32 v104, s7
	s_waitcnt lgkmcnt(12)
	v_mul_f32_e32 v220, v15, v157
	v_fmac_f32_e32 v220, v14, v156
	v_fmac_f32_e32 v220, v16, v158
	v_fmac_f32_e32 v220, v17, v159
	ds_read_b128 v[204:207], v104 offset:192
	s_waitcnt lgkmcnt(12)
	v_fmac_f32_e32 v220, v19, v161
	v_fmac_f32_e32 v220, v18, v160
	v_fmac_f32_e32 v220, v20, v162
	v_fmac_f32_e32 v220, v21, v163
	ds_read_b128 v[208:211], v104 offset:208
	s_waitcnt lgkmcnt(12)
	v_fmac_f32_e32 v220, v23, v165
	v_fmac_f32_e32 v220, v22, v164
	v_fmac_f32_e32 v220, v24, v166
	v_fmac_f32_e32 v220, v25, v167
	ds_read_b128 v[212:215], v104 offset:224
	s_waitcnt lgkmcnt(12)
	v_fmac_f32_e32 v220, v27, v169
	v_fmac_f32_e32 v220, v26, v168
	v_fmac_f32_e32 v220, v28, v170
	v_fmac_f32_e32 v220, v29, v171
	ds_read_b128 v[216:219], v104 offset:240
	s_waitcnt lgkmcnt(12)
	v_fmac_f32_e32 v220, v31, v173
	v_fmac_f32_e32 v220, v30, v172
	v_fmac_f32_e32 v220, v32, v174
	v_fmac_f32_e32 v220, v33, v175
	ds_read_b128 v[156:159], v104 offset:1024
	s_waitcnt lgkmcnt(12)
	v_fmac_f32_e32 v220, v35, v177
	v_fmac_f32_e32 v220, v34, v176
	v_fmac_f32_e32 v220, v36, v178
	v_fmac_f32_e32 v220, v37, v179
	ds_read_b128 v[160:163], v104 offset:1040
	s_waitcnt lgkmcnt(12)
	v_fmac_f32_e32 v220, v39, v181
	v_fmac_f32_e32 v220, v38, v180
	v_fmac_f32_e32 v220, v40, v182
	v_fmac_f32_e32 v220, v41, v183
	ds_read_b128 v[164:167], v104 offset:1056
	s_waitcnt lgkmcnt(12)
	v_fmac_f32_e32 v220, v43, v185
	v_fmac_f32_e32 v220, v42, v184
	v_fmac_f32_e32 v220, v44, v186
	v_fmac_f32_e32 v220, v45, v187
	ds_read_b128 v[168:171], v104 offset:1072
	s_waitcnt lgkmcnt(12)
	v_fmac_f32_e32 v220, v47, v189
	v_fmac_f32_e32 v220, v46, v188
	v_fmac_f32_e32 v220, v48, v190
	v_fmac_f32_e32 v220, v49, v191
	ds_read_b128 v[172:175], v104 offset:1088
	s_waitcnt lgkmcnt(12)
	v_fmac_f32_e32 v220, v51, v193
	v_fmac_f32_e32 v220, v50, v192
	v_fmac_f32_e32 v220, v52, v194
	v_fmac_f32_e32 v220, v53, v195
	ds_read_b128 v[176:179], v104 offset:1104
	s_waitcnt lgkmcnt(12)
	v_fmac_f32_e32 v220, v55, v197
	v_fmac_f32_e32 v220, v54, v196
	v_fmac_f32_e32 v220, v56, v198
	v_fmac_f32_e32 v220, v57, v199
	ds_read_b128 v[180:183], v104 offset:1120
	s_waitcnt lgkmcnt(12)
	v_fmac_f32_e32 v220, v59, v201
	v_fmac_f32_e32 v220, v58, v200
	v_fmac_f32_e32 v220, v60, v202
	v_fmac_f32_e32 v220, v61, v203
	ds_read_b128 v[184:187], v104 offset:1136
	s_waitcnt lgkmcnt(11)
	v_fmac_f32_e32 v220, v63, v205
	v_fmac_f32_e32 v220, v62, v204
	v_fmac_f32_e32 v220, v64, v206
	v_fmac_f32_e32 v220, v65, v207
	ds_read_b128 v[188:191], v104 offset:1152
	s_waitcnt lgkmcnt(11)
; #define LAS __attribute__((address_space(3)))
; __device__ __forceinline__ void pool_phase(const Params& a, LAS unsigned char* lds) {
;     ...
;         float o[32];
; #pragma unroll
;         for (int tt = 0; tt < 32; ++tt) { const int tl = half * 32 + tt; float acc = 0.f;
; #pragma unroll
;             for (int c4 = 0; c4 < 16; ++c4) { const f32x4 pv = *(const LAS f32x4*)(ps + tl * 256 + g * 64 + c4 * 4);
;                 acc += pv[0] * wreg[4 * c4] + pv[1] * wreg[4 * c4 + 1] + pv[2] * wreg[4 * c4 + 2] + pv[3] * wreg[4 * c4 + 3]; }
;             o[tt] = acc * pscale; const float s = wave_sum_valu(o[tt] * o[tt]);
;             if (lane == 0) ssl[g * 64 + tl] = s; }
	v_fmac_f32_e32 v220, v67, v209
	v_fmac_f32_e32 v220, v66, v208
	v_fmac_f32_e32 v220, v68, v210
	v_fmac_f32_e32 v220, v69, v211
	ds_read_b128 v[192:195], v104 offset:1168
	s_waitcnt lgkmcnt(11)
	v_fmac_f32_e32 v220, v71, v213
	v_fmac_f32_e32 v220, v70, v212
	v_fmac_f32_e32 v220, v72, v214
	v_fmac_f32_e32 v220, v73, v215
	ds_read_b128 v[196:199], v104 offset:1184
	s_waitcnt lgkmcnt(11)
	v_fmac_f32_e32 v220, v75, v217
	v_fmac_f32_e32 v220, v74, v216
	v_fmac_f32_e32 v220, v76, v218
	v_fmac_f32_e32 v220, v77, v219
	ds_read_b128 v[200:203], v104 offset:1200
	v_mul_f32_e32 v114, v78, v220
	v_mul_f32_e32 v6, v114, v114
	s_nop 1
	v_mov_b32_dpp v6, v6 quad_perm:[1,0,3,2] row_mask:0xf bank_mask:0xf bound_ctrl:1
	v_fmac_f32_e32 v6, v114, v114
	s_nop 1
	v_add_f32_dpp v6, v6, v6 quad_perm:[2,3,0,1] row_mask:0xf bank_mask:0xf bound_ctrl:1
	s_nop 1
	v_add_f32_dpp v6, v6, v6 row_half_mirror row_mask:0xf bank_mask:0xf bound_ctrl:1
	s_nop 1
	v_add_f32_dpp v6, v6, v6 row_mirror row_mask:0xf bank_mask:0xf bound_ctrl:1
	v_mov_b32_e32 v7, v6
	s_nop 1
	v_permlane16_swap_b32_e32 v6, v7
	v_add_f32_e32 v6, v6, v7
	v_mov_b32_e32 v7, v6
	s_nop 1
	v_permlane32_swap_b32_e32 v6, v7
	s_and_saveexec_b64 s[2:3], s[0:1]
	v_add_f32_e32 v6, v6, v7
	v_mov_b32_e32 v7, s17
	ds_write_b32 v7, v6 offset:20
	s_or_b64 exec, exec, s[2:3]
	v_mov_b32_e32 v104, s67
	s_waitcnt lgkmcnt(12)
	v_mul_f32_e32 v220, v15, v157
	v_fmac_f32_e32 v220, v14, v156
	v_fmac_f32_e32 v220, v16, v158
	v_fmac_f32_e32 v220, v17, v159
	ds_read_b128 v[204:207], v104 offset:192
	s_waitcnt lgkmcnt(12)
	v_fmac_f32_e32 v220, v19, v161
	v_fmac_f32_e32 v220, v18, v160
	v_fmac_f32_e32 v220, v20, v162
	v_fmac_f32_e32 v220, v21, v163
	ds_read_b128 v[208:211], v104 offset:208
	s_waitcnt lgkmcnt(12)
	v_fmac_f32_e32 v220, v23, v165
	v_fmac_f32_e32 v220, v22, v164
	v_fmac_f32_e32 v220, v24, v166
	v_fmac_f32_e32 v220, v25, v167
	ds_read_b128 v[212:215], v104 offset:224
	s_waitcnt lgkmcnt(12)
	v_fmac_f32_e32 v220, v27, v169
	v_fmac_f32_e32 v220, v26, v168
	v_fmac_f32_e32 v220, v28, v170
	v_fmac_f32_e32 v220, v29, v171
	ds_read_b128 v[216:219], v104 offset:240
	s_waitcnt lgkmcnt(12)
	v_fmac_f32_e32 v220, v31, v173
	v_fmac_f32_e32 v220, v30, v172
	v_fmac_f32_e32 v220, v32, v174
	v_fmac_f32_e32 v220, v33, v175
	ds_read_b128 v[156:159], v104 offset:1024
	s_waitcnt lgkmcnt(12)
	v_fmac_f32_e32 v220, v35, v177
	v_fmac_f32_e32 v220, v34, v176
	v_fmac_f32_e32 v220, v36, v178
	v_fmac_f32_e32 v220, v37, v179
	ds_read_b128 v[160:163], v104 offset:1040
	s_waitcnt lgkmcnt(12)
	v_fmac_f32_e32 v220, v39, v181
	v_fmac_f32_e32 v220, v38, v180
	v_fmac_f32_e32 v220, v40, v182
	v_fmac_f32_e32 v220, v41, v183
	ds_read_b128 v[164:167], v104 offset:1056
	s_waitcnt lgkmcnt(12)
	v_fmac_f32_e32 v220, v43, v185
	v_fmac_f32_e32 v220, v42, v184
	v_fmac_f32_e32 v220, v44, v186
	v_fmac_f32_e32 v220, v45, v187
	ds_read_b128 v[168:171], v104 offset:1072
	s_waitcnt lgkmcnt(12)
	v_fmac_f32_e32 v220, v47, v189
	v_fmac_f32_e32 v220, v46, v188
	v_fmac_f32_e32 v220, v48, v190
	v_fmac_f32_e32 v220, v49, v191
	ds_read_b128 v[172:175], v104 offset:1088
	s_waitcnt lgkmcnt(12)
	v_fmac_f32_e32 v220, v51, v193
	v_fmac_f32_e32 v220, v50, v192
	v_fmac_f32_e32 v220, v52, v194
	v_fmac_f32_e32 v220, v53, v195
	ds_read_b128 v[176:179], v104 offset:1104
	s_waitcnt lgkmcnt(12)
	v_fmac_f32_e32 v220, v55, v197
	v_fmac_f32_e32 v220, v54, v196
	v_fmac_f32_e32 v220, v56, v198
	v_fmac_f32_e32 v220, v57, v199
	ds_read_b128 v[180:183], v104 offset:1120
	s_waitcnt lgkmcnt(12)
	v_fmac_f32_e32 v220, v59, v201
	v_fmac_f32_e32 v220, v58, v200
	v_fmac_f32_e32 v220, v60, v202
	v_fmac_f32_e32 v220, v61, v203
	ds_read_b128 v[184:187], v104 offset:1136
	s_waitcnt lgkmcnt(11)
	v_fmac_f32_e32 v220, v63, v205
	v_fmac_f32_e32 v220, v62, v204
	v_fmac_f32_e32 v220, v64, v206
	v_fmac_f32_e32 v220, v65, v207
	ds_read_b128 v[188:191], v104 offset:1152
	s_waitcnt lgkmcnt(11)
	v_fmac_f32_e32 v220, v67, v209
	v_fmac_f32_e32 v220, v66, v208
	v_fmac_f32_e32 v220, v68, v210
	v_fmac_f32_e32 v220, v69, v211
	ds_read_b128 v[192:195], v104 offset:1168
	s_waitcnt lgkmcnt(11)
	v_fmac_f32_e32 v220, v71, v213
	v_fmac_f32_e32 v220, v70, v212
	v_fmac_f32_e32 v220, v72, v214
	v_fmac_f32_e32 v220, v73, v215
	ds_read_b128 v[196:199], v104 offset:1184
	s_waitcnt lgkmcnt(11)
	v_fmac_f32_e32 v220, v75, v217
	v_fmac_f32_e32 v220, v74, v216
	v_fmac_f32_e32 v220, v76, v218
	v_fmac_f32_e32 v220, v77, v219
	ds_read_b128 v[200:203], v104 offset:1200
	v_mul_f32_e32 v113, v78, v220
	v_mul_f32_e32 v6, v113, v113
	s_nop 1
	v_mov_b32_dpp v6, v6 quad_perm:[1,0,3,2] row_mask:0xf bank_mask:0xf bound_ctrl:1
	v_fmac_f32_e32 v6, v113, v113
	s_nop 1
	v_add_f32_dpp v6, v6, v6 quad_perm:[2,3,0,1] row_mask:0xf bank_mask:0xf bound_ctrl:1
	s_nop 1
	v_add_f32_dpp v6, v6, v6 row_half_mirror row_mask:0xf bank_mask:0xf bound_ctrl:1
	s_nop 1
	v_add_f32_dpp v6, v6, v6 row_mirror row_mask:0xf bank_mask:0xf bound_ctrl:1
	v_mov_b32_e32 v7, v6
	s_nop 1
	v_permlane16_swap_b32_e32 v6, v7
	v_add_f32_e32 v6, v6, v7
	v_mov_b32_e32 v7, v6
	s_nop 1
	v_permlane32_swap_b32_e32 v6, v7
	s_and_saveexec_b64 s[2:3], s[0:1]
	v_add_f32_e32 v6, v6, v7
	v_mov_b32_e32 v7, s17
	ds_write_b32 v7, v6 offset:24
	s_or_b64 exec, exec, s[2:3]
	v_mov_b32_e32 v104, s33
	s_waitcnt lgkmcnt(12)
	v_mul_f32_e32 v220, v15, v157
	v_fmac_f32_e32 v220, v14, v156
	v_fmac_f32_e32 v220, v16, v158
	v_fmac_f32_e32 v220, v17, v159
	ds_read_b128 v[204:207], v104 offset:192
	s_waitcnt lgkmcnt(12)
	v_fmac_f32_e32 v220, v19, v161
	v_fmac_f32_e32 v220, v18, v160
	v_fmac_f32_e32 v220, v20, v162
	v_fmac_f32_e32 v220, v21, v163
	ds_read_b128 v[208:211], v104 offset:208
	s_waitcnt lgkmcnt(12)
; #define LAS __attribute__((address_space(3)))
; __device__ __forceinline__ void pool_phase(const Params& a, LAS unsigned char* lds) {
;     ...
;         float o[32];
; #pragma unroll
;         for (int tt = 0; tt < 32; ++tt) { const int tl = half * 32 + tt; float acc = 0.f;
; #pragma unroll
;             for (int c4 = 0; c4 < 16; ++c4) { const f32x4 pv = *(const LAS f32x4*)(ps + tl * 256 + g * 64 + c4 * 4);
;                 acc += pv[0] * wreg[4 * c4] + pv[1] * wreg[4 * c4 + 1] + pv[2] * wreg[4 * c4 + 2] + pv[3] * wreg[4 * c4 + 3]; }
;             o[tt] = acc * pscale; const float s = wave_sum_valu(o[tt] * o[tt]);
;             if (lane == 0) ssl[g * 64 + tl] = s; }
	v_fmac_f32_e32 v220, v23, v165
	v_fmac_f32_e32 v220, v22, v164
	v_fmac_f32_e32 v220, v24, v166
	v_fmac_f32_e32 v220, v25, v167
	ds_read_b128 v[212:215], v104 offset:224
	s_waitcnt lgkmcnt(12)
	v_fmac_f32_e32 v220, v27, v169
	v_fmac_f32_e32 v220, v26, v168
	v_fmac_f32_e32 v220, v28, v170
	v_fmac_f32_e32 v220, v29, v171
	ds_read_b128 v[216:219], v104 offset:240
	s_waitcnt lgkmcnt(12)
	v_fmac_f32_e32 v220, v31, v173
	v_fmac_f32_e32 v220, v30, v172
	v_fmac_f32_e32 v220, v32, v174
	v_fmac_f32_e32 v220, v33, v175
	ds_read_b128 v[156:159], v104 offset:1024
	s_waitcnt lgkmcnt(12)
	v_fmac_f32_e32 v220, v35, v177
	v_fmac_f32_e32 v220, v34, v176
	v_fmac_f32_e32 v220, v36, v178
	v_fmac_f32_e32 v220, v37, v179
	ds_read_b128 v[160:163], v104 offset:1040
	s_waitcnt lgkmcnt(12)
	v_fmac_f32_e32 v220, v39, v181
	v_fmac_f32_e32 v220, v38, v180
	v_fmac_f32_e32 v220, v40, v182
	v_fmac_f32_e32 v220, v41, v183
	ds_read_b128 v[164:167], v104 offset:1056
	s_waitcnt lgkmcnt(12)
	v_fmac_f32_e32 v220, v43, v185
	v_fmac_f32_e32 v220, v42, v184
	v_fmac_f32_e32 v220, v44, v186
	v_fmac_f32_e32 v220, v45, v187
	ds_read_b128 v[168:171], v104 offset:1072
	s_waitcnt lgkmcnt(12)
	v_fmac_f32_e32 v220, v47, v189
	v_fmac_f32_e32 v220, v46, v188
	v_fmac_f32_e32 v220, v48, v190
	v_fmac_f32_e32 v220, v49, v191
	ds_read_b128 v[172:175], v104 offset:1088
	s_waitcnt lgkmcnt(12)
	v_fmac_f32_e32 v220, v51, v193
	v_fmac_f32_e32 v220, v50, v192
	v_fmac_f32_e32 v220, v52, v194
	v_fmac_f32_e32 v220, v53, v195
	ds_read_b128 v[176:179], v104 offset:1104
	s_waitcnt lgkmcnt(12)
	v_fmac_f32_e32 v220, v55, v197
	v_fmac_f32_e32 v220, v54, v196
	v_fmac_f32_e32 v220, v56, v198
	v_fmac_f32_e32 v220, v57, v199
	ds_read_b128 v[180:183], v104 offset:1120
	s_waitcnt lgkmcnt(12)
	v_fmac_f32_e32 v220, v59, v201
	v_fmac_f32_e32 v220, v58, v200
	v_fmac_f32_e32 v220, v60, v202
	v_fmac_f32_e32 v220, v61, v203
	ds_read_b128 v[184:187], v104 offset:1136
	s_waitcnt lgkmcnt(11)
	v_fmac_f32_e32 v220, v63, v205
	v_fmac_f32_e32 v220, v62, v204
	v_fmac_f32_e32 v220, v64, v206
	v_fmac_f32_e32 v220, v65, v207
	ds_read_b128 v[188:191], v104 offset:1152
	s_waitcnt lgkmcnt(11)
	v_fmac_f32_e32 v220, v67, v209
	v_fmac_f32_e32 v220, v66, v208
	v_fmac_f32_e32 v220, v68, v210
	v_fmac_f32_e32 v220, v69, v211
	ds_read_b128 v[192:195], v104 offset:1168
	s_waitcnt lgkmcnt(11)
	v_fmac_f32_e32 v220, v71, v213
	v_fmac_f32_e32 v220, v70, v212
	v_fmac_f32_e32 v220, v72, v214
	v_fmac_f32_e32 v220, v73, v215
	ds_read_b128 v[196:199], v104 offset:1184
	s_waitcnt lgkmcnt(11)
	v_fmac_f32_e32 v220, v75, v217
	v_fmac_f32_e32 v220, v74, v216
	v_fmac_f32_e32 v220, v76, v218
	v_fmac_f32_e32 v220, v77, v219
	ds_read_b128 v[200:203], v104 offset:1200
	v_mul_f32_e32 v112, v78, v220
	v_mul_f32_e32 v6, v112, v112
	s_nop 1
	v_mov_b32_dpp v6, v6 quad_perm:[1,0,3,2] row_mask:0xf bank_mask:0xf bound_ctrl:1
	v_fmac_f32_e32 v6, v112, v112
	s_nop 1
	v_add_f32_dpp v6, v6, v6 quad_perm:[2,3,0,1] row_mask:0xf bank_mask:0xf bound_ctrl:1
	s_nop 1
	v_add_f32_dpp v6, v6, v6 row_half_mirror row_mask:0xf bank_mask:0xf bound_ctrl:1
	s_nop 1
	v_add_f32_dpp v6, v6, v6 row_mirror row_mask:0xf bank_mask:0xf bound_ctrl:1
	v_mov_b32_e32 v7, v6
	s_nop 1
	v_permlane16_swap_b32_e32 v6, v7
	v_add_f32_e32 v6, v6, v7
	v_mov_b32_e32 v7, v6
	s_nop 1
	v_permlane32_swap_b32_e32 v6, v7
	s_and_saveexec_b64 s[2:3], s[0:1]
	v_add_f32_e32 v6, v6, v7
	v_mov_b32_e32 v7, s17
	ds_write_b32 v7, v6 offset:28
	s_or_b64 exec, exec, s[2:3]
	v_mov_b32_e32 v104, s28
	s_waitcnt lgkmcnt(12)
	v_mul_f32_e32 v220, v15, v157
	v_fmac_f32_e32 v220, v14, v156
	v_fmac_f32_e32 v220, v16, v158
	v_fmac_f32_e32 v220, v17, v159
	ds_read_b128 v[204:207], v104 offset:192
	s_waitcnt lgkmcnt(12)
	v_fmac_f32_e32 v220, v19, v161
	v_fmac_f32_e32 v220, v18, v160
	v_fmac_f32_e32 v220, v20, v162
	v_fmac_f32_e32 v220, v21, v163
	ds_read_b128 v[208:211], v104 offset:208
	s_waitcnt lgkmcnt(12)
	v_fmac_f32_e32 v220, v23, v165
	v_fmac_f32_e32 v220, v22, v164
	v_fmac_f32_e32 v220, v24, v166
	v_fmac_f32_e32 v220, v25, v167
	ds_read_b128 v[212:215], v104 offset:224
	s_waitcnt lgkmcnt(12)
	v_fmac_f32_e32 v220, v27, v169
	v_fmac_f32_e32 v220, v26, v168
	v_fmac_f32_e32 v220, v28, v170
	v_fmac_f32_e32 v220, v29, v171
	ds_read_b128 v[216:219], v104 offset:240
	s_waitcnt lgkmcnt(12)
	v_fmac_f32_e32 v220, v31, v173
	v_fmac_f32_e32 v220, v30, v172
	v_fmac_f32_e32 v220, v32, v174
	v_fmac_f32_e32 v220, v33, v175
	ds_read_b128 v[156:159], v104 offset:1024
	s_waitcnt lgkmcnt(12)
	v_fmac_f32_e32 v220, v35, v177
	v_fmac_f32_e32 v220, v34, v176
	v_fmac_f32_e32 v220, v36, v178
	v_fmac_f32_e32 v220, v37, v179
	ds_read_b128 v[160:163], v104 offset:1040
	s_waitcnt lgkmcnt(12)
	v_fmac_f32_e32 v220, v39, v181
	v_fmac_f32_e32 v220, v38, v180
	v_fmac_f32_e32 v220, v40, v182
	v_fmac_f32_e32 v220, v41, v183
	ds_read_b128 v[164:167], v104 offset:1056
	s_waitcnt lgkmcnt(12)
	v_fmac_f32_e32 v220, v43, v185
	v_fmac_f32_e32 v220, v42, v184
	v_fmac_f32_e32 v220, v44, v186
	v_fmac_f32_e32 v220, v45, v187
	ds_read_b128 v[168:171], v104 offset:1072
	s_waitcnt lgkmcnt(12)
	v_fmac_f32_e32 v220, v47, v189
	v_fmac_f32_e32 v220, v46, v188
	v_fmac_f32_e32 v220, v48, v190
	v_fmac_f32_e32 v220, v49, v191
	ds_read_b128 v[172:175], v104 offset:1088
	s_waitcnt lgkmcnt(12)
	v_fmac_f32_e32 v220, v51, v193
	v_fmac_f32_e32 v220, v50, v192
	v_fmac_f32_e32 v220, v52, v194
	v_fmac_f32_e32 v220, v53, v195
	ds_read_b128 v[176:179], v104 offset:1104
	s_waitcnt lgkmcnt(12)
	v_fmac_f32_e32 v220, v55, v197
	v_fmac_f32_e32 v220, v54, v196
	v_fmac_f32_e32 v220, v56, v198
	v_fmac_f32_e32 v220, v57, v199
	ds_read_b128 v[180:183], v104 offset:1120
	s_waitcnt lgkmcnt(12)
; #define LAS __attribute__((address_space(3)))
; #define DPPADD_(v, ctrl) ((v) + __builtin_bit_cast(float, __builtin_amdgcn_update_dpp(0, __builtin_bit_cast(int, (v)), (ctrl), 0xf, 0xf, true)))
; __device__ __forceinline__ float wave_sum_valu(float v) {
;     v = DPPADD_(v, 0xB1); v = DPPADD_(v, 0x4E); v = DPPADD_(v, 0x141); v = DPPADD_(v, 0x140);
;     { auto r = __builtin_amdgcn_permlane16_swap(__float_as_uint(v), __float_as_uint(v), false, false); v = __uint_as_float(r[0]) + __uint_as_float(r[1]); }
;     { auto r = __builtin_amdgcn_permlane32_swap(__float_as_uint(v), __float_as_uint(v), false, false); v = __uint_as_float(r[0]) + __uint_as_float(r[1]); }
;     return v;
; __device__ __forceinline__ void pool_phase(const Params& a, LAS unsigned char* lds) {
;     ...
;         for (int tt = 0; tt < 32; ++tt) { const int tl = half * 32 + tt; float acc = 0.f;
; #pragma unroll
;             for (int c4 = 0; c4 < 16; ++c4) { const f32x4 pv = *(const LAS f32x4*)(ps + tl * 256 + g * 64 + c4 * 4);
;                 acc += pv[0] * wreg[4 * c4] + pv[1] * wreg[4 * c4 + 1] + pv[2] * wreg[4 * c4 + 2] + pv[3] * wreg[4 * c4 + 3]; }
;             o[tt] = acc * pscale; const float s = wave_sum_valu(o[tt] * o[tt]);
;             if (lane == 0) ssl[g * 64 + tl] = s; }
	v_fmac_f32_e32 v220, v59, v201
	v_fmac_f32_e32 v220, v58, v200
	v_fmac_f32_e32 v220, v60, v202
	v_fmac_f32_e32 v220, v61, v203
	ds_read_b128 v[184:187], v104 offset:1136
	s_waitcnt lgkmcnt(11)
	v_fmac_f32_e32 v220, v63, v205
	v_fmac_f32_e32 v220, v62, v204
	v_fmac_f32_e32 v220, v64, v206
	v_fmac_f32_e32 v220, v65, v207
	ds_read_b128 v[188:191], v104 offset:1152
	s_waitcnt lgkmcnt(11)
	v_fmac_f32_e32 v220, v67, v209
	v_fmac_f32_e32 v220, v66, v208
	v_fmac_f32_e32 v220, v68, v210
	v_fmac_f32_e32 v220, v69, v211
	ds_read_b128 v[192:195], v104 offset:1168
	s_waitcnt lgkmcnt(11)
	v_fmac_f32_e32 v220, v71, v213
	v_fmac_f32_e32 v220, v70, v212
	v_fmac_f32_e32 v220, v72, v214
	v_fmac_f32_e32 v220, v73, v215
	ds_read_b128 v[196:199], v104 offset:1184
	s_waitcnt lgkmcnt(11)
	v_fmac_f32_e32 v220, v75, v217
	v_fmac_f32_e32 v220, v74, v216
	v_fmac_f32_e32 v220, v76, v218
	v_fmac_f32_e32 v220, v77, v219
	ds_read_b128 v[200:203], v104 offset:1200
	v_mul_f32_e32 v111, v78, v220
	v_mul_f32_e32 v6, v111, v111
	s_nop 1
	v_mov_b32_dpp v6, v6 quad_perm:[1,0,3,2] row_mask:0xf bank_mask:0xf bound_ctrl:1
	v_fmac_f32_e32 v6, v111, v111
	s_nop 1
	v_add_f32_dpp v6, v6, v6 quad_perm:[2,3,0,1] row_mask:0xf bank_mask:0xf bound_ctrl:1
	s_nop 1
	v_add_f32_dpp v6, v6, v6 row_half_mirror row_mask:0xf bank_mask:0xf bound_ctrl:1
	s_nop 1
	v_add_f32_dpp v6, v6, v6 row_mirror row_mask:0xf bank_mask:0xf bound_ctrl:1
	v_mov_b32_e32 v7, v6
	s_nop 1
	v_permlane16_swap_b32_e32 v6, v7
	v_add_f32_e32 v6, v6, v7
	v_mov_b32_e32 v7, v6
	s_nop 1
	v_permlane32_swap_b32_e32 v6, v7
	s_and_saveexec_b64 s[2:3], s[0:1]
	v_add_f32_e32 v6, v6, v7
	v_mov_b32_e32 v7, s17
	ds_write_b32 v7, v6 offset:32
	s_or_b64 exec, exec, s[2:3]
	v_mov_b32_e32 v104, s29
	s_waitcnt lgkmcnt(12)
	v_mul_f32_e32 v220, v15, v157
	v_fmac_f32_e32 v220, v14, v156
	v_fmac_f32_e32 v220, v16, v158
	v_fmac_f32_e32 v220, v17, v159
	ds_read_b128 v[204:207], v104 offset:192
	s_waitcnt lgkmcnt(12)
	v_fmac_f32_e32 v220, v19, v161
	v_fmac_f32_e32 v220, v18, v160
	v_fmac_f32_e32 v220, v20, v162
	v_fmac_f32_e32 v220, v21, v163
	ds_read_b128 v[208:211], v104 offset:208
	s_waitcnt lgkmcnt(12)
	v_fmac_f32_e32 v220, v23, v165
	v_fmac_f32_e32 v220, v22, v164
	v_fmac_f32_e32 v220, v24, v166
	v_fmac_f32_e32 v220, v25, v167
	ds_read_b128 v[212:215], v104 offset:224
	s_waitcnt lgkmcnt(12)
	v_fmac_f32_e32 v220, v27, v169
	v_fmac_f32_e32 v220, v26, v168
	v_fmac_f32_e32 v220, v28, v170
	v_fmac_f32_e32 v220, v29, v171
	ds_read_b128 v[216:219], v104 offset:240
	s_waitcnt lgkmcnt(12)
	v_fmac_f32_e32 v220, v31, v173
	v_fmac_f32_e32 v220, v30, v172
	v_fmac_f32_e32 v220, v32, v174
	v_fmac_f32_e32 v220, v33, v175
	ds_read_b128 v[156:159], v104 offset:1024
	s_waitcnt lgkmcnt(12)
	v_fmac_f32_e32 v220, v35, v177
	v_fmac_f32_e32 v220, v34, v176
	v_fmac_f32_e32 v220, v36, v178
	v_fmac_f32_e32 v220, v37, v179
	ds_read_b128 v[160:163], v104 offset:1040
	s_waitcnt lgkmcnt(12)
	v_fmac_f32_e32 v220, v39, v181
	v_fmac_f32_e32 v220, v38, v180
	v_fmac_f32_e32 v220, v40, v182
	v_fmac_f32_e32 v220, v41, v183
	ds_read_b128 v[164:167], v104 offset:1056
	s_waitcnt lgkmcnt(12)
	v_fmac_f32_e32 v220, v43, v185
	v_fmac_f32_e32 v220, v42, v184
	v_fmac_f32_e32 v220, v44, v186
	v_fmac_f32_e32 v220, v45, v187
	ds_read_b128 v[168:171], v104 offset:1072
	s_waitcnt lgkmcnt(12)
	v_fmac_f32_e32 v220, v47, v189
	v_fmac_f32_e32 v220, v46, v188
	v_fmac_f32_e32 v220, v48, v190
	v_fmac_f32_e32 v220, v49, v191
	ds_read_b128 v[172:175], v104 offset:1088
	s_waitcnt lgkmcnt(12)
	v_fmac_f32_e32 v220, v51, v193
	v_fmac_f32_e32 v220, v50, v192
	v_fmac_f32_e32 v220, v52, v194
	v_fmac_f32_e32 v220, v53, v195
	ds_read_b128 v[176:179], v104 offset:1104
	s_waitcnt lgkmcnt(12)
	v_fmac_f32_e32 v220, v55, v197
	v_fmac_f32_e32 v220, v54, v196
	v_fmac_f32_e32 v220, v56, v198
	v_fmac_f32_e32 v220, v57, v199
	ds_read_b128 v[180:183], v104 offset:1120
	s_waitcnt lgkmcnt(12)
	v_fmac_f32_e32 v220, v59, v201
	v_fmac_f32_e32 v220, v58, v200
	v_fmac_f32_e32 v220, v60, v202
	v_fmac_f32_e32 v220, v61, v203
	ds_read_b128 v[184:187], v104 offset:1136
	s_waitcnt lgkmcnt(11)
	v_fmac_f32_e32 v220, v63, v205
	v_fmac_f32_e32 v220, v62, v204
	v_fmac_f32_e32 v220, v64, v206
	v_fmac_f32_e32 v220, v65, v207
	ds_read_b128 v[188:191], v104 offset:1152
	s_waitcnt lgkmcnt(11)
	v_fmac_f32_e32 v220, v67, v209
	v_fmac_f32_e32 v220, v66, v208
	v_fmac_f32_e32 v220, v68, v210
	v_fmac_f32_e32 v220, v69, v211
	ds_read_b128 v[192:195], v104 offset:1168
	s_waitcnt lgkmcnt(11)
	v_fmac_f32_e32 v220, v71, v213
	v_fmac_f32_e32 v220, v70, v212
	v_fmac_f32_e32 v220, v72, v214
	v_fmac_f32_e32 v220, v73, v215
	ds_read_b128 v[196:199], v104 offset:1184
	s_waitcnt lgkmcnt(11)
	v_fmac_f32_e32 v220, v75, v217
	v_fmac_f32_e32 v220, v74, v216
	v_fmac_f32_e32 v220, v76, v218
	v_fmac_f32_e32 v220, v77, v219
	ds_read_b128 v[200:203], v104 offset:1200
	v_mul_f32_e32 v110, v78, v220
	v_mul_f32_e32 v6, v110, v110
	s_nop 1
	v_mov_b32_dpp v6, v6 quad_perm:[1,0,3,2] row_mask:0xf bank_mask:0xf bound_ctrl:1
	v_fmac_f32_e32 v6, v110, v110
	s_nop 1
	v_add_f32_dpp v6, v6, v6 quad_perm:[2,3,0,1] row_mask:0xf bank_mask:0xf bound_ctrl:1
	s_nop 1
	v_add_f32_dpp v6, v6, v6 row_half_mirror row_mask:0xf bank_mask:0xf bound_ctrl:1
	s_nop 1
	v_add_f32_dpp v6, v6, v6 row_mirror row_mask:0xf bank_mask:0xf bound_ctrl:1
	v_mov_b32_e32 v7, v6
	s_nop 1
	v_permlane16_swap_b32_e32 v6, v7
	v_add_f32_e32 v6, v6, v7
	v_mov_b32_e32 v7, v6
	s_nop 1
	v_permlane32_swap_b32_e32 v6, v7
	s_and_saveexec_b64 s[2:3], s[0:1]
	v_add_f32_e32 v6, v6, v7
	v_mov_b32_e32 v7, s17
	ds_write_b32 v7, v6 offset:36
	s_or_b64 exec, exec, s[2:3]
	v_mov_b32_e32 v104, s68
	s_waitcnt lgkmcnt(12)
; #define LAS __attribute__((address_space(3)))
; #define DPPADD_(v, ctrl) ((v) + __builtin_bit_cast(float, __builtin_amdgcn_update_dpp(0, __builtin_bit_cast(int, (v)), (ctrl), 0xf, 0xf, true)))
; __device__ __forceinline__ float wave_sum_valu(float v) {
;     v = DPPADD_(v, 0xB1); v = DPPADD_(v, 0x4E); v = DPPADD_(v, 0x141); v = DPPADD_(v, 0x140);
;     { auto r = __builtin_amdgcn_permlane16_swap(__float_as_uint(v), __float_as_uint(v), false, false); v = __uint_as_float(r[0]) + __uint_as_float(r[1]); }
;     { auto r = __builtin_amdgcn_permlane32_swap(__float_as_uint(v), __float_as_uint(v), false, false); v = __uint_as_float(r[0]) + __uint_as_float(r[1]); }
;     return v;
; __device__ __forceinline__ void pool_phase(const Params& a, LAS unsigned char* lds) {
;     ...
;         for (int tt = 0; tt < 32; ++tt) { const int tl = half * 32 + tt; float acc = 0.f;
; #pragma unroll
;             for (int c4 = 0; c4 < 16; ++c4) { const f32x4 pv = *(const LAS f32x4*)(ps + tl * 256 + g * 64 + c4 * 4);
;                 acc += pv[0] * wreg[4 * c4] + pv[1] * wreg[4 * c4 + 1] + pv[2] * wreg[4 * c4 + 2] + pv[3] * wreg[4 * c4 + 3]; }
;             o[tt] = acc * pscale; const float s = wave_sum_valu(o[tt] * o[tt]);
;             if (lane == 0) ssl[g * 64 + tl] = s; }
	v_mul_f32_e32 v220, v15, v157
	v_fmac_f32_e32 v220, v14, v156
	v_fmac_f32_e32 v220, v16, v158
	v_fmac_f32_e32 v220, v17, v159
	ds_read_b128 v[204:207], v104 offset:192
	s_waitcnt lgkmcnt(12)
	v_fmac_f32_e32 v220, v19, v161
	v_fmac_f32_e32 v220, v18, v160
	v_fmac_f32_e32 v220, v20, v162
	v_fmac_f32_e32 v220, v21, v163
	ds_read_b128 v[208:211], v104 offset:208
	s_waitcnt lgkmcnt(12)
	v_fmac_f32_e32 v220, v23, v165
	v_fmac_f32_e32 v220, v22, v164
	v_fmac_f32_e32 v220, v24, v166
	v_fmac_f32_e32 v220, v25, v167
	ds_read_b128 v[212:215], v104 offset:224
	s_waitcnt lgkmcnt(12)
	v_fmac_f32_e32 v220, v27, v169
	v_fmac_f32_e32 v220, v26, v168
	v_fmac_f32_e32 v220, v28, v170
	v_fmac_f32_e32 v220, v29, v171
	ds_read_b128 v[216:219], v104 offset:240
	s_waitcnt lgkmcnt(12)
	v_fmac_f32_e32 v220, v31, v173
	v_fmac_f32_e32 v220, v30, v172
	v_fmac_f32_e32 v220, v32, v174
	v_fmac_f32_e32 v220, v33, v175
	ds_read_b128 v[156:159], v104 offset:1024
	s_waitcnt lgkmcnt(12)
	v_fmac_f32_e32 v220, v35, v177
	v_fmac_f32_e32 v220, v34, v176
	v_fmac_f32_e32 v220, v36, v178
	v_fmac_f32_e32 v220, v37, v179
	ds_read_b128 v[160:163], v104 offset:1040
	s_waitcnt lgkmcnt(12)
	v_fmac_f32_e32 v220, v39, v181
	v_fmac_f32_e32 v220, v38, v180
	v_fmac_f32_e32 v220, v40, v182
	v_fmac_f32_e32 v220, v41, v183
	ds_read_b128 v[164:167], v104 offset:1056
	s_waitcnt lgkmcnt(12)
	v_fmac_f32_e32 v220, v43, v185
	v_fmac_f32_e32 v220, v42, v184
	v_fmac_f32_e32 v220, v44, v186
	v_fmac_f32_e32 v220, v45, v187
	ds_read_b128 v[168:171], v104 offset:1072
	s_waitcnt lgkmcnt(12)
	v_fmac_f32_e32 v220, v47, v189
	v_fmac_f32_e32 v220, v46, v188
	v_fmac_f32_e32 v220, v48, v190
	v_fmac_f32_e32 v220, v49, v191
	ds_read_b128 v[172:175], v104 offset:1088
	s_waitcnt lgkmcnt(12)
	v_fmac_f32_e32 v220, v51, v193
	v_fmac_f32_e32 v220, v50, v192
	v_fmac_f32_e32 v220, v52, v194
	v_fmac_f32_e32 v220, v53, v195
	ds_read_b128 v[176:179], v104 offset:1104
	s_waitcnt lgkmcnt(12)
	v_fmac_f32_e32 v220, v55, v197
	v_fmac_f32_e32 v220, v54, v196
	v_fmac_f32_e32 v220, v56, v198
	v_fmac_f32_e32 v220, v57, v199
	ds_read_b128 v[180:183], v104 offset:1120
	s_waitcnt lgkmcnt(12)
	v_fmac_f32_e32 v220, v59, v201
	v_fmac_f32_e32 v220, v58, v200
	v_fmac_f32_e32 v220, v60, v202
	v_fmac_f32_e32 v220, v61, v203
	ds_read_b128 v[184:187], v104 offset:1136
	s_waitcnt lgkmcnt(11)
	v_fmac_f32_e32 v220, v63, v205
	v_fmac_f32_e32 v220, v62, v204
	v_fmac_f32_e32 v220, v64, v206
	v_fmac_f32_e32 v220, v65, v207
	ds_read_b128 v[188:191], v104 offset:1152
	s_waitcnt lgkmcnt(11)
	v_fmac_f32_e32 v220, v67, v209
	v_fmac_f32_e32 v220, v66, v208
	v_fmac_f32_e32 v220, v68, v210
	v_fmac_f32_e32 v220, v69, v211
	ds_read_b128 v[192:195], v104 offset:1168
	s_waitcnt lgkmcnt(11)
	v_fmac_f32_e32 v220, v71, v213
	v_fmac_f32_e32 v220, v70, v212
	v_fmac_f32_e32 v220, v72, v214
	v_fmac_f32_e32 v220, v73, v215
	ds_read_b128 v[196:199], v104 offset:1184
	s_waitcnt lgkmcnt(11)
	v_fmac_f32_e32 v220, v75, v217
	v_fmac_f32_e32 v220, v74, v216
	v_fmac_f32_e32 v220, v76, v218
	v_fmac_f32_e32 v220, v77, v219
	ds_read_b128 v[200:203], v104 offset:1200
	v_mul_f32_e32 v109, v78, v220
	v_mul_f32_e32 v6, v109, v109
	s_nop 1
	v_mov_b32_dpp v6, v6 quad_perm:[1,0,3,2] row_mask:0xf bank_mask:0xf bound_ctrl:1
	v_fmac_f32_e32 v6, v109, v109
	s_nop 1
	v_add_f32_dpp v6, v6, v6 quad_perm:[2,3,0,1] row_mask:0xf bank_mask:0xf bound_ctrl:1
	s_nop 1
	v_add_f32_dpp v6, v6, v6 row_half_mirror row_mask:0xf bank_mask:0xf bound_ctrl:1
	s_nop 1
	v_add_f32_dpp v6, v6, v6 row_mirror row_mask:0xf bank_mask:0xf bound_ctrl:1
	v_mov_b32_e32 v7, v6
	s_nop 1
	v_permlane16_swap_b32_e32 v6, v7
	v_add_f32_e32 v6, v6, v7
	v_mov_b32_e32 v7, v6
	s_nop 1
	v_permlane32_swap_b32_e32 v6, v7
	s_and_saveexec_b64 s[2:3], s[0:1]
	v_add_f32_e32 v6, v6, v7
	v_mov_b32_e32 v7, s17
	ds_write_b32 v7, v6 offset:40
	s_or_b64 exec, exec, s[2:3]
	v_mov_b32_e32 v104, s69
	s_waitcnt lgkmcnt(12)
	v_mul_f32_e32 v220, v15, v157
	v_fmac_f32_e32 v220, v14, v156
	v_fmac_f32_e32 v220, v16, v158
	v_fmac_f32_e32 v220, v17, v159
	ds_read_b128 v[204:207], v104 offset:192
	s_waitcnt lgkmcnt(12)
	v_fmac_f32_e32 v220, v19, v161
	v_fmac_f32_e32 v220, v18, v160
	v_fmac_f32_e32 v220, v20, v162
	v_fmac_f32_e32 v220, v21, v163
	ds_read_b128 v[208:211], v104 offset:208
	s_waitcnt lgkmcnt(12)
	v_fmac_f32_e32 v220, v23, v165
	v_fmac_f32_e32 v220, v22, v164
	v_fmac_f32_e32 v220, v24, v166
	v_fmac_f32_e32 v220, v25, v167
	ds_read_b128 v[212:215], v104 offset:224
	s_waitcnt lgkmcnt(12)
	v_fmac_f32_e32 v220, v27, v169
	v_fmac_f32_e32 v220, v26, v168
	v_fmac_f32_e32 v220, v28, v170
	v_fmac_f32_e32 v220, v29, v171
	ds_read_b128 v[216:219], v104 offset:240
	s_waitcnt lgkmcnt(12)
	v_fmac_f32_e32 v220, v31, v173
	v_fmac_f32_e32 v220, v30, v172
	v_fmac_f32_e32 v220, v32, v174
	v_fmac_f32_e32 v220, v33, v175
	ds_read_b128 v[156:159], v104 offset:1024
	s_waitcnt lgkmcnt(12)
	v_fmac_f32_e32 v220, v35, v177
	v_fmac_f32_e32 v220, v34, v176
	v_fmac_f32_e32 v220, v36, v178
	v_fmac_f32_e32 v220, v37, v179
	ds_read_b128 v[160:163], v104 offset:1040
	s_waitcnt lgkmcnt(12)
	v_fmac_f32_e32 v220, v39, v181
	v_fmac_f32_e32 v220, v38, v180
	v_fmac_f32_e32 v220, v40, v182
	v_fmac_f32_e32 v220, v41, v183
	ds_read_b128 v[164:167], v104 offset:1056
	s_waitcnt lgkmcnt(12)
	v_fmac_f32_e32 v220, v43, v185
	v_fmac_f32_e32 v220, v42, v184
	v_fmac_f32_e32 v220, v44, v186
	v_fmac_f32_e32 v220, v45, v187
	ds_read_b128 v[168:171], v104 offset:1072
	s_waitcnt lgkmcnt(12)
	v_fmac_f32_e32 v220, v47, v189
	v_fmac_f32_e32 v220, v46, v188
	v_fmac_f32_e32 v220, v48, v190
	v_fmac_f32_e32 v220, v49, v191
	ds_read_b128 v[172:175], v104 offset:1088
	s_waitcnt lgkmcnt(12)
; #define LAS __attribute__((address_space(3)))
; #define DPPADD_(v, ctrl) ((v) + __builtin_bit_cast(float, __builtin_amdgcn_update_dpp(0, __builtin_bit_cast(int, (v)), (ctrl), 0xf, 0xf, true)))
; __device__ __forceinline__ float wave_sum_valu(float v) {
;     v = DPPADD_(v, 0xB1); v = DPPADD_(v, 0x4E); v = DPPADD_(v, 0x141); v = DPPADD_(v, 0x140);
;     { auto r = __builtin_amdgcn_permlane16_swap(__float_as_uint(v), __float_as_uint(v), false, false); v = __uint_as_float(r[0]) + __uint_as_float(r[1]); }
;     { auto r = __builtin_amdgcn_permlane32_swap(__float_as_uint(v), __float_as_uint(v), false, false); v = __uint_as_float(r[0]) + __uint_as_float(r[1]); }
;     return v;
; __device__ __forceinline__ void pool_phase(const Params& a, LAS unsigned char* lds) {
;     ...
;         for (int tt = 0; tt < 32; ++tt) { const int tl = half * 32 + tt; float acc = 0.f;
; #pragma unroll
;             for (int c4 = 0; c4 < 16; ++c4) { const f32x4 pv = *(const LAS f32x4*)(ps + tl * 256 + g * 64 + c4 * 4);
;                 acc += pv[0] * wreg[4 * c4] + pv[1] * wreg[4 * c4 + 1] + pv[2] * wreg[4 * c4 + 2] + pv[3] * wreg[4 * c4 + 3]; }
;             o[tt] = acc * pscale; const float s = wave_sum_valu(o[tt] * o[tt]);
;             if (lane == 0) ssl[g * 64 + tl] = s; }
	v_fmac_f32_e32 v220, v51, v193
	v_fmac_f32_e32 v220, v50, v192
	v_fmac_f32_e32 v220, v52, v194
	v_fmac_f32_e32 v220, v53, v195
	ds_read_b128 v[176:179], v104 offset:1104
	s_waitcnt lgkmcnt(12)
	v_fmac_f32_e32 v220, v55, v197
	v_fmac_f32_e32 v220, v54, v196
	v_fmac_f32_e32 v220, v56, v198
	v_fmac_f32_e32 v220, v57, v199
	ds_read_b128 v[180:183], v104 offset:1120
	s_waitcnt lgkmcnt(12)
	v_fmac_f32_e32 v220, v59, v201
	v_fmac_f32_e32 v220, v58, v200
	v_fmac_f32_e32 v220, v60, v202
	v_fmac_f32_e32 v220, v61, v203
	ds_read_b128 v[184:187], v104 offset:1136
	s_waitcnt lgkmcnt(11)
	v_fmac_f32_e32 v220, v63, v205
	v_fmac_f32_e32 v220, v62, v204
	v_fmac_f32_e32 v220, v64, v206
	v_fmac_f32_e32 v220, v65, v207
	ds_read_b128 v[188:191], v104 offset:1152
	s_waitcnt lgkmcnt(11)
	v_fmac_f32_e32 v220, v67, v209
	v_fmac_f32_e32 v220, v66, v208
	v_fmac_f32_e32 v220, v68, v210
	v_fmac_f32_e32 v220, v69, v211
	ds_read_b128 v[192:195], v104 offset:1168
	s_waitcnt lgkmcnt(11)
	v_fmac_f32_e32 v220, v71, v213
	v_fmac_f32_e32 v220, v70, v212
	v_fmac_f32_e32 v220, v72, v214
	v_fmac_f32_e32 v220, v73, v215
	ds_read_b128 v[196:199], v104 offset:1184
	s_waitcnt lgkmcnt(11)
	v_fmac_f32_e32 v220, v75, v217
	v_fmac_f32_e32 v220, v74, v216
	v_fmac_f32_e32 v220, v76, v218
	v_fmac_f32_e32 v220, v77, v219
	ds_read_b128 v[200:203], v104 offset:1200
	v_mul_f32_e32 v108, v78, v220
	v_mul_f32_e32 v6, v108, v108
	s_nop 1
	v_mov_b32_dpp v6, v6 quad_perm:[1,0,3,2] row_mask:0xf bank_mask:0xf bound_ctrl:1
	v_fmac_f32_e32 v6, v108, v108
	s_nop 1
	v_add_f32_dpp v6, v6, v6 quad_perm:[2,3,0,1] row_mask:0xf bank_mask:0xf bound_ctrl:1
	s_nop 1
	v_add_f32_dpp v6, v6, v6 row_half_mirror row_mask:0xf bank_mask:0xf bound_ctrl:1
	s_nop 1
	v_add_f32_dpp v6, v6, v6 row_mirror row_mask:0xf bank_mask:0xf bound_ctrl:1
	v_mov_b32_e32 v7, v6
	s_nop 1
	v_permlane16_swap_b32_e32 v6, v7
	v_add_f32_e32 v6, v6, v7
	v_mov_b32_e32 v7, v6
	s_nop 1
	v_permlane32_swap_b32_e32 v6, v7
	s_and_saveexec_b64 s[2:3], s[0:1]
	v_add_f32_e32 v6, v6, v7
	v_mov_b32_e32 v7, s17
	ds_write_b32 v7, v6 offset:44
	s_or_b64 exec, exec, s[2:3]
	v_mov_b32_e32 v104, s70
	s_waitcnt lgkmcnt(12)
	v_mul_f32_e32 v220, v15, v157
	v_fmac_f32_e32 v220, v14, v156
	v_fmac_f32_e32 v220, v16, v158
	v_fmac_f32_e32 v220, v17, v159
	ds_read_b128 v[204:207], v104 offset:192
	s_waitcnt lgkmcnt(12)
	v_fmac_f32_e32 v220, v19, v161
	v_fmac_f32_e32 v220, v18, v160
	v_fmac_f32_e32 v220, v20, v162
	v_fmac_f32_e32 v220, v21, v163
	ds_read_b128 v[208:211], v104 offset:208
	s_waitcnt lgkmcnt(12)
	v_fmac_f32_e32 v220, v23, v165
	v_fmac_f32_e32 v220, v22, v164
	v_fmac_f32_e32 v220, v24, v166
	v_fmac_f32_e32 v220, v25, v167
	ds_read_b128 v[212:215], v104 offset:224
	s_waitcnt lgkmcnt(12)
	v_fmac_f32_e32 v220, v27, v169
	v_fmac_f32_e32 v220, v26, v168
	v_fmac_f32_e32 v220, v28, v170
	v_fmac_f32_e32 v220, v29, v171
	ds_read_b128 v[216:219], v104 offset:240
	s_waitcnt lgkmcnt(12)
	v_fmac_f32_e32 v220, v31, v173
	v_fmac_f32_e32 v220, v30, v172
	v_fmac_f32_e32 v220, v32, v174
	v_fmac_f32_e32 v220, v33, v175
	ds_read_b128 v[156:159], v104 offset:1024
	s_waitcnt lgkmcnt(12)
	v_fmac_f32_e32 v220, v35, v177
	v_fmac_f32_e32 v220, v34, v176
	v_fmac_f32_e32 v220, v36, v178
	v_fmac_f32_e32 v220, v37, v179
	ds_read_b128 v[160:163], v104 offset:1040
	s_waitcnt lgkmcnt(12)
	v_fmac_f32_e32 v220, v39, v181
	v_fmac_f32_e32 v220, v38, v180
	v_fmac_f32_e32 v220, v40, v182
	v_fmac_f32_e32 v220, v41, v183
	ds_read_b128 v[164:167], v104 offset:1056
	s_waitcnt lgkmcnt(12)
	v_fmac_f32_e32 v220, v43, v185
	v_fmac_f32_e32 v220, v42, v184
	v_fmac_f32_e32 v220, v44, v186
	v_fmac_f32_e32 v220, v45, v187
	ds_read_b128 v[168:171], v104 offset:1072
	s_waitcnt lgkmcnt(12)
	v_fmac_f32_e32 v220, v47, v189
	v_fmac_f32_e32 v220, v46, v188
	v_fmac_f32_e32 v220, v48, v190
	v_fmac_f32_e32 v220, v49, v191
	ds_read_b128 v[172:175], v104 offset:1088
	s_waitcnt lgkmcnt(12)
	v_fmac_f32_e32 v220, v51, v193
	v_fmac_f32_e32 v220, v50, v192
	v_fmac_f32_e32 v220, v52, v194
	v_fmac_f32_e32 v220, v53, v195
	ds_read_b128 v[176:179], v104 offset:1104
	s_waitcnt lgkmcnt(12)
	v_fmac_f32_e32 v220, v55, v197
	v_fmac_f32_e32 v220, v54, v196
	v_fmac_f32_e32 v220, v56, v198
	v_fmac_f32_e32 v220, v57, v199
	ds_read_b128 v[180:183], v104 offset:1120
	s_waitcnt lgkmcnt(12)
	v_fmac_f32_e32 v220, v59, v201
	v_fmac_f32_e32 v220, v58, v200
	v_fmac_f32_e32 v220, v60, v202
	v_fmac_f32_e32 v220, v61, v203
	ds_read_b128 v[184:187], v104 offset:1136
	s_waitcnt lgkmcnt(11)
	v_fmac_f32_e32 v220, v63, v205
	v_fmac_f32_e32 v220, v62, v204
	v_fmac_f32_e32 v220, v64, v206
	v_fmac_f32_e32 v220, v65, v207
	ds_read_b128 v[188:191], v104 offset:1152
	s_waitcnt lgkmcnt(11)
	v_fmac_f32_e32 v220, v67, v209
	v_fmac_f32_e32 v220, v66, v208
	v_fmac_f32_e32 v220, v68, v210
	v_fmac_f32_e32 v220, v69, v211
	ds_read_b128 v[192:195], v104 offset:1168
	s_waitcnt lgkmcnt(11)
	v_fmac_f32_e32 v220, v71, v213
	v_fmac_f32_e32 v220, v70, v212
	v_fmac_f32_e32 v220, v72, v214
	v_fmac_f32_e32 v220, v73, v215
	ds_read_b128 v[196:199], v104 offset:1184
	s_waitcnt lgkmcnt(11)
	v_fmac_f32_e32 v220, v75, v217
	v_fmac_f32_e32 v220, v74, v216
	v_fmac_f32_e32 v220, v76, v218
	v_fmac_f32_e32 v220, v77, v219
	ds_read_b128 v[200:203], v104 offset:1200
	v_mul_f32_e32 v107, v78, v220
	v_mul_f32_e32 v6, v107, v107
	s_nop 1
	v_mov_b32_dpp v6, v6 quad_perm:[1,0,3,2] row_mask:0xf bank_mask:0xf bound_ctrl:1
	v_fmac_f32_e32 v6, v107, v107
	s_nop 1
	v_add_f32_dpp v6, v6, v6 quad_perm:[2,3,0,1] row_mask:0xf bank_mask:0xf bound_ctrl:1
	s_nop 1
	v_add_f32_dpp v6, v6, v6 row_half_mirror row_mask:0xf bank_mask:0xf bound_ctrl:1
	s_nop 1
	v_add_f32_dpp v6, v6, v6 row_mirror row_mask:0xf bank_mask:0xf bound_ctrl:1
	v_mov_b32_e32 v7, v6
	s_nop 1
	v_permlane16_swap_b32_e32 v6, v7
	v_add_f32_e32 v6, v6, v7
	v_mov_b32_e32 v7, v6
	s_nop 1
	v_permlane32_swap_b32_e32 v6, v7
	s_and_saveexec_b64 s[2:3], s[0:1]
	v_add_f32_e32 v6, v6, v7
	v_mov_b32_e32 v7, s17
	ds_write_b32 v7, v6 offset:48
	s_or_b64 exec, exec, s[2:3]
	v_mov_b32_e32 v104, s71
	s_waitcnt lgkmcnt(12)
; #define LAS __attribute__((address_space(3)))
; #define DPPADD_(v, ctrl) ((v) + __builtin_bit_cast(float, __builtin_amdgcn_update_dpp(0, __builtin_bit_cast(int, (v)), (ctrl), 0xf, 0xf, true)))
; __device__ __forceinline__ float wave_sum_valu(float v) {
;     v = DPPADD_(v, 0xB1); v = DPPADD_(v, 0x4E); v = DPPADD_(v, 0x141); v = DPPADD_(v, 0x140);
;     { auto r = __builtin_amdgcn_permlane16_swap(__float_as_uint(v), __float_as_uint(v), false, false); v = __uint_as_float(r[0]) + __uint_as_float(r[1]); }
;     { auto r = __builtin_amdgcn_permlane32_swap(__float_as_uint(v), __float_as_uint(v), false, false); v = __uint_as_float(r[0]) + __uint_as_float(r[1]); }
;     return v;
; __device__ __forceinline__ void pool_phase(const Params& a, LAS unsigned char* lds) {
;     ...
;         for (int tt = 0; tt < 32; ++tt) { const int tl = half * 32 + tt; float acc = 0.f;
; #pragma unroll
;             for (int c4 = 0; c4 < 16; ++c4) { const f32x4 pv = *(const LAS f32x4*)(ps + tl * 256 + g * 64 + c4 * 4);
;                 acc += pv[0] * wreg[4 * c4] + pv[1] * wreg[4 * c4 + 1] + pv[2] * wreg[4 * c4 + 2] + pv[3] * wreg[4 * c4 + 3]; }
;             o[tt] = acc * pscale; const float s = wave_sum_valu(o[tt] * o[tt]);
;             if (lane == 0) ssl[g * 64 + tl] = s; }
	v_mul_f32_e32 v220, v15, v157
	v_fmac_f32_e32 v220, v14, v156
	v_fmac_f32_e32 v220, v16, v158
	v_fmac_f32_e32 v220, v17, v159
	ds_read_b128 v[204:207], v104 offset:192
	s_waitcnt lgkmcnt(12)
	v_fmac_f32_e32 v220, v19, v161
	v_fmac_f32_e32 v220, v18, v160
	v_fmac_f32_e32 v220, v20, v162
	v_fmac_f32_e32 v220, v21, v163
	ds_read_b128 v[208:211], v104 offset:208
	s_waitcnt lgkmcnt(12)
	v_fmac_f32_e32 v220, v23, v165
	v_fmac_f32_e32 v220, v22, v164
	v_fmac_f32_e32 v220, v24, v166
	v_fmac_f32_e32 v220, v25, v167
	ds_read_b128 v[212:215], v104 offset:224
	s_waitcnt lgkmcnt(12)
	v_fmac_f32_e32 v220, v27, v169
	v_fmac_f32_e32 v220, v26, v168
	v_fmac_f32_e32 v220, v28, v170
	v_fmac_f32_e32 v220, v29, v171
	ds_read_b128 v[216:219], v104 offset:240
	s_waitcnt lgkmcnt(12)
	v_fmac_f32_e32 v220, v31, v173
	v_fmac_f32_e32 v220, v30, v172
	v_fmac_f32_e32 v220, v32, v174
	v_fmac_f32_e32 v220, v33, v175
	ds_read_b128 v[156:159], v104 offset:1024
	s_waitcnt lgkmcnt(12)
	v_fmac_f32_e32 v220, v35, v177
	v_fmac_f32_e32 v220, v34, v176
	v_fmac_f32_e32 v220, v36, v178
	v_fmac_f32_e32 v220, v37, v179
	ds_read_b128 v[160:163], v104 offset:1040
	s_waitcnt lgkmcnt(12)
	v_fmac_f32_e32 v220, v39, v181
	v_fmac_f32_e32 v220, v38, v180
	v_fmac_f32_e32 v220, v40, v182
	v_fmac_f32_e32 v220, v41, v183
	ds_read_b128 v[164:167], v104 offset:1056
	s_waitcnt lgkmcnt(12)
	v_fmac_f32_e32 v220, v43, v185
	v_fmac_f32_e32 v220, v42, v184
	v_fmac_f32_e32 v220, v44, v186
	v_fmac_f32_e32 v220, v45, v187
	ds_read_b128 v[168:171], v104 offset:1072
	s_waitcnt lgkmcnt(12)
	v_fmac_f32_e32 v220, v47, v189
	v_fmac_f32_e32 v220, v46, v188
	v_fmac_f32_e32 v220, v48, v190
	v_fmac_f32_e32 v220, v49, v191
	ds_read_b128 v[172:175], v104 offset:1088
	s_waitcnt lgkmcnt(12)
	v_fmac_f32_e32 v220, v51, v193
	v_fmac_f32_e32 v220, v50, v192
	v_fmac_f32_e32 v220, v52, v194
	v_fmac_f32_e32 v220, v53, v195
	ds_read_b128 v[176:179], v104 offset:1104
	s_waitcnt lgkmcnt(12)
	v_fmac_f32_e32 v220, v55, v197
	v_fmac_f32_e32 v220, v54, v196
	v_fmac_f32_e32 v220, v56, v198
	v_fmac_f32_e32 v220, v57, v199
	ds_read_b128 v[180:183], v104 offset:1120
	s_waitcnt lgkmcnt(12)
	v_fmac_f32_e32 v220, v59, v201
	v_fmac_f32_e32 v220, v58, v200
	v_fmac_f32_e32 v220, v60, v202
	v_fmac_f32_e32 v220, v61, v203
	ds_read_b128 v[184:187], v104 offset:1136
	s_waitcnt lgkmcnt(11)
	v_fmac_f32_e32 v220, v63, v205
	v_fmac_f32_e32 v220, v62, v204
	v_fmac_f32_e32 v220, v64, v206
	v_fmac_f32_e32 v220, v65, v207
	ds_read_b128 v[188:191], v104 offset:1152
	s_waitcnt lgkmcnt(11)
	v_fmac_f32_e32 v220, v67, v209
	v_fmac_f32_e32 v220, v66, v208
	v_fmac_f32_e32 v220, v68, v210
	v_fmac_f32_e32 v220, v69, v211
	ds_read_b128 v[192:195], v104 offset:1168
	s_waitcnt lgkmcnt(11)
	v_fmac_f32_e32 v220, v71, v213
	v_fmac_f32_e32 v220, v70, v212
	v_fmac_f32_e32 v220, v72, v214
	v_fmac_f32_e32 v220, v73, v215
	ds_read_b128 v[196:199], v104 offset:1184
	s_waitcnt lgkmcnt(11)
	v_fmac_f32_e32 v220, v75, v217
	v_fmac_f32_e32 v220, v74, v216
	v_fmac_f32_e32 v220, v76, v218
	v_fmac_f32_e32 v220, v77, v219
	ds_read_b128 v[200:203], v104 offset:1200
	v_mul_f32_e32 v106, v78, v220
	v_mul_f32_e32 v6, v106, v106
	s_nop 1
	v_mov_b32_dpp v6, v6 quad_perm:[1,0,3,2] row_mask:0xf bank_mask:0xf bound_ctrl:1
	v_fmac_f32_e32 v6, v106, v106
	s_nop 1
	v_add_f32_dpp v6, v6, v6 quad_perm:[2,3,0,1] row_mask:0xf bank_mask:0xf bound_ctrl:1
	s_nop 1
	v_add_f32_dpp v6, v6, v6 row_half_mirror row_mask:0xf bank_mask:0xf bound_ctrl:1
	s_nop 1
	v_add_f32_dpp v6, v6, v6 row_mirror row_mask:0xf bank_mask:0xf bound_ctrl:1
	v_mov_b32_e32 v7, v6
	s_nop 1
	v_permlane16_swap_b32_e32 v6, v7
	v_add_f32_e32 v6, v6, v7
	v_mov_b32_e32 v7, v6
	s_nop 1
	v_permlane32_swap_b32_e32 v6, v7
	s_and_saveexec_b64 s[2:3], s[0:1]
	v_add_f32_e32 v6, v6, v7
	v_mov_b32_e32 v7, s17
	ds_write_b32 v7, v6 offset:52
	s_or_b64 exec, exec, s[2:3]
	v_mov_b32_e32 v104, s72
	s_waitcnt lgkmcnt(12)
	v_mul_f32_e32 v220, v15, v157
	v_fmac_f32_e32 v220, v14, v156
	v_fmac_f32_e32 v220, v16, v158
	v_fmac_f32_e32 v220, v17, v159
	ds_read_b128 v[204:207], v104 offset:192
	s_waitcnt lgkmcnt(12)
	v_fmac_f32_e32 v220, v19, v161
	v_fmac_f32_e32 v220, v18, v160
	v_fmac_f32_e32 v220, v20, v162
	v_fmac_f32_e32 v220, v21, v163
	ds_read_b128 v[208:211], v104 offset:208
	s_waitcnt lgkmcnt(12)
	v_fmac_f32_e32 v220, v23, v165
	v_fmac_f32_e32 v220, v22, v164
	v_fmac_f32_e32 v220, v24, v166
	v_fmac_f32_e32 v220, v25, v167
	ds_read_b128 v[212:215], v104 offset:224
	s_waitcnt lgkmcnt(12)
	v_fmac_f32_e32 v220, v27, v169
	v_fmac_f32_e32 v220, v26, v168
	v_fmac_f32_e32 v220, v28, v170
	v_fmac_f32_e32 v220, v29, v171
	ds_read_b128 v[216:219], v104 offset:240
	s_waitcnt lgkmcnt(12)
	v_fmac_f32_e32 v220, v31, v173
	v_fmac_f32_e32 v220, v30, v172
	v_fmac_f32_e32 v220, v32, v174
	v_fmac_f32_e32 v220, v33, v175
	ds_read_b128 v[156:159], v104 offset:1024
	s_waitcnt lgkmcnt(12)
	v_fmac_f32_e32 v220, v35, v177
	v_fmac_f32_e32 v220, v34, v176
	v_fmac_f32_e32 v220, v36, v178
	v_fmac_f32_e32 v220, v37, v179
	ds_read_b128 v[160:163], v104 offset:1040
	s_waitcnt lgkmcnt(12)
	v_fmac_f32_e32 v220, v39, v181
	v_fmac_f32_e32 v220, v38, v180
	v_fmac_f32_e32 v220, v40, v182
	v_fmac_f32_e32 v220, v41, v183
	ds_read_b128 v[164:167], v104 offset:1056
	s_waitcnt lgkmcnt(12)
	v_fmac_f32_e32 v220, v43, v185
	v_fmac_f32_e32 v220, v42, v184
	v_fmac_f32_e32 v220, v44, v186
	v_fmac_f32_e32 v220, v45, v187
	ds_read_b128 v[168:171], v104 offset:1072
	s_waitcnt lgkmcnt(12)
	v_fmac_f32_e32 v220, v47, v189
	v_fmac_f32_e32 v220, v46, v188
	v_fmac_f32_e32 v220, v48, v190
	v_fmac_f32_e32 v220, v49, v191
	ds_read_b128 v[172:175], v104 offset:1088
	s_waitcnt lgkmcnt(12)
; #define LAS __attribute__((address_space(3)))
; #define DPPADD_(v, ctrl) ((v) + __builtin_bit_cast(float, __builtin_amdgcn_update_dpp(0, __builtin_bit_cast(int, (v)), (ctrl), 0xf, 0xf, true)))
; __device__ __forceinline__ float wave_sum_valu(float v) {
;     v = DPPADD_(v, 0xB1); v = DPPADD_(v, 0x4E); v = DPPADD_(v, 0x141); v = DPPADD_(v, 0x140);
;     { auto r = __builtin_amdgcn_permlane16_swap(__float_as_uint(v), __float_as_uint(v), false, false); v = __uint_as_float(r[0]) + __uint_as_float(r[1]); }
;     { auto r = __builtin_amdgcn_permlane32_swap(__float_as_uint(v), __float_as_uint(v), false, false); v = __uint_as_float(r[0]) + __uint_as_float(r[1]); }
;     return v;
; __device__ __forceinline__ void pool_phase(const Params& a, LAS unsigned char* lds) {
;     ...
;         for (int tt = 0; tt < 32; ++tt) { const int tl = half * 32 + tt; float acc = 0.f;
; #pragma unroll
;             for (int c4 = 0; c4 < 16; ++c4) { const f32x4 pv = *(const LAS f32x4*)(ps + tl * 256 + g * 64 + c4 * 4);
;                 acc += pv[0] * wreg[4 * c4] + pv[1] * wreg[4 * c4 + 1] + pv[2] * wreg[4 * c4 + 2] + pv[3] * wreg[4 * c4 + 3]; }
;             o[tt] = acc * pscale; const float s = wave_sum_valu(o[tt] * o[tt]);
;             if (lane == 0) ssl[g * 64 + tl] = s; }
	v_fmac_f32_e32 v220, v51, v193
	v_fmac_f32_e32 v220, v50, v192
	v_fmac_f32_e32 v220, v52, v194
	v_fmac_f32_e32 v220, v53, v195
	ds_read_b128 v[176:179], v104 offset:1104
	s_waitcnt lgkmcnt(12)
	v_fmac_f32_e32 v220, v55, v197
	v_fmac_f32_e32 v220, v54, v196
	v_fmac_f32_e32 v220, v56, v198
	v_fmac_f32_e32 v220, v57, v199
	ds_read_b128 v[180:183], v104 offset:1120
	s_waitcnt lgkmcnt(12)
	v_fmac_f32_e32 v220, v59, v201
	v_fmac_f32_e32 v220, v58, v200
	v_fmac_f32_e32 v220, v60, v202
	v_fmac_f32_e32 v220, v61, v203
	ds_read_b128 v[184:187], v104 offset:1136
	s_waitcnt lgkmcnt(11)
	v_fmac_f32_e32 v220, v63, v205
	v_fmac_f32_e32 v220, v62, v204
	v_fmac_f32_e32 v220, v64, v206
	v_fmac_f32_e32 v220, v65, v207
	ds_read_b128 v[188:191], v104 offset:1152
	s_waitcnt lgkmcnt(11)
	v_fmac_f32_e32 v220, v67, v209
	v_fmac_f32_e32 v220, v66, v208
	v_fmac_f32_e32 v220, v68, v210
	v_fmac_f32_e32 v220, v69, v211
	ds_read_b128 v[192:195], v104 offset:1168
	s_waitcnt lgkmcnt(11)
	v_fmac_f32_e32 v220, v71, v213
	v_fmac_f32_e32 v220, v70, v212
	v_fmac_f32_e32 v220, v72, v214
	v_fmac_f32_e32 v220, v73, v215
	ds_read_b128 v[196:199], v104 offset:1184
	s_waitcnt lgkmcnt(11)
	v_fmac_f32_e32 v220, v75, v217
	v_fmac_f32_e32 v220, v74, v216
	v_fmac_f32_e32 v220, v76, v218
	v_fmac_f32_e32 v220, v77, v219
	ds_read_b128 v[200:203], v104 offset:1200
	v_mul_f32_e32 v105, v78, v220
	v_mul_f32_e32 v6, v105, v105
	s_nop 1
	v_mov_b32_dpp v6, v6 quad_perm:[1,0,3,2] row_mask:0xf bank_mask:0xf bound_ctrl:1
	v_fmac_f32_e32 v6, v105, v105
	s_nop 1
	v_add_f32_dpp v6, v6, v6 quad_perm:[2,3,0,1] row_mask:0xf bank_mask:0xf bound_ctrl:1
	s_nop 1
	v_add_f32_dpp v6, v6, v6 row_half_mirror row_mask:0xf bank_mask:0xf bound_ctrl:1
	s_nop 1
	v_add_f32_dpp v6, v6, v6 row_mirror row_mask:0xf bank_mask:0xf bound_ctrl:1
	v_mov_b32_e32 v7, v6
	s_nop 1
	v_permlane16_swap_b32_e32 v6, v7
	v_add_f32_e32 v6, v6, v7
	v_mov_b32_e32 v7, v6
	s_nop 1
	v_permlane32_swap_b32_e32 v6, v7
	s_and_saveexec_b64 s[2:3], s[0:1]
	v_add_f32_e32 v6, v6, v7
	v_mov_b32_e32 v7, s17
	ds_write_b32 v7, v6 offset:56
	s_or_b64 exec, exec, s[2:3]
	v_mov_b32_e32 v104, s73
	s_waitcnt lgkmcnt(12)
	v_mul_f32_e32 v220, v15, v157
	v_fmac_f32_e32 v220, v14, v156
	v_fmac_f32_e32 v220, v16, v158
	v_fmac_f32_e32 v220, v17, v159
	ds_read_b128 v[204:207], v104 offset:192
	s_waitcnt lgkmcnt(12)
	v_fmac_f32_e32 v220, v19, v161
	v_fmac_f32_e32 v220, v18, v160
	v_fmac_f32_e32 v220, v20, v162
	v_fmac_f32_e32 v220, v21, v163
	ds_read_b128 v[208:211], v104 offset:208
	s_waitcnt lgkmcnt(12)
	v_fmac_f32_e32 v220, v23, v165
	v_fmac_f32_e32 v220, v22, v164
	v_fmac_f32_e32 v220, v24, v166
	v_fmac_f32_e32 v220, v25, v167
	ds_read_b128 v[212:215], v104 offset:224
	s_waitcnt lgkmcnt(12)
	v_fmac_f32_e32 v220, v27, v169
	v_fmac_f32_e32 v220, v26, v168
	v_fmac_f32_e32 v220, v28, v170
	v_fmac_f32_e32 v220, v29, v171
	ds_read_b128 v[216:219], v104 offset:240
	s_waitcnt lgkmcnt(12)
	v_fmac_f32_e32 v220, v31, v173
	v_fmac_f32_e32 v220, v30, v172
	v_fmac_f32_e32 v220, v32, v174
	v_fmac_f32_e32 v220, v33, v175
	ds_read_b128 v[156:159], v104 offset:1024
	s_waitcnt lgkmcnt(12)
	v_fmac_f32_e32 v220, v35, v177
	v_fmac_f32_e32 v220, v34, v176
	v_fmac_f32_e32 v220, v36, v178
	v_fmac_f32_e32 v220, v37, v179
	ds_read_b128 v[160:163], v104 offset:1040
	s_waitcnt lgkmcnt(12)
	v_fmac_f32_e32 v220, v39, v181
	v_fmac_f32_e32 v220, v38, v180
	v_fmac_f32_e32 v220, v40, v182
	v_fmac_f32_e32 v220, v41, v183
	ds_read_b128 v[164:167], v104 offset:1056
	s_waitcnt lgkmcnt(12)
	v_fmac_f32_e32 v220, v43, v185
	v_fmac_f32_e32 v220, v42, v184
	v_fmac_f32_e32 v220, v44, v186
	v_fmac_f32_e32 v220, v45, v187
	ds_read_b128 v[168:171], v104 offset:1072
	s_waitcnt lgkmcnt(12)
	v_fmac_f32_e32 v220, v47, v189
	v_fmac_f32_e32 v220, v46, v188
	v_fmac_f32_e32 v220, v48, v190
	v_fmac_f32_e32 v220, v49, v191
	ds_read_b128 v[172:175], v104 offset:1088
	s_waitcnt lgkmcnt(12)
	v_fmac_f32_e32 v220, v51, v193
	v_fmac_f32_e32 v220, v50, v192
	v_fmac_f32_e32 v220, v52, v194
	v_fmac_f32_e32 v220, v53, v195
	ds_read_b128 v[176:179], v104 offset:1104
	s_waitcnt lgkmcnt(12)
	v_fmac_f32_e32 v220, v55, v197
	v_fmac_f32_e32 v220, v54, v196
	v_fmac_f32_e32 v220, v56, v198
	v_fmac_f32_e32 v220, v57, v199
	ds_read_b128 v[180:183], v104 offset:1120
	s_waitcnt lgkmcnt(12)
	v_fmac_f32_e32 v220, v59, v201
	v_fmac_f32_e32 v220, v58, v200
	v_fmac_f32_e32 v220, v60, v202
	v_fmac_f32_e32 v220, v61, v203
	ds_read_b128 v[184:187], v104 offset:1136
	s_waitcnt lgkmcnt(11)
	v_fmac_f32_e32 v220, v63, v205
	v_fmac_f32_e32 v220, v62, v204
	v_fmac_f32_e32 v220, v64, v206
	v_fmac_f32_e32 v220, v65, v207
	ds_read_b128 v[188:191], v104 offset:1152
	s_waitcnt lgkmcnt(11)
	v_fmac_f32_e32 v220, v67, v209
	v_fmac_f32_e32 v220, v66, v208
	v_fmac_f32_e32 v220, v68, v210
	v_fmac_f32_e32 v220, v69, v211
	ds_read_b128 v[192:195], v104 offset:1168
	s_waitcnt lgkmcnt(11)
	v_fmac_f32_e32 v220, v71, v213
	v_fmac_f32_e32 v220, v70, v212
	v_fmac_f32_e32 v220, v72, v214
	v_fmac_f32_e32 v220, v73, v215
	ds_read_b128 v[196:199], v104 offset:1184
	s_waitcnt lgkmcnt(11)
	v_fmac_f32_e32 v220, v75, v217
	v_fmac_f32_e32 v220, v74, v216
	v_fmac_f32_e32 v220, v76, v218
	v_fmac_f32_e32 v220, v77, v219
	ds_read_b128 v[200:203], v104 offset:1200
	v_mul_f32_e32 v104, v78, v220
	v_mul_f32_e32 v6, v104, v104
	s_nop 1
	v_mov_b32_dpp v6, v6 quad_perm:[1,0,3,2] row_mask:0xf bank_mask:0xf bound_ctrl:1
	v_fmac_f32_e32 v6, v104, v104
	s_nop 1
	v_add_f32_dpp v6, v6, v6 quad_perm:[2,3,0,1] row_mask:0xf bank_mask:0xf bound_ctrl:1
	s_nop 1
	v_add_f32_dpp v6, v6, v6 row_half_mirror row_mask:0xf bank_mask:0xf bound_ctrl:1
	s_nop 1
	v_add_f32_dpp v6, v6, v6 row_mirror row_mask:0xf bank_mask:0xf bound_ctrl:1
	v_mov_b32_e32 v7, v6
	s_nop 1
	v_permlane16_swap_b32_e32 v6, v7
	v_add_f32_e32 v6, v6, v7
	v_mov_b32_e32 v7, v6
	s_nop 1
	v_permlane32_swap_b32_e32 v6, v7
	s_and_saveexec_b64 s[2:3], s[0:1]
	v_add_f32_e32 v6, v6, v7
	v_mov_b32_e32 v7, s17
	ds_write_b32 v7, v6 offset:60
	s_or_b64 exec, exec, s[2:3]
	v_mov_b32_e32 v120, s74
	s_waitcnt lgkmcnt(12)
; #define LAS __attribute__((address_space(3)))
; #define DPPADD_(v, ctrl) ((v) + __builtin_bit_cast(float, __builtin_amdgcn_update_dpp(0, __builtin_bit_cast(int, (v)), (ctrl), 0xf, 0xf, true)))
; __device__ __forceinline__ float wave_sum_valu(float v) {
;     v = DPPADD_(v, 0xB1); v = DPPADD_(v, 0x4E); v = DPPADD_(v, 0x141); v = DPPADD_(v, 0x140);
;     { auto r = __builtin_amdgcn_permlane16_swap(__float_as_uint(v), __float_as_uint(v), false, false); v = __uint_as_float(r[0]) + __uint_as_float(r[1]); }
;     { auto r = __builtin_amdgcn_permlane32_swap(__float_as_uint(v), __float_as_uint(v), false, false); v = __uint_as_float(r[0]) + __uint_as_float(r[1]); }
;     return v;
; __device__ __forceinline__ void pool_phase(const Params& a, LAS unsigned char* lds) {
;     ...
;         for (int tt = 0; tt < 32; ++tt) { const int tl = half * 32 + tt; float acc = 0.f;
; #pragma unroll
;             for (int c4 = 0; c4 < 16; ++c4) { const f32x4 pv = *(const LAS f32x4*)(ps + tl * 256 + g * 64 + c4 * 4);
;                 acc += pv[0] * wreg[4 * c4] + pv[1] * wreg[4 * c4 + 1] + pv[2] * wreg[4 * c4 + 2] + pv[3] * wreg[4 * c4 + 3]; }
;             o[tt] = acc * pscale; const float s = wave_sum_valu(o[tt] * o[tt]);
;             if (lane == 0) ssl[g * 64 + tl] = s; }
	v_mul_f32_e32 v220, v15, v157
	v_fmac_f32_e32 v220, v14, v156
	v_fmac_f32_e32 v220, v16, v158
	v_fmac_f32_e32 v220, v17, v159
	ds_read_b128 v[204:207], v120 offset:192
	s_waitcnt lgkmcnt(12)
	v_fmac_f32_e32 v220, v19, v161
	v_fmac_f32_e32 v220, v18, v160
	v_fmac_f32_e32 v220, v20, v162
	v_fmac_f32_e32 v220, v21, v163
	ds_read_b128 v[208:211], v120 offset:208
	s_waitcnt lgkmcnt(12)
	v_fmac_f32_e32 v220, v23, v165
	v_fmac_f32_e32 v220, v22, v164
	v_fmac_f32_e32 v220, v24, v166
	v_fmac_f32_e32 v220, v25, v167
	ds_read_b128 v[212:215], v120 offset:224
	s_waitcnt lgkmcnt(12)
	v_fmac_f32_e32 v220, v27, v169
	v_fmac_f32_e32 v220, v26, v168
	v_fmac_f32_e32 v220, v28, v170
	v_fmac_f32_e32 v220, v29, v171
	ds_read_b128 v[216:219], v120 offset:240
	s_waitcnt lgkmcnt(12)
	v_fmac_f32_e32 v220, v31, v173
	v_fmac_f32_e32 v220, v30, v172
	v_fmac_f32_e32 v220, v32, v174
	v_fmac_f32_e32 v220, v33, v175
	ds_read_b128 v[156:159], v120 offset:1024
	s_waitcnt lgkmcnt(12)
	v_fmac_f32_e32 v220, v35, v177
	v_fmac_f32_e32 v220, v34, v176
	v_fmac_f32_e32 v220, v36, v178
	v_fmac_f32_e32 v220, v37, v179
	ds_read_b128 v[160:163], v120 offset:1040
	s_waitcnt lgkmcnt(12)
	v_fmac_f32_e32 v220, v39, v181
	v_fmac_f32_e32 v220, v38, v180
	v_fmac_f32_e32 v220, v40, v182
	v_fmac_f32_e32 v220, v41, v183
	ds_read_b128 v[164:167], v120 offset:1056
	s_waitcnt lgkmcnt(12)
	v_fmac_f32_e32 v220, v43, v185
	v_fmac_f32_e32 v220, v42, v184
	v_fmac_f32_e32 v220, v44, v186
	v_fmac_f32_e32 v220, v45, v187
	ds_read_b128 v[168:171], v120 offset:1072
	s_waitcnt lgkmcnt(12)
	v_fmac_f32_e32 v220, v47, v189
	v_fmac_f32_e32 v220, v46, v188
	v_fmac_f32_e32 v220, v48, v190
	v_fmac_f32_e32 v220, v49, v191
	ds_read_b128 v[172:175], v120 offset:1088
	s_waitcnt lgkmcnt(12)
	v_fmac_f32_e32 v220, v51, v193
	v_fmac_f32_e32 v220, v50, v192
	v_fmac_f32_e32 v220, v52, v194
	v_fmac_f32_e32 v220, v53, v195
	ds_read_b128 v[176:179], v120 offset:1104
	s_waitcnt lgkmcnt(12)
	v_fmac_f32_e32 v220, v55, v197
	v_fmac_f32_e32 v220, v54, v196
	v_fmac_f32_e32 v220, v56, v198
	v_fmac_f32_e32 v220, v57, v199
	ds_read_b128 v[180:183], v120 offset:1120
	s_waitcnt lgkmcnt(12)
	v_fmac_f32_e32 v220, v59, v201
	v_fmac_f32_e32 v220, v58, v200
	v_fmac_f32_e32 v220, v60, v202
	v_fmac_f32_e32 v220, v61, v203
	ds_read_b128 v[184:187], v120 offset:1136
	s_waitcnt lgkmcnt(11)
	v_fmac_f32_e32 v220, v63, v205
	v_fmac_f32_e32 v220, v62, v204
	v_fmac_f32_e32 v220, v64, v206
	v_fmac_f32_e32 v220, v65, v207
	ds_read_b128 v[188:191], v120 offset:1152
	s_waitcnt lgkmcnt(11)
	v_fmac_f32_e32 v220, v67, v209
	v_fmac_f32_e32 v220, v66, v208
	v_fmac_f32_e32 v220, v68, v210
	v_fmac_f32_e32 v220, v69, v211
	ds_read_b128 v[192:195], v120 offset:1168
	s_waitcnt lgkmcnt(11)
	v_fmac_f32_e32 v220, v71, v213
	v_fmac_f32_e32 v220, v70, v212
	v_fmac_f32_e32 v220, v72, v214
	v_fmac_f32_e32 v220, v73, v215
	ds_read_b128 v[196:199], v120 offset:1184
	s_waitcnt lgkmcnt(11)
	v_fmac_f32_e32 v220, v75, v217
	v_fmac_f32_e32 v220, v74, v216
	v_fmac_f32_e32 v220, v76, v218
	v_fmac_f32_e32 v220, v77, v219
	ds_read_b128 v[200:203], v120 offset:1200
	v_mul_f32_e32 v103, v78, v220
	v_mul_f32_e32 v6, v103, v103
	s_nop 1
	v_mov_b32_dpp v6, v6 quad_perm:[1,0,3,2] row_mask:0xf bank_mask:0xf bound_ctrl:1
	v_fmac_f32_e32 v6, v103, v103
	s_nop 1
	v_add_f32_dpp v6, v6, v6 quad_perm:[2,3,0,1] row_mask:0xf bank_mask:0xf bound_ctrl:1
	s_nop 1
	v_add_f32_dpp v6, v6, v6 row_half_mirror row_mask:0xf bank_mask:0xf bound_ctrl:1
	s_nop 1
	v_add_f32_dpp v6, v6, v6 row_mirror row_mask:0xf bank_mask:0xf bound_ctrl:1
	v_mov_b32_e32 v7, v6
	s_nop 1
	v_permlane16_swap_b32_e32 v6, v7
	v_add_f32_e32 v6, v6, v7
	v_mov_b32_e32 v7, v6
	s_nop 1
	v_permlane32_swap_b32_e32 v6, v7
	s_and_saveexec_b64 s[2:3], s[0:1]
	v_add_f32_e32 v6, v6, v7
	v_mov_b32_e32 v7, s17
	ds_write_b32 v7, v6 offset:64
	s_or_b64 exec, exec, s[2:3]
	v_mov_b32_e32 v100, s75
	s_waitcnt lgkmcnt(12)
	v_mul_f32_e32 v220, v15, v157
	v_fmac_f32_e32 v220, v14, v156
	v_fmac_f32_e32 v220, v16, v158
	v_fmac_f32_e32 v220, v17, v159
	ds_read_b128 v[204:207], v100 offset:192
	s_waitcnt lgkmcnt(12)
	v_fmac_f32_e32 v220, v19, v161
	v_fmac_f32_e32 v220, v18, v160
	v_fmac_f32_e32 v220, v20, v162
	v_fmac_f32_e32 v220, v21, v163
	ds_read_b128 v[208:211], v100 offset:208
	s_waitcnt lgkmcnt(12)
	v_fmac_f32_e32 v220, v23, v165
	v_fmac_f32_e32 v220, v22, v164
	v_fmac_f32_e32 v220, v24, v166
	v_fmac_f32_e32 v220, v25, v167
	ds_read_b128 v[212:215], v100 offset:224
	s_waitcnt lgkmcnt(12)
	v_fmac_f32_e32 v220, v27, v169
	v_fmac_f32_e32 v220, v26, v168
	v_fmac_f32_e32 v220, v28, v170
	v_fmac_f32_e32 v220, v29, v171
	ds_read_b128 v[216:219], v100 offset:240
	s_waitcnt lgkmcnt(12)
	v_fmac_f32_e32 v220, v31, v173
	v_fmac_f32_e32 v220, v30, v172
	v_fmac_f32_e32 v220, v32, v174
	v_fmac_f32_e32 v220, v33, v175
	ds_read_b128 v[156:159], v100 offset:1024
	s_waitcnt lgkmcnt(12)
	v_fmac_f32_e32 v220, v35, v177
	v_fmac_f32_e32 v220, v34, v176
	v_fmac_f32_e32 v220, v36, v178
	v_fmac_f32_e32 v220, v37, v179
	ds_read_b128 v[160:163], v100 offset:1040
	s_waitcnt lgkmcnt(12)
	v_fmac_f32_e32 v220, v39, v181
	v_fmac_f32_e32 v220, v38, v180
	v_fmac_f32_e32 v220, v40, v182
	v_fmac_f32_e32 v220, v41, v183
	ds_read_b128 v[164:167], v100 offset:1056
	s_waitcnt lgkmcnt(12)
	v_fmac_f32_e32 v220, v43, v185
	v_fmac_f32_e32 v220, v42, v184
	v_fmac_f32_e32 v220, v44, v186
	v_fmac_f32_e32 v220, v45, v187
	ds_read_b128 v[168:171], v100 offset:1072
	s_waitcnt lgkmcnt(12)
	v_fmac_f32_e32 v220, v47, v189
	v_fmac_f32_e32 v220, v46, v188
	v_fmac_f32_e32 v220, v48, v190
	v_fmac_f32_e32 v220, v49, v191
	ds_read_b128 v[172:175], v100 offset:1088
	s_waitcnt lgkmcnt(12)
; #define LAS __attribute__((address_space(3)))
; #define DPPADD_(v, ctrl) ((v) + __builtin_bit_cast(float, __builtin_amdgcn_update_dpp(0, __builtin_bit_cast(int, (v)), (ctrl), 0xf, 0xf, true)))
; __device__ __forceinline__ float wave_sum_valu(float v) {
;     v = DPPADD_(v, 0xB1); v = DPPADD_(v, 0x4E); v = DPPADD_(v, 0x141); v = DPPADD_(v, 0x140);
;     { auto r = __builtin_amdgcn_permlane16_swap(__float_as_uint(v), __float_as_uint(v), false, false); v = __uint_as_float(r[0]) + __uint_as_float(r[1]); }
;     { auto r = __builtin_amdgcn_permlane32_swap(__float_as_uint(v), __float_as_uint(v), false, false); v = __uint_as_float(r[0]) + __uint_as_float(r[1]); }
;     return v;
; __device__ __forceinline__ void pool_phase(const Params& a, LAS unsigned char* lds) {
;     ...
;         for (int tt = 0; tt < 32; ++tt) { const int tl = half * 32 + tt; float acc = 0.f;
; #pragma unroll
;             for (int c4 = 0; c4 < 16; ++c4) { const f32x4 pv = *(const LAS f32x4*)(ps + tl * 256 + g * 64 + c4 * 4);
;                 acc += pv[0] * wreg[4 * c4] + pv[1] * wreg[4 * c4 + 1] + pv[2] * wreg[4 * c4 + 2] + pv[3] * wreg[4 * c4 + 3]; }
;             o[tt] = acc * pscale; const float s = wave_sum_valu(o[tt] * o[tt]);
;             if (lane == 0) ssl[g * 64 + tl] = s; }
	v_fmac_f32_e32 v220, v51, v193
	v_fmac_f32_e32 v220, v50, v192
	v_fmac_f32_e32 v220, v52, v194
	v_fmac_f32_e32 v220, v53, v195
	ds_read_b128 v[176:179], v100 offset:1104
	s_waitcnt lgkmcnt(12)
	v_fmac_f32_e32 v220, v55, v197
	v_fmac_f32_e32 v220, v54, v196
	v_fmac_f32_e32 v220, v56, v198
	v_fmac_f32_e32 v220, v57, v199
	ds_read_b128 v[180:183], v100 offset:1120
	s_waitcnt lgkmcnt(12)
	v_fmac_f32_e32 v220, v59, v201
	v_fmac_f32_e32 v220, v58, v200
	v_fmac_f32_e32 v220, v60, v202
	v_fmac_f32_e32 v220, v61, v203
	ds_read_b128 v[184:187], v100 offset:1136
	s_waitcnt lgkmcnt(11)
	v_fmac_f32_e32 v220, v63, v205
	v_fmac_f32_e32 v220, v62, v204
	v_fmac_f32_e32 v220, v64, v206
	v_fmac_f32_e32 v220, v65, v207
	ds_read_b128 v[188:191], v100 offset:1152
	s_waitcnt lgkmcnt(11)
	v_fmac_f32_e32 v220, v67, v209
	v_fmac_f32_e32 v220, v66, v208
	v_fmac_f32_e32 v220, v68, v210
	v_fmac_f32_e32 v220, v69, v211
	ds_read_b128 v[192:195], v100 offset:1168
	s_waitcnt lgkmcnt(11)
	v_fmac_f32_e32 v220, v71, v213
	v_fmac_f32_e32 v220, v70, v212
	v_fmac_f32_e32 v220, v72, v214
	v_fmac_f32_e32 v220, v73, v215
	ds_read_b128 v[196:199], v100 offset:1184
	s_waitcnt lgkmcnt(11)
	v_fmac_f32_e32 v220, v75, v217
	v_fmac_f32_e32 v220, v74, v216
	v_fmac_f32_e32 v220, v76, v218
	v_fmac_f32_e32 v220, v77, v219
	ds_read_b128 v[200:203], v100 offset:1200
	v_mul_f32_e32 v102, v78, v220
	v_mul_f32_e32 v6, v102, v102
	s_nop 1
	v_mov_b32_dpp v6, v6 quad_perm:[1,0,3,2] row_mask:0xf bank_mask:0xf bound_ctrl:1
	v_fmac_f32_e32 v6, v102, v102
	s_nop 1
	v_add_f32_dpp v6, v6, v6 quad_perm:[2,3,0,1] row_mask:0xf bank_mask:0xf bound_ctrl:1
	s_nop 1
	v_add_f32_dpp v6, v6, v6 row_half_mirror row_mask:0xf bank_mask:0xf bound_ctrl:1
	s_nop 1
	v_add_f32_dpp v6, v6, v6 row_mirror row_mask:0xf bank_mask:0xf bound_ctrl:1
	v_mov_b32_e32 v7, v6
	s_nop 1
	v_permlane16_swap_b32_e32 v6, v7
	v_add_f32_e32 v6, v6, v7
	v_mov_b32_e32 v7, v6
	s_nop 1
	v_permlane32_swap_b32_e32 v6, v7
	s_and_saveexec_b64 s[2:3], s[0:1]
	v_add_f32_e32 v6, v6, v7
	v_mov_b32_e32 v7, s17
	ds_write_b32 v7, v6 offset:68
	s_or_b64 exec, exec, s[2:3]
	v_mov_b32_e32 v100, s76
	s_waitcnt lgkmcnt(12)
	v_mul_f32_e32 v220, v15, v157
	v_fmac_f32_e32 v220, v14, v156
	v_fmac_f32_e32 v220, v16, v158
	v_fmac_f32_e32 v220, v17, v159
	ds_read_b128 v[204:207], v100 offset:192
	s_waitcnt lgkmcnt(12)
	v_fmac_f32_e32 v220, v19, v161
	v_fmac_f32_e32 v220, v18, v160
	v_fmac_f32_e32 v220, v20, v162
	v_fmac_f32_e32 v220, v21, v163
	ds_read_b128 v[208:211], v100 offset:208
	s_waitcnt lgkmcnt(12)
	v_fmac_f32_e32 v220, v23, v165
	v_fmac_f32_e32 v220, v22, v164
	v_fmac_f32_e32 v220, v24, v166
	v_fmac_f32_e32 v220, v25, v167
	ds_read_b128 v[212:215], v100 offset:224
	s_waitcnt lgkmcnt(12)
	v_fmac_f32_e32 v220, v27, v169
	v_fmac_f32_e32 v220, v26, v168
	v_fmac_f32_e32 v220, v28, v170
	v_fmac_f32_e32 v220, v29, v171
	ds_read_b128 v[216:219], v100 offset:240
	s_waitcnt lgkmcnt(12)
	v_fmac_f32_e32 v220, v31, v173
	v_fmac_f32_e32 v220, v30, v172
	v_fmac_f32_e32 v220, v32, v174
	v_fmac_f32_e32 v220, v33, v175
	ds_read_b128 v[156:159], v100 offset:1024
	s_waitcnt lgkmcnt(12)
	v_fmac_f32_e32 v220, v35, v177
	v_fmac_f32_e32 v220, v34, v176
	v_fmac_f32_e32 v220, v36, v178
	v_fmac_f32_e32 v220, v37, v179
	ds_read_b128 v[160:163], v100 offset:1040
	s_waitcnt lgkmcnt(12)
	v_fmac_f32_e32 v220, v39, v181
	v_fmac_f32_e32 v220, v38, v180
	v_fmac_f32_e32 v220, v40, v182
	v_fmac_f32_e32 v220, v41, v183
	ds_read_b128 v[164:167], v100 offset:1056
	s_waitcnt lgkmcnt(12)
	v_fmac_f32_e32 v220, v43, v185
	v_fmac_f32_e32 v220, v42, v184
	v_fmac_f32_e32 v220, v44, v186
	v_fmac_f32_e32 v220, v45, v187
	ds_read_b128 v[168:171], v100 offset:1072
	s_waitcnt lgkmcnt(12)
	v_fmac_f32_e32 v220, v47, v189
	v_fmac_f32_e32 v220, v46, v188
	v_fmac_f32_e32 v220, v48, v190
	v_fmac_f32_e32 v220, v49, v191
	ds_read_b128 v[172:175], v100 offset:1088
	s_waitcnt lgkmcnt(12)
	v_fmac_f32_e32 v220, v51, v193
	v_fmac_f32_e32 v220, v50, v192
	v_fmac_f32_e32 v220, v52, v194
	v_fmac_f32_e32 v220, v53, v195
	ds_read_b128 v[176:179], v100 offset:1104
	s_waitcnt lgkmcnt(12)
	v_fmac_f32_e32 v220, v55, v197
	v_fmac_f32_e32 v220, v54, v196
	v_fmac_f32_e32 v220, v56, v198
	v_fmac_f32_e32 v220, v57, v199
	ds_read_b128 v[180:183], v100 offset:1120
	s_waitcnt lgkmcnt(12)
	v_fmac_f32_e32 v220, v59, v201
	v_fmac_f32_e32 v220, v58, v200
	v_fmac_f32_e32 v220, v60, v202
	v_fmac_f32_e32 v220, v61, v203
	ds_read_b128 v[184:187], v100 offset:1136
	s_waitcnt lgkmcnt(11)
	v_fmac_f32_e32 v220, v63, v205
	v_fmac_f32_e32 v220, v62, v204
	v_fmac_f32_e32 v220, v64, v206
	v_fmac_f32_e32 v220, v65, v207
	ds_read_b128 v[188:191], v100 offset:1152
	s_waitcnt lgkmcnt(11)
	v_fmac_f32_e32 v220, v67, v209
	v_fmac_f32_e32 v220, v66, v208
	v_fmac_f32_e32 v220, v68, v210
	v_fmac_f32_e32 v220, v69, v211
	ds_read_b128 v[192:195], v100 offset:1168
	s_waitcnt lgkmcnt(11)
	v_fmac_f32_e32 v220, v71, v213
	v_fmac_f32_e32 v220, v70, v212
	v_fmac_f32_e32 v220, v72, v214
	v_fmac_f32_e32 v220, v73, v215
	ds_read_b128 v[196:199], v100 offset:1184
	s_waitcnt lgkmcnt(11)
	v_fmac_f32_e32 v220, v75, v217
	v_fmac_f32_e32 v220, v74, v216
	v_fmac_f32_e32 v220, v76, v218
	v_fmac_f32_e32 v220, v77, v219
	ds_read_b128 v[200:203], v100 offset:1200
	v_mul_f32_e32 v101, v78, v220
	v_mul_f32_e32 v6, v101, v101
	s_nop 1
	v_mov_b32_dpp v6, v6 quad_perm:[1,0,3,2] row_mask:0xf bank_mask:0xf bound_ctrl:1
	v_fmac_f32_e32 v6, v101, v101
	s_nop 1
	v_add_f32_dpp v6, v6, v6 quad_perm:[2,3,0,1] row_mask:0xf bank_mask:0xf bound_ctrl:1
	s_nop 1
	v_add_f32_dpp v6, v6, v6 row_half_mirror row_mask:0xf bank_mask:0xf bound_ctrl:1
	s_nop 1
	v_add_f32_dpp v6, v6, v6 row_mirror row_mask:0xf bank_mask:0xf bound_ctrl:1
	v_mov_b32_e32 v7, v6
	s_nop 1
	v_permlane16_swap_b32_e32 v6, v7
	v_add_f32_e32 v6, v6, v7
	v_mov_b32_e32 v7, v6
	s_nop 1
	v_permlane32_swap_b32_e32 v6, v7
	s_and_saveexec_b64 s[2:3], s[0:1]
	v_add_f32_e32 v6, v6, v7
	v_mov_b32_e32 v7, s17
	ds_write_b32 v7, v6 offset:72
	s_or_b64 exec, exec, s[2:3]
	v_mov_b32_e32 v100, s77
	s_waitcnt lgkmcnt(12)
; #define LAS __attribute__((address_space(3)))
; #define DPPADD_(v, ctrl) ((v) + __builtin_bit_cast(float, __builtin_amdgcn_update_dpp(0, __builtin_bit_cast(int, (v)), (ctrl), 0xf, 0xf, true)))
; __device__ __forceinline__ float wave_sum_valu(float v) {
;     v = DPPADD_(v, 0xB1); v = DPPADD_(v, 0x4E); v = DPPADD_(v, 0x141); v = DPPADD_(v, 0x140);
;     { auto r = __builtin_amdgcn_permlane16_swap(__float_as_uint(v), __float_as_uint(v), false, false); v = __uint_as_float(r[0]) + __uint_as_float(r[1]); }
;     { auto r = __builtin_amdgcn_permlane32_swap(__float_as_uint(v), __float_as_uint(v), false, false); v = __uint_as_float(r[0]) + __uint_as_float(r[1]); }
;     return v;
; __device__ __forceinline__ void pool_phase(const Params& a, LAS unsigned char* lds) {
;     ...
;         for (int tt = 0; tt < 32; ++tt) { const int tl = half * 32 + tt; float acc = 0.f;
; #pragma unroll
;             for (int c4 = 0; c4 < 16; ++c4) { const f32x4 pv = *(const LAS f32x4*)(ps + tl * 256 + g * 64 + c4 * 4);
;                 acc += pv[0] * wreg[4 * c4] + pv[1] * wreg[4 * c4 + 1] + pv[2] * wreg[4 * c4 + 2] + pv[3] * wreg[4 * c4 + 3]; }
;             o[tt] = acc * pscale; const float s = wave_sum_valu(o[tt] * o[tt]);
;             if (lane == 0) ssl[g * 64 + tl] = s; }
	v_mul_f32_e32 v220, v15, v157
	v_fmac_f32_e32 v220, v14, v156
	v_fmac_f32_e32 v220, v16, v158
	v_fmac_f32_e32 v220, v17, v159
	ds_read_b128 v[204:207], v100 offset:192
	s_waitcnt lgkmcnt(12)
	v_fmac_f32_e32 v220, v19, v161
	v_fmac_f32_e32 v220, v18, v160
	v_fmac_f32_e32 v220, v20, v162
	v_fmac_f32_e32 v220, v21, v163
	ds_read_b128 v[208:211], v100 offset:208
	s_waitcnt lgkmcnt(12)
	v_fmac_f32_e32 v220, v23, v165
	v_fmac_f32_e32 v220, v22, v164
	v_fmac_f32_e32 v220, v24, v166
	v_fmac_f32_e32 v220, v25, v167
	ds_read_b128 v[212:215], v100 offset:224
	s_waitcnt lgkmcnt(12)
	v_fmac_f32_e32 v220, v27, v169
	v_fmac_f32_e32 v220, v26, v168
	v_fmac_f32_e32 v220, v28, v170
	v_fmac_f32_e32 v220, v29, v171
	ds_read_b128 v[216:219], v100 offset:240
	s_waitcnt lgkmcnt(12)
	v_fmac_f32_e32 v220, v31, v173
	v_fmac_f32_e32 v220, v30, v172
	v_fmac_f32_e32 v220, v32, v174
	v_fmac_f32_e32 v220, v33, v175
	ds_read_b128 v[156:159], v100 offset:1024
	s_waitcnt lgkmcnt(12)
	v_fmac_f32_e32 v220, v35, v177
	v_fmac_f32_e32 v220, v34, v176
	v_fmac_f32_e32 v220, v36, v178
	v_fmac_f32_e32 v220, v37, v179
	ds_read_b128 v[160:163], v100 offset:1040
	s_waitcnt lgkmcnt(12)
	v_fmac_f32_e32 v220, v39, v181
	v_fmac_f32_e32 v220, v38, v180
	v_fmac_f32_e32 v220, v40, v182
	v_fmac_f32_e32 v220, v41, v183
	ds_read_b128 v[164:167], v100 offset:1056
	s_waitcnt lgkmcnt(12)
	v_fmac_f32_e32 v220, v43, v185
	v_fmac_f32_e32 v220, v42, v184
	v_fmac_f32_e32 v220, v44, v186
	v_fmac_f32_e32 v220, v45, v187
	ds_read_b128 v[168:171], v100 offset:1072
	s_waitcnt lgkmcnt(12)
	v_fmac_f32_e32 v220, v47, v189
	v_fmac_f32_e32 v220, v46, v188
	v_fmac_f32_e32 v220, v48, v190
	v_fmac_f32_e32 v220, v49, v191
	ds_read_b128 v[172:175], v100 offset:1088
	s_waitcnt lgkmcnt(12)
	v_fmac_f32_e32 v220, v51, v193
	v_fmac_f32_e32 v220, v50, v192
	v_fmac_f32_e32 v220, v52, v194
	v_fmac_f32_e32 v220, v53, v195
	ds_read_b128 v[176:179], v100 offset:1104
	s_waitcnt lgkmcnt(12)
	v_fmac_f32_e32 v220, v55, v197
	v_fmac_f32_e32 v220, v54, v196
	v_fmac_f32_e32 v220, v56, v198
	v_fmac_f32_e32 v220, v57, v199
	ds_read_b128 v[180:183], v100 offset:1120
	s_waitcnt lgkmcnt(12)
	v_fmac_f32_e32 v220, v59, v201
	v_fmac_f32_e32 v220, v58, v200
	v_fmac_f32_e32 v220, v60, v202
	v_fmac_f32_e32 v220, v61, v203
	ds_read_b128 v[184:187], v100 offset:1136
	s_waitcnt lgkmcnt(11)
	v_fmac_f32_e32 v220, v63, v205
	v_fmac_f32_e32 v220, v62, v204
	v_fmac_f32_e32 v220, v64, v206
	v_fmac_f32_e32 v220, v65, v207
	ds_read_b128 v[188:191], v100 offset:1152
	s_waitcnt lgkmcnt(11)
	v_fmac_f32_e32 v220, v67, v209
	v_fmac_f32_e32 v220, v66, v208
	v_fmac_f32_e32 v220, v68, v210
	v_fmac_f32_e32 v220, v69, v211
	ds_read_b128 v[192:195], v100 offset:1168
	s_waitcnt lgkmcnt(11)
	v_fmac_f32_e32 v220, v71, v213
	v_fmac_f32_e32 v220, v70, v212
	v_fmac_f32_e32 v220, v72, v214
	v_fmac_f32_e32 v220, v73, v215
	ds_read_b128 v[196:199], v100 offset:1184
	s_waitcnt lgkmcnt(11)
	v_fmac_f32_e32 v220, v75, v217
	v_fmac_f32_e32 v220, v74, v216
	v_fmac_f32_e32 v220, v76, v218
	v_fmac_f32_e32 v220, v77, v219
	ds_read_b128 v[200:203], v100 offset:1200
	v_mul_f32_e32 v100, v78, v220
	v_mul_f32_e32 v6, v100, v100
	s_nop 1
	v_mov_b32_dpp v6, v6 quad_perm:[1,0,3,2] row_mask:0xf bank_mask:0xf bound_ctrl:1
	v_fmac_f32_e32 v6, v100, v100
	s_nop 1
	v_add_f32_dpp v6, v6, v6 quad_perm:[2,3,0,1] row_mask:0xf bank_mask:0xf bound_ctrl:1
	s_nop 1
	v_add_f32_dpp v6, v6, v6 row_half_mirror row_mask:0xf bank_mask:0xf bound_ctrl:1
	s_nop 1
	v_add_f32_dpp v6, v6, v6 row_mirror row_mask:0xf bank_mask:0xf bound_ctrl:1
	v_mov_b32_e32 v7, v6
	s_nop 1
	v_permlane16_swap_b32_e32 v6, v7
	v_add_f32_e32 v6, v6, v7
	v_mov_b32_e32 v7, v6
	s_nop 1
	v_permlane32_swap_b32_e32 v6, v7
	s_and_saveexec_b64 s[2:3], s[0:1]
	v_add_f32_e32 v6, v6, v7
	v_mov_b32_e32 v7, s17
	ds_write_b32 v7, v6 offset:76
	s_or_b64 exec, exec, s[2:3]
	v_mov_b32_e32 v124, s78
	s_waitcnt lgkmcnt(12)
	v_mul_f32_e32 v220, v15, v157
	v_fmac_f32_e32 v220, v14, v156
	v_fmac_f32_e32 v220, v16, v158
	v_fmac_f32_e32 v220, v17, v159
	ds_read_b128 v[204:207], v124 offset:192
	s_waitcnt lgkmcnt(12)
	v_fmac_f32_e32 v220, v19, v161
	v_fmac_f32_e32 v220, v18, v160
	v_fmac_f32_e32 v220, v20, v162
	v_fmac_f32_e32 v220, v21, v163
	ds_read_b128 v[208:211], v124 offset:208
	s_waitcnt lgkmcnt(12)
	v_fmac_f32_e32 v220, v23, v165
	v_fmac_f32_e32 v220, v22, v164
	v_fmac_f32_e32 v220, v24, v166
	v_fmac_f32_e32 v220, v25, v167
	ds_read_b128 v[212:215], v124 offset:224
	s_waitcnt lgkmcnt(12)
	v_fmac_f32_e32 v220, v27, v169
	v_fmac_f32_e32 v220, v26, v168
	v_fmac_f32_e32 v220, v28, v170
	v_fmac_f32_e32 v220, v29, v171
	ds_read_b128 v[216:219], v124 offset:240
	s_waitcnt lgkmcnt(12)
	v_fmac_f32_e32 v220, v31, v173
	v_fmac_f32_e32 v220, v30, v172
	v_fmac_f32_e32 v220, v32, v174
	v_fmac_f32_e32 v220, v33, v175
	ds_read_b128 v[156:159], v124 offset:1024
	s_waitcnt lgkmcnt(12)
	v_fmac_f32_e32 v220, v35, v177
	v_fmac_f32_e32 v220, v34, v176
	v_fmac_f32_e32 v220, v36, v178
	v_fmac_f32_e32 v220, v37, v179
	ds_read_b128 v[160:163], v124 offset:1040
	s_waitcnt lgkmcnt(12)
	v_fmac_f32_e32 v220, v39, v181
	v_fmac_f32_e32 v220, v38, v180
	v_fmac_f32_e32 v220, v40, v182
	v_fmac_f32_e32 v220, v41, v183
	ds_read_b128 v[164:167], v124 offset:1056
	s_waitcnt lgkmcnt(12)
	v_fmac_f32_e32 v220, v43, v185
	v_fmac_f32_e32 v220, v42, v184
	v_fmac_f32_e32 v220, v44, v186
	v_fmac_f32_e32 v220, v45, v187
	ds_read_b128 v[168:171], v124 offset:1072
	s_waitcnt lgkmcnt(12)
	v_fmac_f32_e32 v220, v47, v189
	v_fmac_f32_e32 v220, v46, v188
	v_fmac_f32_e32 v220, v48, v190
	v_fmac_f32_e32 v220, v49, v191
	ds_read_b128 v[172:175], v124 offset:1088
	s_waitcnt lgkmcnt(12)
; #define LAS __attribute__((address_space(3)))
; #define DPPADD_(v, ctrl) ((v) + __builtin_bit_cast(float, __builtin_amdgcn_update_dpp(0, __builtin_bit_cast(int, (v)), (ctrl), 0xf, 0xf, true)))
; __device__ __forceinline__ float wave_sum_valu(float v) {
;     v = DPPADD_(v, 0xB1); v = DPPADD_(v, 0x4E); v = DPPADD_(v, 0x141); v = DPPADD_(v, 0x140);
;     { auto r = __builtin_amdgcn_permlane16_swap(__float_as_uint(v), __float_as_uint(v), false, false); v = __uint_as_float(r[0]) + __uint_as_float(r[1]); }
;     { auto r = __builtin_amdgcn_permlane32_swap(__float_as_uint(v), __float_as_uint(v), false, false); v = __uint_as_float(r[0]) + __uint_as_float(r[1]); }
;     return v;
; __device__ __forceinline__ void pool_phase(const Params& a, LAS unsigned char* lds) {
;     ...
;         for (int tt = 0; tt < 32; ++tt) { const int tl = half * 32 + tt; float acc = 0.f;
; #pragma unroll
;             for (int c4 = 0; c4 < 16; ++c4) { const f32x4 pv = *(const LAS f32x4*)(ps + tl * 256 + g * 64 + c4 * 4);
;                 acc += pv[0] * wreg[4 * c4] + pv[1] * wreg[4 * c4 + 1] + pv[2] * wreg[4 * c4 + 2] + pv[3] * wreg[4 * c4 + 3]; }
;             o[tt] = acc * pscale; const float s = wave_sum_valu(o[tt] * o[tt]);
;             if (lane == 0) ssl[g * 64 + tl] = s; }
	v_fmac_f32_e32 v220, v51, v193
	v_fmac_f32_e32 v220, v50, v192
	v_fmac_f32_e32 v220, v52, v194
	v_fmac_f32_e32 v220, v53, v195
	ds_read_b128 v[176:179], v124 offset:1104
	s_waitcnt lgkmcnt(12)
	v_fmac_f32_e32 v220, v55, v197
	v_fmac_f32_e32 v220, v54, v196
	v_fmac_f32_e32 v220, v56, v198
	v_fmac_f32_e32 v220, v57, v199
	ds_read_b128 v[180:183], v124 offset:1120
	s_waitcnt lgkmcnt(12)
	v_fmac_f32_e32 v220, v59, v201
	v_fmac_f32_e32 v220, v58, v200
	v_fmac_f32_e32 v220, v60, v202
	v_fmac_f32_e32 v220, v61, v203
	ds_read_b128 v[184:187], v124 offset:1136
	s_waitcnt lgkmcnt(11)
	v_fmac_f32_e32 v220, v63, v205
	v_fmac_f32_e32 v220, v62, v204
	v_fmac_f32_e32 v220, v64, v206
	v_fmac_f32_e32 v220, v65, v207
	ds_read_b128 v[188:191], v124 offset:1152
	s_waitcnt lgkmcnt(11)
	v_fmac_f32_e32 v220, v67, v209
	v_fmac_f32_e32 v220, v66, v208
	v_fmac_f32_e32 v220, v68, v210
	v_fmac_f32_e32 v220, v69, v211
	ds_read_b128 v[192:195], v124 offset:1168
	s_waitcnt lgkmcnt(11)
	v_fmac_f32_e32 v220, v71, v213
	v_fmac_f32_e32 v220, v70, v212
	v_fmac_f32_e32 v220, v72, v214
	v_fmac_f32_e32 v220, v73, v215
	ds_read_b128 v[196:199], v124 offset:1184
	s_waitcnt lgkmcnt(11)
	v_fmac_f32_e32 v220, v75, v217
	v_fmac_f32_e32 v220, v74, v216
	v_fmac_f32_e32 v220, v76, v218
	v_fmac_f32_e32 v220, v77, v219
	ds_read_b128 v[200:203], v124 offset:1200
	v_mul_f32_e32 v99, v78, v220
	v_mul_f32_e32 v6, v99, v99
	s_nop 1
	v_mov_b32_dpp v6, v6 quad_perm:[1,0,3,2] row_mask:0xf bank_mask:0xf bound_ctrl:1
	v_fmac_f32_e32 v6, v99, v99
	s_nop 1
	v_add_f32_dpp v6, v6, v6 quad_perm:[2,3,0,1] row_mask:0xf bank_mask:0xf bound_ctrl:1
	s_nop 1
	v_add_f32_dpp v6, v6, v6 row_half_mirror row_mask:0xf bank_mask:0xf bound_ctrl:1
	s_nop 1
	v_add_f32_dpp v6, v6, v6 row_mirror row_mask:0xf bank_mask:0xf bound_ctrl:1
	v_mov_b32_e32 v7, v6
	s_nop 1
	v_permlane16_swap_b32_e32 v6, v7
	v_add_f32_e32 v6, v6, v7
	v_mov_b32_e32 v7, v6
	s_nop 1
	v_permlane32_swap_b32_e32 v6, v7
	s_and_saveexec_b64 s[2:3], s[0:1]
	v_add_f32_e32 v6, v6, v7
	v_mov_b32_e32 v7, s17
	ds_write_b32 v7, v6 offset:80
	s_or_b64 exec, exec, s[2:3]
	v_mov_b32_e32 v96, s79
	s_waitcnt lgkmcnt(12)
	v_mul_f32_e32 v220, v15, v157
	v_fmac_f32_e32 v220, v14, v156
	v_fmac_f32_e32 v220, v16, v158
	v_fmac_f32_e32 v220, v17, v159
	ds_read_b128 v[204:207], v96 offset:192
	s_waitcnt lgkmcnt(12)
	v_fmac_f32_e32 v220, v19, v161
	v_fmac_f32_e32 v220, v18, v160
	v_fmac_f32_e32 v220, v20, v162
	v_fmac_f32_e32 v220, v21, v163
	ds_read_b128 v[208:211], v96 offset:208
	s_waitcnt lgkmcnt(12)
	v_fmac_f32_e32 v220, v23, v165
	v_fmac_f32_e32 v220, v22, v164
	v_fmac_f32_e32 v220, v24, v166
	v_fmac_f32_e32 v220, v25, v167
	ds_read_b128 v[212:215], v96 offset:224
	s_waitcnt lgkmcnt(12)
	v_fmac_f32_e32 v220, v27, v169
	v_fmac_f32_e32 v220, v26, v168
	v_fmac_f32_e32 v220, v28, v170
	v_fmac_f32_e32 v220, v29, v171
	ds_read_b128 v[216:219], v96 offset:240
	s_waitcnt lgkmcnt(12)
	v_fmac_f32_e32 v220, v31, v173
	v_fmac_f32_e32 v220, v30, v172
	v_fmac_f32_e32 v220, v32, v174
	v_fmac_f32_e32 v220, v33, v175
	ds_read_b128 v[156:159], v96 offset:1024
	s_waitcnt lgkmcnt(12)
	v_fmac_f32_e32 v220, v35, v177
	v_fmac_f32_e32 v220, v34, v176
	v_fmac_f32_e32 v220, v36, v178
	v_fmac_f32_e32 v220, v37, v179
	ds_read_b128 v[160:163], v96 offset:1040
	s_waitcnt lgkmcnt(12)
	v_fmac_f32_e32 v220, v39, v181
	v_fmac_f32_e32 v220, v38, v180
	v_fmac_f32_e32 v220, v40, v182
	v_fmac_f32_e32 v220, v41, v183
	ds_read_b128 v[164:167], v96 offset:1056
	s_waitcnt lgkmcnt(12)
	v_fmac_f32_e32 v220, v43, v185
	v_fmac_f32_e32 v220, v42, v184
	v_fmac_f32_e32 v220, v44, v186
	v_fmac_f32_e32 v220, v45, v187
	ds_read_b128 v[168:171], v96 offset:1072
	s_waitcnt lgkmcnt(12)
	v_fmac_f32_e32 v220, v47, v189
	v_fmac_f32_e32 v220, v46, v188
	v_fmac_f32_e32 v220, v48, v190
	v_fmac_f32_e32 v220, v49, v191
	ds_read_b128 v[172:175], v96 offset:1088
	s_waitcnt lgkmcnt(12)
	v_fmac_f32_e32 v220, v51, v193
	v_fmac_f32_e32 v220, v50, v192
	v_fmac_f32_e32 v220, v52, v194
	v_fmac_f32_e32 v220, v53, v195
	ds_read_b128 v[176:179], v96 offset:1104
	s_waitcnt lgkmcnt(12)
	v_fmac_f32_e32 v220, v55, v197
	v_fmac_f32_e32 v220, v54, v196
	v_fmac_f32_e32 v220, v56, v198
	v_fmac_f32_e32 v220, v57, v199
	ds_read_b128 v[180:183], v96 offset:1120
	s_waitcnt lgkmcnt(12)
	v_fmac_f32_e32 v220, v59, v201
	v_fmac_f32_e32 v220, v58, v200
	v_fmac_f32_e32 v220, v60, v202
	v_fmac_f32_e32 v220, v61, v203
	ds_read_b128 v[184:187], v96 offset:1136
	s_waitcnt lgkmcnt(11)
	v_fmac_f32_e32 v220, v63, v205
	v_fmac_f32_e32 v220, v62, v204
	v_fmac_f32_e32 v220, v64, v206
	v_fmac_f32_e32 v220, v65, v207
	ds_read_b128 v[188:191], v96 offset:1152
	s_waitcnt lgkmcnt(11)
	v_fmac_f32_e32 v220, v67, v209
	v_fmac_f32_e32 v220, v66, v208
	v_fmac_f32_e32 v220, v68, v210
	v_fmac_f32_e32 v220, v69, v211
	ds_read_b128 v[192:195], v96 offset:1168
	s_waitcnt lgkmcnt(11)
	v_fmac_f32_e32 v220, v71, v213
	v_fmac_f32_e32 v220, v70, v212
	v_fmac_f32_e32 v220, v72, v214
	v_fmac_f32_e32 v220, v73, v215
	ds_read_b128 v[196:199], v96 offset:1184
	s_waitcnt lgkmcnt(11)
	v_fmac_f32_e32 v220, v75, v217
	v_fmac_f32_e32 v220, v74, v216
	v_fmac_f32_e32 v220, v76, v218
	v_fmac_f32_e32 v220, v77, v219
	ds_read_b128 v[200:203], v96 offset:1200
	v_mul_f32_e32 v98, v78, v220
	v_mul_f32_e32 v6, v98, v98
	s_nop 1
	v_mov_b32_dpp v6, v6 quad_perm:[1,0,3,2] row_mask:0xf bank_mask:0xf bound_ctrl:1
	v_fmac_f32_e32 v6, v98, v98
	s_nop 1
	v_add_f32_dpp v6, v6, v6 quad_perm:[2,3,0,1] row_mask:0xf bank_mask:0xf bound_ctrl:1
	s_nop 1
	v_add_f32_dpp v6, v6, v6 row_half_mirror row_mask:0xf bank_mask:0xf bound_ctrl:1
	s_nop 1
	v_add_f32_dpp v6, v6, v6 row_mirror row_mask:0xf bank_mask:0xf bound_ctrl:1
	v_mov_b32_e32 v7, v6
	s_nop 1
	v_permlane16_swap_b32_e32 v6, v7
	v_add_f32_e32 v6, v6, v7
	v_mov_b32_e32 v7, v6
	s_nop 1
	v_permlane32_swap_b32_e32 v6, v7
	s_and_saveexec_b64 s[2:3], s[0:1]
	v_add_f32_e32 v6, v6, v7
	v_mov_b32_e32 v7, s17
	ds_write_b32 v7, v6 offset:84
	s_or_b64 exec, exec, s[2:3]
	v_mov_b32_e32 v96, s80
	s_waitcnt lgkmcnt(12)
; #define LAS __attribute__((address_space(3)))
; #define DPPADD_(v, ctrl) ((v) + __builtin_bit_cast(float, __builtin_amdgcn_update_dpp(0, __builtin_bit_cast(int, (v)), (ctrl), 0xf, 0xf, true)))
; __device__ __forceinline__ float wave_sum_valu(float v) {
;     v = DPPADD_(v, 0xB1); v = DPPADD_(v, 0x4E); v = DPPADD_(v, 0x141); v = DPPADD_(v, 0x140);
;     { auto r = __builtin_amdgcn_permlane16_swap(__float_as_uint(v), __float_as_uint(v), false, false); v = __uint_as_float(r[0]) + __uint_as_float(r[1]); }
;     { auto r = __builtin_amdgcn_permlane32_swap(__float_as_uint(v), __float_as_uint(v), false, false); v = __uint_as_float(r[0]) + __uint_as_float(r[1]); }
;     return v;
; __device__ __forceinline__ void pool_phase(const Params& a, LAS unsigned char* lds) {
;     ...
;         for (int tt = 0; tt < 32; ++tt) { const int tl = half * 32 + tt; float acc = 0.f;
; #pragma unroll
;             for (int c4 = 0; c4 < 16; ++c4) { const f32x4 pv = *(const LAS f32x4*)(ps + tl * 256 + g * 64 + c4 * 4);
;                 acc += pv[0] * wreg[4 * c4] + pv[1] * wreg[4 * c4 + 1] + pv[2] * wreg[4 * c4 + 2] + pv[3] * wreg[4 * c4 + 3]; }
;             o[tt] = acc * pscale; const float s = wave_sum_valu(o[tt] * o[tt]);
;             if (lane == 0) ssl[g * 64 + tl] = s; }
	v_mul_f32_e32 v220, v15, v157
	v_fmac_f32_e32 v220, v14, v156
	v_fmac_f32_e32 v220, v16, v158
	v_fmac_f32_e32 v220, v17, v159
	ds_read_b128 v[204:207], v96 offset:192
	s_waitcnt lgkmcnt(12)
	v_fmac_f32_e32 v220, v19, v161
	v_fmac_f32_e32 v220, v18, v160
	v_fmac_f32_e32 v220, v20, v162
	v_fmac_f32_e32 v220, v21, v163
	ds_read_b128 v[208:211], v96 offset:208
	s_waitcnt lgkmcnt(12)
	v_fmac_f32_e32 v220, v23, v165
	v_fmac_f32_e32 v220, v22, v164
	v_fmac_f32_e32 v220, v24, v166
	v_fmac_f32_e32 v220, v25, v167
	ds_read_b128 v[212:215], v96 offset:224
	s_waitcnt lgkmcnt(12)
	v_fmac_f32_e32 v220, v27, v169
	v_fmac_f32_e32 v220, v26, v168
	v_fmac_f32_e32 v220, v28, v170
	v_fmac_f32_e32 v220, v29, v171
	ds_read_b128 v[216:219], v96 offset:240
	s_waitcnt lgkmcnt(12)
	v_fmac_f32_e32 v220, v31, v173
	v_fmac_f32_e32 v220, v30, v172
	v_fmac_f32_e32 v220, v32, v174
	v_fmac_f32_e32 v220, v33, v175
	ds_read_b128 v[156:159], v96 offset:1024
	s_waitcnt lgkmcnt(12)
	v_fmac_f32_e32 v220, v35, v177
	v_fmac_f32_e32 v220, v34, v176
	v_fmac_f32_e32 v220, v36, v178
	v_fmac_f32_e32 v220, v37, v179
	ds_read_b128 v[160:163], v96 offset:1040
	s_waitcnt lgkmcnt(12)
	v_fmac_f32_e32 v220, v39, v181
	v_fmac_f32_e32 v220, v38, v180
	v_fmac_f32_e32 v220, v40, v182
	v_fmac_f32_e32 v220, v41, v183
	ds_read_b128 v[164:167], v96 offset:1056
	s_waitcnt lgkmcnt(12)
	v_fmac_f32_e32 v220, v43, v185
	v_fmac_f32_e32 v220, v42, v184
	v_fmac_f32_e32 v220, v44, v186
	v_fmac_f32_e32 v220, v45, v187
	ds_read_b128 v[168:171], v96 offset:1072
	s_waitcnt lgkmcnt(12)
	v_fmac_f32_e32 v220, v47, v189
	v_fmac_f32_e32 v220, v46, v188
	v_fmac_f32_e32 v220, v48, v190
	v_fmac_f32_e32 v220, v49, v191
	ds_read_b128 v[172:175], v96 offset:1088
	s_waitcnt lgkmcnt(12)
	v_fmac_f32_e32 v220, v51, v193
	v_fmac_f32_e32 v220, v50, v192
	v_fmac_f32_e32 v220, v52, v194
	v_fmac_f32_e32 v220, v53, v195
	ds_read_b128 v[176:179], v96 offset:1104
	s_waitcnt lgkmcnt(12)
	v_fmac_f32_e32 v220, v55, v197
	v_fmac_f32_e32 v220, v54, v196
	v_fmac_f32_e32 v220, v56, v198
	v_fmac_f32_e32 v220, v57, v199
	ds_read_b128 v[180:183], v96 offset:1120
	s_waitcnt lgkmcnt(12)
	v_fmac_f32_e32 v220, v59, v201
	v_fmac_f32_e32 v220, v58, v200
	v_fmac_f32_e32 v220, v60, v202
	v_fmac_f32_e32 v220, v61, v203
	ds_read_b128 v[184:187], v96 offset:1136
	s_waitcnt lgkmcnt(11)
	v_fmac_f32_e32 v220, v63, v205
	v_fmac_f32_e32 v220, v62, v204
	v_fmac_f32_e32 v220, v64, v206
	v_fmac_f32_e32 v220, v65, v207
	ds_read_b128 v[188:191], v96 offset:1152
	s_waitcnt lgkmcnt(11)
	v_fmac_f32_e32 v220, v67, v209
	v_fmac_f32_e32 v220, v66, v208
	v_fmac_f32_e32 v220, v68, v210
	v_fmac_f32_e32 v220, v69, v211
	ds_read_b128 v[192:195], v96 offset:1168
	s_waitcnt lgkmcnt(11)
	v_fmac_f32_e32 v220, v71, v213
	v_fmac_f32_e32 v220, v70, v212
	v_fmac_f32_e32 v220, v72, v214
	v_fmac_f32_e32 v220, v73, v215
	ds_read_b128 v[196:199], v96 offset:1184
	s_waitcnt lgkmcnt(11)
	v_fmac_f32_e32 v220, v75, v217
	v_fmac_f32_e32 v220, v74, v216
	v_fmac_f32_e32 v220, v76, v218
	v_fmac_f32_e32 v220, v77, v219
	ds_read_b128 v[200:203], v96 offset:1200
	v_mul_f32_e32 v97, v78, v220
	v_mul_f32_e32 v6, v97, v97
	s_nop 1
	v_mov_b32_dpp v6, v6 quad_perm:[1,0,3,2] row_mask:0xf bank_mask:0xf bound_ctrl:1
	v_fmac_f32_e32 v6, v97, v97
	s_nop 1
	v_add_f32_dpp v6, v6, v6 quad_perm:[2,3,0,1] row_mask:0xf bank_mask:0xf bound_ctrl:1
	s_nop 1
	v_add_f32_dpp v6, v6, v6 row_half_mirror row_mask:0xf bank_mask:0xf bound_ctrl:1
	s_nop 1
	v_add_f32_dpp v6, v6, v6 row_mirror row_mask:0xf bank_mask:0xf bound_ctrl:1
	v_mov_b32_e32 v7, v6
	s_nop 1
	v_permlane16_swap_b32_e32 v6, v7
	v_add_f32_e32 v6, v6, v7
	v_mov_b32_e32 v7, v6
	s_nop 1
	v_permlane32_swap_b32_e32 v6, v7
	s_and_saveexec_b64 s[2:3], s[0:1]
	v_add_f32_e32 v6, v6, v7
	v_mov_b32_e32 v7, s17
	ds_write_b32 v7, v6 offset:88
	s_or_b64 exec, exec, s[2:3]
	v_mov_b32_e32 v96, s81
	s_waitcnt lgkmcnt(12)
	v_mul_f32_e32 v220, v15, v157
	v_fmac_f32_e32 v220, v14, v156
	v_fmac_f32_e32 v220, v16, v158
	v_fmac_f32_e32 v220, v17, v159
	ds_read_b128 v[204:207], v96 offset:192
	s_waitcnt lgkmcnt(12)
	v_fmac_f32_e32 v220, v19, v161
	v_fmac_f32_e32 v220, v18, v160
	v_fmac_f32_e32 v220, v20, v162
	v_fmac_f32_e32 v220, v21, v163
	ds_read_b128 v[208:211], v96 offset:208
	s_waitcnt lgkmcnt(12)
	v_fmac_f32_e32 v220, v23, v165
	v_fmac_f32_e32 v220, v22, v164
	v_fmac_f32_e32 v220, v24, v166
	v_fmac_f32_e32 v220, v25, v167
	ds_read_b128 v[212:215], v96 offset:224
	s_waitcnt lgkmcnt(12)
	v_fmac_f32_e32 v220, v27, v169
	v_fmac_f32_e32 v220, v26, v168
	v_fmac_f32_e32 v220, v28, v170
	v_fmac_f32_e32 v220, v29, v171
	ds_read_b128 v[216:219], v96 offset:240
	s_waitcnt lgkmcnt(12)
	v_fmac_f32_e32 v220, v31, v173
	v_fmac_f32_e32 v220, v30, v172
	v_fmac_f32_e32 v220, v32, v174
	v_fmac_f32_e32 v220, v33, v175
	ds_read_b128 v[156:159], v96 offset:1024
	s_waitcnt lgkmcnt(12)
	v_fmac_f32_e32 v220, v35, v177
	v_fmac_f32_e32 v220, v34, v176
	v_fmac_f32_e32 v220, v36, v178
	v_fmac_f32_e32 v220, v37, v179
	ds_read_b128 v[160:163], v96 offset:1040
	s_waitcnt lgkmcnt(12)
	v_fmac_f32_e32 v220, v39, v181
	v_fmac_f32_e32 v220, v38, v180
	v_fmac_f32_e32 v220, v40, v182
	v_fmac_f32_e32 v220, v41, v183
	ds_read_b128 v[164:167], v96 offset:1056
	s_waitcnt lgkmcnt(12)
	v_fmac_f32_e32 v220, v43, v185
	v_fmac_f32_e32 v220, v42, v184
	v_fmac_f32_e32 v220, v44, v186
	v_fmac_f32_e32 v220, v45, v187
	ds_read_b128 v[168:171], v96 offset:1072
	s_waitcnt lgkmcnt(12)
	v_fmac_f32_e32 v220, v47, v189
	v_fmac_f32_e32 v220, v46, v188
	v_fmac_f32_e32 v220, v48, v190
	v_fmac_f32_e32 v220, v49, v191
	ds_read_b128 v[172:175], v96 offset:1088
	s_waitcnt lgkmcnt(12)
; #define LAS __attribute__((address_space(3)))
; #define DPPADD_(v, ctrl) ((v) + __builtin_bit_cast(float, __builtin_amdgcn_update_dpp(0, __builtin_bit_cast(int, (v)), (ctrl), 0xf, 0xf, true)))
; __device__ __forceinline__ float wave_sum_valu(float v) {
;     v = DPPADD_(v, 0xB1); v = DPPADD_(v, 0x4E); v = DPPADD_(v, 0x141); v = DPPADD_(v, 0x140);
;     { auto r = __builtin_amdgcn_permlane16_swap(__float_as_uint(v), __float_as_uint(v), false, false); v = __uint_as_float(r[0]) + __uint_as_float(r[1]); }
;     { auto r = __builtin_amdgcn_permlane32_swap(__float_as_uint(v), __float_as_uint(v), false, false); v = __uint_as_float(r[0]) + __uint_as_float(r[1]); }
;     return v;
; __device__ __forceinline__ void pool_phase(const Params& a, LAS unsigned char* lds) {
;     ...
;         for (int tt = 0; tt < 32; ++tt) { const int tl = half * 32 + tt; float acc = 0.f;
; #pragma unroll
;             for (int c4 = 0; c4 < 16; ++c4) { const f32x4 pv = *(const LAS f32x4*)(ps + tl * 256 + g * 64 + c4 * 4);
;                 acc += pv[0] * wreg[4 * c4] + pv[1] * wreg[4 * c4 + 1] + pv[2] * wreg[4 * c4 + 2] + pv[3] * wreg[4 * c4 + 3]; }
;             o[tt] = acc * pscale; const float s = wave_sum_valu(o[tt] * o[tt]);
;             if (lane == 0) ssl[g * 64 + tl] = s; }
	v_fmac_f32_e32 v220, v51, v193
	v_fmac_f32_e32 v220, v50, v192
	v_fmac_f32_e32 v220, v52, v194
	v_fmac_f32_e32 v220, v53, v195
	ds_read_b128 v[176:179], v96 offset:1104
	s_waitcnt lgkmcnt(12)
	v_fmac_f32_e32 v220, v55, v197
	v_fmac_f32_e32 v220, v54, v196
	v_fmac_f32_e32 v220, v56, v198
	v_fmac_f32_e32 v220, v57, v199
	ds_read_b128 v[180:183], v96 offset:1120
	s_waitcnt lgkmcnt(12)
	v_fmac_f32_e32 v220, v59, v201
	v_fmac_f32_e32 v220, v58, v200
	v_fmac_f32_e32 v220, v60, v202
	v_fmac_f32_e32 v220, v61, v203
	ds_read_b128 v[184:187], v96 offset:1136
	s_waitcnt lgkmcnt(11)
	v_fmac_f32_e32 v220, v63, v205
	v_fmac_f32_e32 v220, v62, v204
	v_fmac_f32_e32 v220, v64, v206
	v_fmac_f32_e32 v220, v65, v207
	ds_read_b128 v[188:191], v96 offset:1152
	s_waitcnt lgkmcnt(11)
	v_fmac_f32_e32 v220, v67, v209
	v_fmac_f32_e32 v220, v66, v208
	v_fmac_f32_e32 v220, v68, v210
	v_fmac_f32_e32 v220, v69, v211
	ds_read_b128 v[192:195], v96 offset:1168
	s_waitcnt lgkmcnt(11)
	v_fmac_f32_e32 v220, v71, v213
	v_fmac_f32_e32 v220, v70, v212
	v_fmac_f32_e32 v220, v72, v214
	v_fmac_f32_e32 v220, v73, v215
	ds_read_b128 v[196:199], v96 offset:1184
	s_waitcnt lgkmcnt(11)
	v_fmac_f32_e32 v220, v75, v217
	v_fmac_f32_e32 v220, v74, v216
	v_fmac_f32_e32 v220, v76, v218
	v_fmac_f32_e32 v220, v77, v219
	ds_read_b128 v[200:203], v96 offset:1200
	v_mul_f32_e32 v96, v78, v220
	v_mul_f32_e32 v6, v96, v96
	s_nop 1
	v_mov_b32_dpp v6, v6 quad_perm:[1,0,3,2] row_mask:0xf bank_mask:0xf bound_ctrl:1
	v_fmac_f32_e32 v6, v96, v96
	s_nop 1
	v_add_f32_dpp v6, v6, v6 quad_perm:[2,3,0,1] row_mask:0xf bank_mask:0xf bound_ctrl:1
	s_nop 1
	v_add_f32_dpp v6, v6, v6 row_half_mirror row_mask:0xf bank_mask:0xf bound_ctrl:1
	s_nop 1
	v_add_f32_dpp v6, v6, v6 row_mirror row_mask:0xf bank_mask:0xf bound_ctrl:1
	v_mov_b32_e32 v7, v6
	s_nop 1
	v_permlane16_swap_b32_e32 v6, v7
	v_add_f32_e32 v6, v6, v7
	v_mov_b32_e32 v7, v6
	s_nop 1
	v_permlane32_swap_b32_e32 v6, v7
	s_and_saveexec_b64 s[2:3], s[0:1]
	v_add_f32_e32 v6, v6, v7
	v_mov_b32_e32 v7, s17
	ds_write_b32 v7, v6 offset:92
	s_or_b64 exec, exec, s[2:3]
	v_mov_b32_e32 v128, s82
	s_waitcnt lgkmcnt(12)
	v_mul_f32_e32 v220, v15, v157
	v_fmac_f32_e32 v220, v14, v156
	v_fmac_f32_e32 v220, v16, v158
	v_fmac_f32_e32 v220, v17, v159
	ds_read_b128 v[204:207], v128 offset:192
	s_waitcnt lgkmcnt(12)
	v_fmac_f32_e32 v220, v19, v161
	v_fmac_f32_e32 v220, v18, v160
	v_fmac_f32_e32 v220, v20, v162
	v_fmac_f32_e32 v220, v21, v163
	ds_read_b128 v[208:211], v128 offset:208
	s_waitcnt lgkmcnt(12)
	v_fmac_f32_e32 v220, v23, v165
	v_fmac_f32_e32 v220, v22, v164
	v_fmac_f32_e32 v220, v24, v166
	v_fmac_f32_e32 v220, v25, v167
	ds_read_b128 v[212:215], v128 offset:224
	s_waitcnt lgkmcnt(12)
	v_fmac_f32_e32 v220, v27, v169
	v_fmac_f32_e32 v220, v26, v168
	v_fmac_f32_e32 v220, v28, v170
	v_fmac_f32_e32 v220, v29, v171
	ds_read_b128 v[216:219], v128 offset:240
	s_waitcnt lgkmcnt(12)
	v_fmac_f32_e32 v220, v31, v173
	v_fmac_f32_e32 v220, v30, v172
	v_fmac_f32_e32 v220, v32, v174
	v_fmac_f32_e32 v220, v33, v175
	ds_read_b128 v[156:159], v128 offset:1024
	s_waitcnt lgkmcnt(12)
	v_fmac_f32_e32 v220, v35, v177
	v_fmac_f32_e32 v220, v34, v176
	v_fmac_f32_e32 v220, v36, v178
	v_fmac_f32_e32 v220, v37, v179
	ds_read_b128 v[160:163], v128 offset:1040
	s_waitcnt lgkmcnt(12)
	v_fmac_f32_e32 v220, v39, v181
	v_fmac_f32_e32 v220, v38, v180
	v_fmac_f32_e32 v220, v40, v182
	v_fmac_f32_e32 v220, v41, v183
	ds_read_b128 v[164:167], v128 offset:1056
	s_waitcnt lgkmcnt(12)
	v_fmac_f32_e32 v220, v43, v185
	v_fmac_f32_e32 v220, v42, v184
	v_fmac_f32_e32 v220, v44, v186
	v_fmac_f32_e32 v220, v45, v187
	ds_read_b128 v[168:171], v128 offset:1072
	s_waitcnt lgkmcnt(12)
	v_fmac_f32_e32 v220, v47, v189
	v_fmac_f32_e32 v220, v46, v188
	v_fmac_f32_e32 v220, v48, v190
	v_fmac_f32_e32 v220, v49, v191
	ds_read_b128 v[172:175], v128 offset:1088
	s_waitcnt lgkmcnt(12)
	v_fmac_f32_e32 v220, v51, v193
	v_fmac_f32_e32 v220, v50, v192
	v_fmac_f32_e32 v220, v52, v194
	v_fmac_f32_e32 v220, v53, v195
	ds_read_b128 v[176:179], v128 offset:1104
	s_waitcnt lgkmcnt(12)
	v_fmac_f32_e32 v220, v55, v197
	v_fmac_f32_e32 v220, v54, v196
	v_fmac_f32_e32 v220, v56, v198
	v_fmac_f32_e32 v220, v57, v199
	ds_read_b128 v[180:183], v128 offset:1120
	s_waitcnt lgkmcnt(12)
	v_fmac_f32_e32 v220, v59, v201
	v_fmac_f32_e32 v220, v58, v200
	v_fmac_f32_e32 v220, v60, v202
	v_fmac_f32_e32 v220, v61, v203
	ds_read_b128 v[184:187], v128 offset:1136
	s_waitcnt lgkmcnt(11)
	v_fmac_f32_e32 v220, v63, v205
	v_fmac_f32_e32 v220, v62, v204
	v_fmac_f32_e32 v220, v64, v206
	v_fmac_f32_e32 v220, v65, v207
	ds_read_b128 v[188:191], v128 offset:1152
	s_waitcnt lgkmcnt(11)
	v_fmac_f32_e32 v220, v67, v209
	v_fmac_f32_e32 v220, v66, v208
	v_fmac_f32_e32 v220, v68, v210
	v_fmac_f32_e32 v220, v69, v211
	ds_read_b128 v[192:195], v128 offset:1168
	s_waitcnt lgkmcnt(11)
	v_fmac_f32_e32 v220, v71, v213
	v_fmac_f32_e32 v220, v70, v212
	v_fmac_f32_e32 v220, v72, v214
	v_fmac_f32_e32 v220, v73, v215
	ds_read_b128 v[196:199], v128 offset:1184
	s_waitcnt lgkmcnt(11)
	v_fmac_f32_e32 v220, v75, v217
	v_fmac_f32_e32 v220, v74, v216
	v_fmac_f32_e32 v220, v76, v218
	v_fmac_f32_e32 v220, v77, v219
	ds_read_b128 v[200:203], v128 offset:1200
	v_mul_f32_e32 v13, v78, v220
	v_mul_f32_e32 v6, v13, v13
	s_nop 1
	v_mov_b32_dpp v6, v6 quad_perm:[1,0,3,2] row_mask:0xf bank_mask:0xf bound_ctrl:1
	v_fmac_f32_e32 v6, v13, v13
	s_nop 1
	v_add_f32_dpp v6, v6, v6 quad_perm:[2,3,0,1] row_mask:0xf bank_mask:0xf bound_ctrl:1
	s_nop 1
	v_add_f32_dpp v6, v6, v6 row_half_mirror row_mask:0xf bank_mask:0xf bound_ctrl:1
	s_nop 1
	v_add_f32_dpp v6, v6, v6 row_mirror row_mask:0xf bank_mask:0xf bound_ctrl:1
	v_mov_b32_e32 v7, v6
	s_nop 1
	v_permlane16_swap_b32_e32 v6, v7
	v_add_f32_e32 v6, v6, v7
	v_mov_b32_e32 v7, v6
	s_nop 1
	v_permlane32_swap_b32_e32 v6, v7
	s_and_saveexec_b64 s[2:3], s[0:1]
	v_add_f32_e32 v6, v6, v7
	v_mov_b32_e32 v7, s17
	ds_write_b32 v7, v6 offset:96
	s_or_b64 exec, exec, s[2:3]
	v_mov_b32_e32 v10, s83
	s_waitcnt lgkmcnt(12)
; #define LAS __attribute__((address_space(3)))
; #define DPPADD_(v, ctrl) ((v) + __builtin_bit_cast(float, __builtin_amdgcn_update_dpp(0, __builtin_bit_cast(int, (v)), (ctrl), 0xf, 0xf, true)))
; __device__ __forceinline__ float wave_sum_valu(float v) {
;     v = DPPADD_(v, 0xB1); v = DPPADD_(v, 0x4E); v = DPPADD_(v, 0x141); v = DPPADD_(v, 0x140);
;     { auto r = __builtin_amdgcn_permlane16_swap(__float_as_uint(v), __float_as_uint(v), false, false); v = __uint_as_float(r[0]) + __uint_as_float(r[1]); }
;     { auto r = __builtin_amdgcn_permlane32_swap(__float_as_uint(v), __float_as_uint(v), false, false); v = __uint_as_float(r[0]) + __uint_as_float(r[1]); }
;     return v;
; __device__ __forceinline__ void pool_phase(const Params& a, LAS unsigned char* lds) {
;     ...
;         for (int tt = 0; tt < 32; ++tt) { const int tl = half * 32 + tt; float acc = 0.f;
; #pragma unroll
;             for (int c4 = 0; c4 < 16; ++c4) { const f32x4 pv = *(const LAS f32x4*)(ps + tl * 256 + g * 64 + c4 * 4);
;                 acc += pv[0] * wreg[4 * c4] + pv[1] * wreg[4 * c4 + 1] + pv[2] * wreg[4 * c4 + 2] + pv[3] * wreg[4 * c4 + 3]; }
;             o[tt] = acc * pscale; const float s = wave_sum_valu(o[tt] * o[tt]);
;             if (lane == 0) ssl[g * 64 + tl] = s; }
	v_mul_f32_e32 v220, v15, v157
	v_fmac_f32_e32 v220, v14, v156
	v_fmac_f32_e32 v220, v16, v158
	v_fmac_f32_e32 v220, v17, v159
	ds_read_b128 v[204:207], v10 offset:192
	s_waitcnt lgkmcnt(12)
	v_fmac_f32_e32 v220, v19, v161
	v_fmac_f32_e32 v220, v18, v160
	v_fmac_f32_e32 v220, v20, v162
	v_fmac_f32_e32 v220, v21, v163
	ds_read_b128 v[208:211], v10 offset:208
	s_waitcnt lgkmcnt(12)
	v_fmac_f32_e32 v220, v23, v165
	v_fmac_f32_e32 v220, v22, v164
	v_fmac_f32_e32 v220, v24, v166
	v_fmac_f32_e32 v220, v25, v167
	ds_read_b128 v[212:215], v10 offset:224
	s_waitcnt lgkmcnt(12)
	v_fmac_f32_e32 v220, v27, v169
	v_fmac_f32_e32 v220, v26, v168
	v_fmac_f32_e32 v220, v28, v170
	v_fmac_f32_e32 v220, v29, v171
	ds_read_b128 v[216:219], v10 offset:240
	s_waitcnt lgkmcnt(12)
	v_fmac_f32_e32 v220, v31, v173
	v_fmac_f32_e32 v220, v30, v172
	v_fmac_f32_e32 v220, v32, v174
	v_fmac_f32_e32 v220, v33, v175
	ds_read_b128 v[156:159], v10 offset:1024
	s_waitcnt lgkmcnt(12)
	v_fmac_f32_e32 v220, v35, v177
	v_fmac_f32_e32 v220, v34, v176
	v_fmac_f32_e32 v220, v36, v178
	v_fmac_f32_e32 v220, v37, v179
	ds_read_b128 v[160:163], v10 offset:1040
	s_waitcnt lgkmcnt(12)
	v_fmac_f32_e32 v220, v39, v181
	v_fmac_f32_e32 v220, v38, v180
	v_fmac_f32_e32 v220, v40, v182
	v_fmac_f32_e32 v220, v41, v183
	ds_read_b128 v[164:167], v10 offset:1056
	s_waitcnt lgkmcnt(12)
	v_fmac_f32_e32 v220, v43, v185
	v_fmac_f32_e32 v220, v42, v184
	v_fmac_f32_e32 v220, v44, v186
	v_fmac_f32_e32 v220, v45, v187
	ds_read_b128 v[168:171], v10 offset:1072
	s_waitcnt lgkmcnt(12)
	v_fmac_f32_e32 v220, v47, v189
	v_fmac_f32_e32 v220, v46, v188
	v_fmac_f32_e32 v220, v48, v190
	v_fmac_f32_e32 v220, v49, v191
	ds_read_b128 v[172:175], v10 offset:1088
	s_waitcnt lgkmcnt(12)
	v_fmac_f32_e32 v220, v51, v193
	v_fmac_f32_e32 v220, v50, v192
	v_fmac_f32_e32 v220, v52, v194
	v_fmac_f32_e32 v220, v53, v195
	ds_read_b128 v[176:179], v10 offset:1104
	s_waitcnt lgkmcnt(12)
	v_fmac_f32_e32 v220, v55, v197
	v_fmac_f32_e32 v220, v54, v196
	v_fmac_f32_e32 v220, v56, v198
	v_fmac_f32_e32 v220, v57, v199
	ds_read_b128 v[180:183], v10 offset:1120
	s_waitcnt lgkmcnt(12)
	v_fmac_f32_e32 v220, v59, v201
	v_fmac_f32_e32 v220, v58, v200
	v_fmac_f32_e32 v220, v60, v202
	v_fmac_f32_e32 v220, v61, v203
	ds_read_b128 v[184:187], v10 offset:1136
	s_waitcnt lgkmcnt(11)
	v_fmac_f32_e32 v220, v63, v205
	v_fmac_f32_e32 v220, v62, v204
	v_fmac_f32_e32 v220, v64, v206
	v_fmac_f32_e32 v220, v65, v207
	ds_read_b128 v[188:191], v10 offset:1152
	s_waitcnt lgkmcnt(11)
	v_fmac_f32_e32 v220, v67, v209
	v_fmac_f32_e32 v220, v66, v208
	v_fmac_f32_e32 v220, v68, v210
	v_fmac_f32_e32 v220, v69, v211
	ds_read_b128 v[192:195], v10 offset:1168
	s_waitcnt lgkmcnt(11)
	v_fmac_f32_e32 v220, v71, v213
	v_fmac_f32_e32 v220, v70, v212
	v_fmac_f32_e32 v220, v72, v214
	v_fmac_f32_e32 v220, v73, v215
	ds_read_b128 v[196:199], v10 offset:1184
	s_waitcnt lgkmcnt(11)
	v_fmac_f32_e32 v220, v75, v217
	v_fmac_f32_e32 v220, v74, v216
	v_fmac_f32_e32 v220, v76, v218
	v_fmac_f32_e32 v220, v77, v219
	ds_read_b128 v[200:203], v10 offset:1200
	v_mul_f32_e32 v12, v78, v220
	v_mul_f32_e32 v6, v12, v12
	s_nop 1
	v_mov_b32_dpp v6, v6 quad_perm:[1,0,3,2] row_mask:0xf bank_mask:0xf bound_ctrl:1
	v_fmac_f32_e32 v6, v12, v12
	s_nop 1
	v_add_f32_dpp v6, v6, v6 quad_perm:[2,3,0,1] row_mask:0xf bank_mask:0xf bound_ctrl:1
	s_nop 1
	v_add_f32_dpp v6, v6, v6 row_half_mirror row_mask:0xf bank_mask:0xf bound_ctrl:1
	s_nop 1
	v_add_f32_dpp v6, v6, v6 row_mirror row_mask:0xf bank_mask:0xf bound_ctrl:1
	v_mov_b32_e32 v7, v6
	s_nop 1
	v_permlane16_swap_b32_e32 v6, v7
	v_add_f32_e32 v6, v6, v7
	v_mov_b32_e32 v7, v6
	s_nop 1
	v_permlane32_swap_b32_e32 v6, v7
	s_and_saveexec_b64 s[2:3], s[0:1]
	v_add_f32_e32 v6, v6, v7
	v_mov_b32_e32 v7, s17
	ds_write_b32 v7, v6 offset:100
	s_or_b64 exec, exec, s[2:3]
	v_mov_b32_e32 v10, s84
	s_waitcnt lgkmcnt(12)
	v_mul_f32_e32 v220, v15, v157
	v_fmac_f32_e32 v220, v14, v156
	v_fmac_f32_e32 v220, v16, v158
	v_fmac_f32_e32 v220, v17, v159
	ds_read_b128 v[204:207], v10 offset:192
	s_waitcnt lgkmcnt(12)
	v_fmac_f32_e32 v220, v19, v161
	v_fmac_f32_e32 v220, v18, v160
	v_fmac_f32_e32 v220, v20, v162
	v_fmac_f32_e32 v220, v21, v163
	ds_read_b128 v[208:211], v10 offset:208
	s_waitcnt lgkmcnt(12)
	v_fmac_f32_e32 v220, v23, v165
	v_fmac_f32_e32 v220, v22, v164
	v_fmac_f32_e32 v220, v24, v166
	v_fmac_f32_e32 v220, v25, v167
	ds_read_b128 v[212:215], v10 offset:224
	s_waitcnt lgkmcnt(12)
	v_fmac_f32_e32 v220, v27, v169
	v_fmac_f32_e32 v220, v26, v168
	v_fmac_f32_e32 v220, v28, v170
	v_fmac_f32_e32 v220, v29, v171
	ds_read_b128 v[216:219], v10 offset:240
	s_waitcnt lgkmcnt(12)
	v_fmac_f32_e32 v220, v31, v173
	v_fmac_f32_e32 v220, v30, v172
	v_fmac_f32_e32 v220, v32, v174
	v_fmac_f32_e32 v220, v33, v175
	ds_read_b128 v[156:159], v10 offset:1024
	s_waitcnt lgkmcnt(12)
	v_fmac_f32_e32 v220, v35, v177
	v_fmac_f32_e32 v220, v34, v176
	v_fmac_f32_e32 v220, v36, v178
	v_fmac_f32_e32 v220, v37, v179
	ds_read_b128 v[160:163], v10 offset:1040
	s_waitcnt lgkmcnt(12)
	v_fmac_f32_e32 v220, v39, v181
	v_fmac_f32_e32 v220, v38, v180
	v_fmac_f32_e32 v220, v40, v182
	v_fmac_f32_e32 v220, v41, v183
	ds_read_b128 v[164:167], v10 offset:1056
	s_waitcnt lgkmcnt(12)
	v_fmac_f32_e32 v220, v43, v185
	v_fmac_f32_e32 v220, v42, v184
	v_fmac_f32_e32 v220, v44, v186
	v_fmac_f32_e32 v220, v45, v187
	ds_read_b128 v[168:171], v10 offset:1072
	s_waitcnt lgkmcnt(12)
	v_fmac_f32_e32 v220, v47, v189
	v_fmac_f32_e32 v220, v46, v188
	v_fmac_f32_e32 v220, v48, v190
	v_fmac_f32_e32 v220, v49, v191
	ds_read_b128 v[172:175], v10 offset:1088
	s_waitcnt lgkmcnt(12)
; #define LAS __attribute__((address_space(3)))
; #define DPPADD_(v, ctrl) ((v) + __builtin_bit_cast(float, __builtin_amdgcn_update_dpp(0, __builtin_bit_cast(int, (v)), (ctrl), 0xf, 0xf, true)))
; __device__ __forceinline__ float wave_sum_valu(float v) {
;     v = DPPADD_(v, 0xB1); v = DPPADD_(v, 0x4E); v = DPPADD_(v, 0x141); v = DPPADD_(v, 0x140);
;     { auto r = __builtin_amdgcn_permlane16_swap(__float_as_uint(v), __float_as_uint(v), false, false); v = __uint_as_float(r[0]) + __uint_as_float(r[1]); }
;     { auto r = __builtin_amdgcn_permlane32_swap(__float_as_uint(v), __float_as_uint(v), false, false); v = __uint_as_float(r[0]) + __uint_as_float(r[1]); }
;     return v;
; __device__ __forceinline__ void pool_phase(const Params& a, LAS unsigned char* lds) {
;     ...
;         for (int tt = 0; tt < 32; ++tt) { const int tl = half * 32 + tt; float acc = 0.f;
; #pragma unroll
;             for (int c4 = 0; c4 < 16; ++c4) { const f32x4 pv = *(const LAS f32x4*)(ps + tl * 256 + g * 64 + c4 * 4);
;                 acc += pv[0] * wreg[4 * c4] + pv[1] * wreg[4 * c4 + 1] + pv[2] * wreg[4 * c4 + 2] + pv[3] * wreg[4 * c4 + 3]; }
;             o[tt] = acc * pscale; const float s = wave_sum_valu(o[tt] * o[tt]);
;             if (lane == 0) ssl[g * 64 + tl] = s; }
	v_fmac_f32_e32 v220, v51, v193
	v_fmac_f32_e32 v220, v50, v192
	v_fmac_f32_e32 v220, v52, v194
	v_fmac_f32_e32 v220, v53, v195
	ds_read_b128 v[176:179], v10 offset:1104
	s_waitcnt lgkmcnt(12)
	v_fmac_f32_e32 v220, v55, v197
	v_fmac_f32_e32 v220, v54, v196
	v_fmac_f32_e32 v220, v56, v198
	v_fmac_f32_e32 v220, v57, v199
	ds_read_b128 v[180:183], v10 offset:1120
	s_waitcnt lgkmcnt(12)
	v_fmac_f32_e32 v220, v59, v201
	v_fmac_f32_e32 v220, v58, v200
	v_fmac_f32_e32 v220, v60, v202
	v_fmac_f32_e32 v220, v61, v203
	ds_read_b128 v[184:187], v10 offset:1136
	s_waitcnt lgkmcnt(11)
	v_fmac_f32_e32 v220, v63, v205
	v_fmac_f32_e32 v220, v62, v204
	v_fmac_f32_e32 v220, v64, v206
	v_fmac_f32_e32 v220, v65, v207
	ds_read_b128 v[188:191], v10 offset:1152
	s_waitcnt lgkmcnt(11)
	v_fmac_f32_e32 v220, v67, v209
	v_fmac_f32_e32 v220, v66, v208
	v_fmac_f32_e32 v220, v68, v210
	v_fmac_f32_e32 v220, v69, v211
	ds_read_b128 v[192:195], v10 offset:1168
	s_waitcnt lgkmcnt(11)
	v_fmac_f32_e32 v220, v71, v213
	v_fmac_f32_e32 v220, v70, v212
	v_fmac_f32_e32 v220, v72, v214
	v_fmac_f32_e32 v220, v73, v215
	ds_read_b128 v[196:199], v10 offset:1184
	s_waitcnt lgkmcnt(11)
	v_fmac_f32_e32 v220, v75, v217
	v_fmac_f32_e32 v220, v74, v216
	v_fmac_f32_e32 v220, v76, v218
	v_fmac_f32_e32 v220, v77, v219
	ds_read_b128 v[200:203], v10 offset:1200
	v_mul_f32_e32 v11, v78, v220
	v_mul_f32_e32 v6, v11, v11
	s_nop 1
	v_mov_b32_dpp v6, v6 quad_perm:[1,0,3,2] row_mask:0xf bank_mask:0xf bound_ctrl:1
	v_fmac_f32_e32 v6, v11, v11
	s_nop 1
	v_add_f32_dpp v6, v6, v6 quad_perm:[2,3,0,1] row_mask:0xf bank_mask:0xf bound_ctrl:1
	s_nop 1
	v_add_f32_dpp v6, v6, v6 row_half_mirror row_mask:0xf bank_mask:0xf bound_ctrl:1
	s_nop 1
	v_add_f32_dpp v6, v6, v6 row_mirror row_mask:0xf bank_mask:0xf bound_ctrl:1
	v_mov_b32_e32 v7, v6
	s_nop 1
	v_permlane16_swap_b32_e32 v6, v7
	v_add_f32_e32 v6, v6, v7
	v_mov_b32_e32 v7, v6
	s_nop 1
	v_permlane32_swap_b32_e32 v6, v7
	s_and_saveexec_b64 s[2:3], s[0:1]
	v_add_f32_e32 v6, v6, v7
	v_mov_b32_e32 v7, s17
	ds_write_b32 v7, v6 offset:104
	s_or_b64 exec, exec, s[2:3]
	v_mov_b32_e32 v10, s85
	s_waitcnt lgkmcnt(12)
	v_mul_f32_e32 v220, v15, v157
	v_fmac_f32_e32 v220, v14, v156
	v_fmac_f32_e32 v220, v16, v158
	v_fmac_f32_e32 v220, v17, v159
	ds_read_b128 v[204:207], v10 offset:192
	s_waitcnt lgkmcnt(12)
	v_fmac_f32_e32 v220, v19, v161
	v_fmac_f32_e32 v220, v18, v160
	v_fmac_f32_e32 v220, v20, v162
	v_fmac_f32_e32 v220, v21, v163
	ds_read_b128 v[208:211], v10 offset:208
	s_waitcnt lgkmcnt(12)
	v_fmac_f32_e32 v220, v23, v165
	v_fmac_f32_e32 v220, v22, v164
	v_fmac_f32_e32 v220, v24, v166
	v_fmac_f32_e32 v220, v25, v167
	ds_read_b128 v[212:215], v10 offset:224
	s_waitcnt lgkmcnt(12)
	v_fmac_f32_e32 v220, v27, v169
	v_fmac_f32_e32 v220, v26, v168
	v_fmac_f32_e32 v220, v28, v170
	v_fmac_f32_e32 v220, v29, v171
	ds_read_b128 v[216:219], v10 offset:240
	s_waitcnt lgkmcnt(12)
	v_fmac_f32_e32 v220, v31, v173
	v_fmac_f32_e32 v220, v30, v172
	v_fmac_f32_e32 v220, v32, v174
	v_fmac_f32_e32 v220, v33, v175
	ds_read_b128 v[156:159], v10 offset:1024
	s_waitcnt lgkmcnt(12)
	v_fmac_f32_e32 v220, v35, v177
	v_fmac_f32_e32 v220, v34, v176
	v_fmac_f32_e32 v220, v36, v178
	v_fmac_f32_e32 v220, v37, v179
	ds_read_b128 v[160:163], v10 offset:1040
	s_waitcnt lgkmcnt(12)
	v_fmac_f32_e32 v220, v39, v181
	v_fmac_f32_e32 v220, v38, v180
	v_fmac_f32_e32 v220, v40, v182
	v_fmac_f32_e32 v220, v41, v183
	ds_read_b128 v[164:167], v10 offset:1056
	s_waitcnt lgkmcnt(12)
	v_fmac_f32_e32 v220, v43, v185
	v_fmac_f32_e32 v220, v42, v184
	v_fmac_f32_e32 v220, v44, v186
	v_fmac_f32_e32 v220, v45, v187
	ds_read_b128 v[168:171], v10 offset:1072
	s_waitcnt lgkmcnt(12)
	v_fmac_f32_e32 v220, v47, v189
	v_fmac_f32_e32 v220, v46, v188
	v_fmac_f32_e32 v220, v48, v190
	v_fmac_f32_e32 v220, v49, v191
	ds_read_b128 v[172:175], v10 offset:1088
	s_waitcnt lgkmcnt(12)
	v_fmac_f32_e32 v220, v51, v193
	v_fmac_f32_e32 v220, v50, v192
	v_fmac_f32_e32 v220, v52, v194
	v_fmac_f32_e32 v220, v53, v195
	ds_read_b128 v[176:179], v10 offset:1104
	s_waitcnt lgkmcnt(12)
	v_fmac_f32_e32 v220, v55, v197
	v_fmac_f32_e32 v220, v54, v196
	v_fmac_f32_e32 v220, v56, v198
	v_fmac_f32_e32 v220, v57, v199
	ds_read_b128 v[180:183], v10 offset:1120
	s_waitcnt lgkmcnt(12)
	v_fmac_f32_e32 v220, v59, v201
	v_fmac_f32_e32 v220, v58, v200
	v_fmac_f32_e32 v220, v60, v202
	v_fmac_f32_e32 v220, v61, v203
	ds_read_b128 v[184:187], v10 offset:1136
	s_waitcnt lgkmcnt(11)
	v_fmac_f32_e32 v220, v63, v205
	v_fmac_f32_e32 v220, v62, v204
	v_fmac_f32_e32 v220, v64, v206
	v_fmac_f32_e32 v220, v65, v207
	ds_read_b128 v[188:191], v10 offset:1152
	s_waitcnt lgkmcnt(11)
	v_fmac_f32_e32 v220, v67, v209
	v_fmac_f32_e32 v220, v66, v208
	v_fmac_f32_e32 v220, v68, v210
	v_fmac_f32_e32 v220, v69, v211
	ds_read_b128 v[192:195], v10 offset:1168
	s_waitcnt lgkmcnt(11)
	v_fmac_f32_e32 v220, v71, v213
	v_fmac_f32_e32 v220, v70, v212
	v_fmac_f32_e32 v220, v72, v214
	v_fmac_f32_e32 v220, v73, v215
	ds_read_b128 v[196:199], v10 offset:1184
	s_waitcnt lgkmcnt(11)
	v_fmac_f32_e32 v220, v75, v217
	v_fmac_f32_e32 v220, v74, v216
	v_fmac_f32_e32 v220, v76, v218
	v_fmac_f32_e32 v220, v77, v219
	ds_read_b128 v[200:203], v10 offset:1200
	v_mul_f32_e32 v10, v78, v220
	v_mul_f32_e32 v6, v10, v10
	s_nop 1
	v_mov_b32_dpp v6, v6 quad_perm:[1,0,3,2] row_mask:0xf bank_mask:0xf bound_ctrl:1
	v_fmac_f32_e32 v6, v10, v10
	s_nop 1
	v_add_f32_dpp v6, v6, v6 quad_perm:[2,3,0,1] row_mask:0xf bank_mask:0xf bound_ctrl:1
	s_nop 1
	v_add_f32_dpp v6, v6, v6 row_half_mirror row_mask:0xf bank_mask:0xf bound_ctrl:1
	s_nop 1
	v_add_f32_dpp v6, v6, v6 row_mirror row_mask:0xf bank_mask:0xf bound_ctrl:1
	v_mov_b32_e32 v7, v6
	s_nop 1
	v_permlane16_swap_b32_e32 v6, v7
	v_add_f32_e32 v6, v6, v7
	v_mov_b32_e32 v7, v6
	s_nop 1
	v_permlane32_swap_b32_e32 v6, v7
	s_and_saveexec_b64 s[2:3], s[0:1]
	v_add_f32_e32 v6, v6, v7
	v_mov_b32_e32 v7, s17
	ds_write_b32 v7, v6 offset:108
	s_or_b64 exec, exec, s[2:3]
	v_mov_b32_e32 v132, s86
	s_waitcnt lgkmcnt(12)
; #define LAS __attribute__((address_space(3)))
; #define DPPADD_(v, ctrl) ((v) + __builtin_bit_cast(float, __builtin_amdgcn_update_dpp(0, __builtin_bit_cast(int, (v)), (ctrl), 0xf, 0xf, true)))
; __device__ __forceinline__ float wave_sum_valu(float v) {
;     v = DPPADD_(v, 0xB1); v = DPPADD_(v, 0x4E); v = DPPADD_(v, 0x141); v = DPPADD_(v, 0x140);
;     { auto r = __builtin_amdgcn_permlane16_swap(__float_as_uint(v), __float_as_uint(v), false, false); v = __uint_as_float(r[0]) + __uint_as_float(r[1]); }
;     { auto r = __builtin_amdgcn_permlane32_swap(__float_as_uint(v), __float_as_uint(v), false, false); v = __uint_as_float(r[0]) + __uint_as_float(r[1]); }
;     return v;
; __device__ __forceinline__ void pool_phase(const Params& a, LAS unsigned char* lds) {
;     ...
;         for (int tt = 0; tt < 32; ++tt) { const int tl = half * 32 + tt; float acc = 0.f;
; #pragma unroll
;             for (int c4 = 0; c4 < 16; ++c4) { const f32x4 pv = *(const LAS f32x4*)(ps + tl * 256 + g * 64 + c4 * 4);
;                 acc += pv[0] * wreg[4 * c4] + pv[1] * wreg[4 * c4 + 1] + pv[2] * wreg[4 * c4 + 2] + pv[3] * wreg[4 * c4 + 3]; }
;             o[tt] = acc * pscale; const float s = wave_sum_valu(o[tt] * o[tt]);
;             if (lane == 0) ssl[g * 64 + tl] = s; }
	v_mul_f32_e32 v220, v15, v157
	v_fmac_f32_e32 v220, v14, v156
	v_fmac_f32_e32 v220, v16, v158
	v_fmac_f32_e32 v220, v17, v159
	ds_read_b128 v[204:207], v132 offset:192
	s_waitcnt lgkmcnt(12)
	v_fmac_f32_e32 v220, v19, v161
	v_fmac_f32_e32 v220, v18, v160
	v_fmac_f32_e32 v220, v20, v162
	v_fmac_f32_e32 v220, v21, v163
	ds_read_b128 v[208:211], v132 offset:208
	s_waitcnt lgkmcnt(12)
	v_fmac_f32_e32 v220, v23, v165
	v_fmac_f32_e32 v220, v22, v164
	v_fmac_f32_e32 v220, v24, v166
	v_fmac_f32_e32 v220, v25, v167
	ds_read_b128 v[212:215], v132 offset:224
	s_waitcnt lgkmcnt(12)
	v_fmac_f32_e32 v220, v27, v169
	v_fmac_f32_e32 v220, v26, v168
	v_fmac_f32_e32 v220, v28, v170
	v_fmac_f32_e32 v220, v29, v171
	ds_read_b128 v[216:219], v132 offset:240
	s_waitcnt lgkmcnt(12)
	v_fmac_f32_e32 v220, v31, v173
	v_fmac_f32_e32 v220, v30, v172
	v_fmac_f32_e32 v220, v32, v174
	v_fmac_f32_e32 v220, v33, v175
	ds_read_b128 v[156:159], v132 offset:1024
	s_waitcnt lgkmcnt(12)
	v_fmac_f32_e32 v220, v35, v177
	v_fmac_f32_e32 v220, v34, v176
	v_fmac_f32_e32 v220, v36, v178
	v_fmac_f32_e32 v220, v37, v179
	ds_read_b128 v[160:163], v132 offset:1040
	s_waitcnt lgkmcnt(12)
	v_fmac_f32_e32 v220, v39, v181
	v_fmac_f32_e32 v220, v38, v180
	v_fmac_f32_e32 v220, v40, v182
	v_fmac_f32_e32 v220, v41, v183
	ds_read_b128 v[164:167], v132 offset:1056
	s_waitcnt lgkmcnt(12)
	v_fmac_f32_e32 v220, v43, v185
	v_fmac_f32_e32 v220, v42, v184
	v_fmac_f32_e32 v220, v44, v186
	v_fmac_f32_e32 v220, v45, v187
	ds_read_b128 v[168:171], v132 offset:1072
	s_waitcnt lgkmcnt(12)
	v_fmac_f32_e32 v220, v47, v189
	v_fmac_f32_e32 v220, v46, v188
	v_fmac_f32_e32 v220, v48, v190
	v_fmac_f32_e32 v220, v49, v191
	ds_read_b128 v[172:175], v132 offset:1088
	s_waitcnt lgkmcnt(12)
	v_fmac_f32_e32 v220, v51, v193
	v_fmac_f32_e32 v220, v50, v192
	v_fmac_f32_e32 v220, v52, v194
	v_fmac_f32_e32 v220, v53, v195
	ds_read_b128 v[176:179], v132 offset:1104
	s_waitcnt lgkmcnt(12)
	v_fmac_f32_e32 v220, v55, v197
	v_fmac_f32_e32 v220, v54, v196
	v_fmac_f32_e32 v220, v56, v198
	v_fmac_f32_e32 v220, v57, v199
	ds_read_b128 v[180:183], v132 offset:1120
	s_waitcnt lgkmcnt(12)
	v_fmac_f32_e32 v220, v59, v201
	v_fmac_f32_e32 v220, v58, v200
	v_fmac_f32_e32 v220, v60, v202
	v_fmac_f32_e32 v220, v61, v203
	ds_read_b128 v[184:187], v132 offset:1136
	s_waitcnt lgkmcnt(11)
	v_fmac_f32_e32 v220, v63, v205
	v_fmac_f32_e32 v220, v62, v204
	v_fmac_f32_e32 v220, v64, v206
	v_fmac_f32_e32 v220, v65, v207
	ds_read_b128 v[188:191], v132 offset:1152
	s_waitcnt lgkmcnt(11)
	v_fmac_f32_e32 v220, v67, v209
	v_fmac_f32_e32 v220, v66, v208
	v_fmac_f32_e32 v220, v68, v210
	v_fmac_f32_e32 v220, v69, v211
	ds_read_b128 v[192:195], v132 offset:1168
	s_waitcnt lgkmcnt(11)
	v_fmac_f32_e32 v220, v71, v213
	v_fmac_f32_e32 v220, v70, v212
	v_fmac_f32_e32 v220, v72, v214
	v_fmac_f32_e32 v220, v73, v215
	ds_read_b128 v[196:199], v132 offset:1184
	s_waitcnt lgkmcnt(11)
	v_fmac_f32_e32 v220, v75, v217
	v_fmac_f32_e32 v220, v74, v216
	v_fmac_f32_e32 v220, v76, v218
	v_fmac_f32_e32 v220, v77, v219
	ds_read_b128 v[200:203], v132 offset:1200
	v_mul_f32_e32 v9, v78, v220
	v_mul_f32_e32 v6, v9, v9
	s_nop 1
	v_mov_b32_dpp v6, v6 quad_perm:[1,0,3,2] row_mask:0xf bank_mask:0xf bound_ctrl:1
	v_fmac_f32_e32 v6, v9, v9
	s_nop 1
	v_add_f32_dpp v6, v6, v6 quad_perm:[2,3,0,1] row_mask:0xf bank_mask:0xf bound_ctrl:1
	s_nop 1
	v_add_f32_dpp v6, v6, v6 row_half_mirror row_mask:0xf bank_mask:0xf bound_ctrl:1
	s_nop 1
	v_add_f32_dpp v6, v6, v6 row_mirror row_mask:0xf bank_mask:0xf bound_ctrl:1
	v_mov_b32_e32 v7, v6
	s_nop 1
	v_permlane16_swap_b32_e32 v6, v7
	v_add_f32_e32 v6, v6, v7
	v_mov_b32_e32 v7, v6
	s_nop 1
	v_permlane32_swap_b32_e32 v6, v7
	s_and_saveexec_b64 s[2:3], s[0:1]
	v_add_f32_e32 v6, v6, v7
	v_mov_b32_e32 v7, s17
	ds_write_b32 v7, v6 offset:112
	s_or_b64 exec, exec, s[2:3]
	v_mov_b32_e32 v6, s87
	s_waitcnt lgkmcnt(12)
	v_mul_f32_e32 v220, v15, v157
	v_fmac_f32_e32 v220, v14, v156
	v_fmac_f32_e32 v220, v16, v158
	v_fmac_f32_e32 v220, v17, v159
	ds_read_b128 v[204:207], v6 offset:192
	s_waitcnt lgkmcnt(12)
	v_fmac_f32_e32 v220, v19, v161
	v_fmac_f32_e32 v220, v18, v160
	v_fmac_f32_e32 v220, v20, v162
	v_fmac_f32_e32 v220, v21, v163
	ds_read_b128 v[208:211], v6 offset:208
	s_waitcnt lgkmcnt(12)
	v_fmac_f32_e32 v220, v23, v165
	v_fmac_f32_e32 v220, v22, v164
	v_fmac_f32_e32 v220, v24, v166
	v_fmac_f32_e32 v220, v25, v167
	ds_read_b128 v[212:215], v6 offset:224
	s_waitcnt lgkmcnt(12)
	v_fmac_f32_e32 v220, v27, v169
	v_fmac_f32_e32 v220, v26, v168
	v_fmac_f32_e32 v220, v28, v170
	v_fmac_f32_e32 v220, v29, v171
	ds_read_b128 v[216:219], v6 offset:240
	s_waitcnt lgkmcnt(12)
	v_fmac_f32_e32 v220, v31, v173
	v_fmac_f32_e32 v220, v30, v172
	v_fmac_f32_e32 v220, v32, v174
	v_fmac_f32_e32 v220, v33, v175
	ds_read_b128 v[156:159], v6 offset:1024
	s_waitcnt lgkmcnt(12)
	v_fmac_f32_e32 v220, v35, v177
	v_fmac_f32_e32 v220, v34, v176
	v_fmac_f32_e32 v220, v36, v178
	v_fmac_f32_e32 v220, v37, v179
	ds_read_b128 v[160:163], v6 offset:1040
	s_waitcnt lgkmcnt(12)
	v_fmac_f32_e32 v220, v39, v181
	v_fmac_f32_e32 v220, v38, v180
	v_fmac_f32_e32 v220, v40, v182
	v_fmac_f32_e32 v220, v41, v183
	ds_read_b128 v[164:167], v6 offset:1056
	s_waitcnt lgkmcnt(12)
	v_fmac_f32_e32 v220, v43, v185
	v_fmac_f32_e32 v220, v42, v184
	v_fmac_f32_e32 v220, v44, v186
	v_fmac_f32_e32 v220, v45, v187
	ds_read_b128 v[168:171], v6 offset:1072
	s_waitcnt lgkmcnt(12)
	v_fmac_f32_e32 v220, v47, v189
	v_fmac_f32_e32 v220, v46, v188
	v_fmac_f32_e32 v220, v48, v190
	v_fmac_f32_e32 v220, v49, v191
	ds_read_b128 v[172:175], v6 offset:1088
	s_waitcnt lgkmcnt(12)
; #define LAS __attribute__((address_space(3)))
; #define DPPADD_(v, ctrl) ((v) + __builtin_bit_cast(float, __builtin_amdgcn_update_dpp(0, __builtin_bit_cast(int, (v)), (ctrl), 0xf, 0xf, true)))
; __device__ __forceinline__ float wave_sum_valu(float v) {
;     v = DPPADD_(v, 0xB1); v = DPPADD_(v, 0x4E); v = DPPADD_(v, 0x141); v = DPPADD_(v, 0x140);
;     { auto r = __builtin_amdgcn_permlane16_swap(__float_as_uint(v), __float_as_uint(v), false, false); v = __uint_as_float(r[0]) + __uint_as_float(r[1]); }
;     { auto r = __builtin_amdgcn_permlane32_swap(__float_as_uint(v), __float_as_uint(v), false, false); v = __uint_as_float(r[0]) + __uint_as_float(r[1]); }
;     return v;
; __device__ __forceinline__ void pool_phase(const Params& a, LAS unsigned char* lds) {
;     ...
;         for (int tt = 0; tt < 32; ++tt) { const int tl = half * 32 + tt; float acc = 0.f;
; #pragma unroll
;             for (int c4 = 0; c4 < 16; ++c4) { const f32x4 pv = *(const LAS f32x4*)(ps + tl * 256 + g * 64 + c4 * 4);
;                 acc += pv[0] * wreg[4 * c4] + pv[1] * wreg[4 * c4 + 1] + pv[2] * wreg[4 * c4 + 2] + pv[3] * wreg[4 * c4 + 3]; }
;             o[tt] = acc * pscale; const float s = wave_sum_valu(o[tt] * o[tt]);
;             if (lane == 0) ssl[g * 64 + tl] = s; }
	v_fmac_f32_e32 v220, v51, v193
	v_fmac_f32_e32 v220, v50, v192
	v_fmac_f32_e32 v220, v52, v194
	v_fmac_f32_e32 v220, v53, v195
	ds_read_b128 v[176:179], v6 offset:1104
	s_waitcnt lgkmcnt(12)
	v_fmac_f32_e32 v220, v55, v197
	v_fmac_f32_e32 v220, v54, v196
	v_fmac_f32_e32 v220, v56, v198
	v_fmac_f32_e32 v220, v57, v199
	ds_read_b128 v[180:183], v6 offset:1120
	s_waitcnt lgkmcnt(12)
	v_fmac_f32_e32 v220, v59, v201
	v_fmac_f32_e32 v220, v58, v200
	v_fmac_f32_e32 v220, v60, v202
	v_fmac_f32_e32 v220, v61, v203
	ds_read_b128 v[184:187], v6 offset:1136
	s_waitcnt lgkmcnt(11)
	v_fmac_f32_e32 v220, v63, v205
	v_fmac_f32_e32 v220, v62, v204
	v_fmac_f32_e32 v220, v64, v206
	v_fmac_f32_e32 v220, v65, v207
	ds_read_b128 v[188:191], v6 offset:1152
	s_waitcnt lgkmcnt(11)
	v_fmac_f32_e32 v220, v67, v209
	v_fmac_f32_e32 v220, v66, v208
	v_fmac_f32_e32 v220, v68, v210
	v_fmac_f32_e32 v220, v69, v211
	ds_read_b128 v[192:195], v6 offset:1168
	s_waitcnt lgkmcnt(11)
	v_fmac_f32_e32 v220, v71, v213
	v_fmac_f32_e32 v220, v70, v212
	v_fmac_f32_e32 v220, v72, v214
	v_fmac_f32_e32 v220, v73, v215
	ds_read_b128 v[196:199], v6 offset:1184
	s_waitcnt lgkmcnt(11)
	v_fmac_f32_e32 v220, v75, v217
	v_fmac_f32_e32 v220, v74, v216
	v_fmac_f32_e32 v220, v76, v218
	v_fmac_f32_e32 v220, v77, v219
	ds_read_b128 v[200:203], v6 offset:1200
	v_mul_f32_e32 v8, v78, v220
	v_mul_f32_e32 v6, v8, v8
	s_nop 1
	v_mov_b32_dpp v6, v6 quad_perm:[1,0,3,2] row_mask:0xf bank_mask:0xf bound_ctrl:1
	v_fmac_f32_e32 v6, v8, v8
	s_nop 1
	v_add_f32_dpp v6, v6, v6 quad_perm:[2,3,0,1] row_mask:0xf bank_mask:0xf bound_ctrl:1
	s_nop 1
	v_add_f32_dpp v6, v6, v6 row_half_mirror row_mask:0xf bank_mask:0xf bound_ctrl:1
	s_nop 1
	v_add_f32_dpp v6, v6, v6 row_mirror row_mask:0xf bank_mask:0xf bound_ctrl:1
	v_mov_b32_e32 v7, v6
	s_nop 1
	v_permlane16_swap_b32_e32 v6, v7
	v_add_f32_e32 v6, v6, v7
	v_mov_b32_e32 v7, v6
	s_nop 1
	v_permlane32_swap_b32_e32 v6, v7
	s_and_saveexec_b64 s[2:3], s[0:1]
	v_add_f32_e32 v6, v6, v7
	v_mov_b32_e32 v7, s17
	ds_write_b32 v7, v6 offset:116
	s_or_b64 exec, exec, s[2:3]
	v_mov_b32_e32 v6, s88
	s_waitcnt lgkmcnt(12)
	v_mul_f32_e32 v220, v15, v157
	v_fmac_f32_e32 v220, v14, v156
	v_fmac_f32_e32 v220, v16, v158
	v_fmac_f32_e32 v220, v17, v159
	ds_read_b128 v[204:207], v6 offset:192
	s_waitcnt lgkmcnt(12)
	v_fmac_f32_e32 v220, v19, v161
	v_fmac_f32_e32 v220, v18, v160
	v_fmac_f32_e32 v220, v20, v162
	v_fmac_f32_e32 v220, v21, v163
	ds_read_b128 v[208:211], v6 offset:208
	s_waitcnt lgkmcnt(12)
	v_fmac_f32_e32 v220, v23, v165
	v_fmac_f32_e32 v220, v22, v164
	v_fmac_f32_e32 v220, v24, v166
	v_fmac_f32_e32 v220, v25, v167
	ds_read_b128 v[212:215], v6 offset:224
	s_waitcnt lgkmcnt(12)
	v_fmac_f32_e32 v220, v27, v169
	v_fmac_f32_e32 v220, v26, v168
	v_fmac_f32_e32 v220, v28, v170
	v_fmac_f32_e32 v220, v29, v171
	ds_read_b128 v[216:219], v6 offset:240
	s_waitcnt lgkmcnt(12)
	v_fmac_f32_e32 v220, v31, v173
	v_fmac_f32_e32 v220, v30, v172
	v_fmac_f32_e32 v220, v32, v174
	v_fmac_f32_e32 v220, v33, v175
	ds_read_b128 v[156:159], v6 offset:1024
	s_waitcnt lgkmcnt(12)
	v_fmac_f32_e32 v220, v35, v177
	v_fmac_f32_e32 v220, v34, v176
	v_fmac_f32_e32 v220, v36, v178
	v_fmac_f32_e32 v220, v37, v179
	ds_read_b128 v[160:163], v6 offset:1040
	s_waitcnt lgkmcnt(12)
	v_fmac_f32_e32 v220, v39, v181
	v_fmac_f32_e32 v220, v38, v180
	v_fmac_f32_e32 v220, v40, v182
	v_fmac_f32_e32 v220, v41, v183
	ds_read_b128 v[164:167], v6 offset:1056
	s_waitcnt lgkmcnt(12)
	v_fmac_f32_e32 v220, v43, v185
	v_fmac_f32_e32 v220, v42, v184
	v_fmac_f32_e32 v220, v44, v186
	v_fmac_f32_e32 v220, v45, v187
	ds_read_b128 v[168:171], v6 offset:1072
	s_waitcnt lgkmcnt(12)
	v_fmac_f32_e32 v220, v47, v189
	v_fmac_f32_e32 v220, v46, v188
	v_fmac_f32_e32 v220, v48, v190
	v_fmac_f32_e32 v220, v49, v191
	ds_read_b128 v[172:175], v6 offset:1088
	s_waitcnt lgkmcnt(12)
	v_fmac_f32_e32 v220, v51, v193
	v_fmac_f32_e32 v220, v50, v192
	v_fmac_f32_e32 v220, v52, v194
	v_fmac_f32_e32 v220, v53, v195
	ds_read_b128 v[176:179], v6 offset:1104
	s_waitcnt lgkmcnt(12)
	v_fmac_f32_e32 v220, v55, v197
	v_fmac_f32_e32 v220, v54, v196
	v_fmac_f32_e32 v220, v56, v198
	v_fmac_f32_e32 v220, v57, v199
	ds_read_b128 v[180:183], v6 offset:1120
	s_waitcnt lgkmcnt(12)
	v_fmac_f32_e32 v220, v59, v201
	v_fmac_f32_e32 v220, v58, v200
	v_fmac_f32_e32 v220, v60, v202
	v_fmac_f32_e32 v220, v61, v203
	ds_read_b128 v[184:187], v6 offset:1136
	s_waitcnt lgkmcnt(11)
	v_fmac_f32_e32 v220, v63, v205
	v_fmac_f32_e32 v220, v62, v204
	v_fmac_f32_e32 v220, v64, v206
	v_fmac_f32_e32 v220, v65, v207
	ds_read_b128 v[188:191], v6 offset:1152
	s_waitcnt lgkmcnt(11)
; #define LAS __attribute__((address_space(3)))
; #define DPPADD_(v, ctrl) ((v) + __builtin_bit_cast(float, __builtin_amdgcn_update_dpp(0, __builtin_bit_cast(int, (v)), (ctrl), 0xf, 0xf, true)))
; __device__ __forceinline__ float wave_sum_valu(float v) {
;     v = DPPADD_(v, 0xB1); v = DPPADD_(v, 0x4E); v = DPPADD_(v, 0x141); v = DPPADD_(v, 0x140);
;     { auto r = __builtin_amdgcn_permlane16_swap(__float_as_uint(v), __float_as_uint(v), false, false); v = __uint_as_float(r[0]) + __uint_as_float(r[1]); }
;     { auto r = __builtin_amdgcn_permlane32_swap(__float_as_uint(v), __float_as_uint(v), false, false); v = __uint_as_float(r[0]) + __uint_as_float(r[1]); }
;     return v;
; __device__ __forceinline__ void pool_phase(const Params& a, LAS unsigned char* lds) {
;     ...
;         for (int tt = 0; tt < 32; ++tt) { const int tl = half * 32 + tt; float acc = 0.f;
; #pragma unroll
;             for (int c4 = 0; c4 < 16; ++c4) { const f32x4 pv = *(const LAS f32x4*)(ps + tl * 256 + g * 64 + c4 * 4);
;                 acc += pv[0] * wreg[4 * c4] + pv[1] * wreg[4 * c4 + 1] + pv[2] * wreg[4 * c4 + 2] + pv[3] * wreg[4 * c4 + 3]; }
;             o[tt] = acc * pscale; const float s = wave_sum_valu(o[tt] * o[tt]);
;             if (lane == 0) ssl[g * 64 + tl] = s; }
	v_fmac_f32_e32 v220, v67, v209
	v_fmac_f32_e32 v220, v66, v208
	v_fmac_f32_e32 v220, v68, v210
	v_fmac_f32_e32 v220, v69, v211
	ds_read_b128 v[192:195], v6 offset:1168
	s_waitcnt lgkmcnt(11)
	v_fmac_f32_e32 v220, v71, v213
	v_fmac_f32_e32 v220, v70, v212
	v_fmac_f32_e32 v220, v72, v214
	v_fmac_f32_e32 v220, v73, v215
	ds_read_b128 v[196:199], v6 offset:1184
	s_waitcnt lgkmcnt(11)
	v_fmac_f32_e32 v220, v75, v217
	v_fmac_f32_e32 v220, v74, v216
	v_fmac_f32_e32 v220, v76, v218
	v_fmac_f32_e32 v220, v77, v219
	ds_read_b128 v[200:203], v6 offset:1200
	v_mul_f32_e32 v7, v78, v220
	v_mul_f32_e32 v6, v7, v7
	s_nop 1
	v_mov_b32_dpp v6, v6 quad_perm:[1,0,3,2] row_mask:0xf bank_mask:0xf bound_ctrl:1
	v_fmac_f32_e32 v6, v7, v7
	s_nop 1
	v_add_f32_dpp v6, v6, v6 quad_perm:[2,3,0,1] row_mask:0xf bank_mask:0xf bound_ctrl:1
	s_nop 1
	v_add_f32_dpp v6, v6, v6 row_half_mirror row_mask:0xf bank_mask:0xf bound_ctrl:1
	s_nop 1
	v_add_f32_dpp v6, v6, v6 row_mirror row_mask:0xf bank_mask:0xf bound_ctrl:1
	v_mov_b32_e32 v120, v6
	s_nop 1
	v_permlane16_swap_b32_e32 v6, v120
	v_add_f32_e32 v6, v6, v120
	v_mov_b32_e32 v120, v6
	s_nop 1
	v_permlane32_swap_b32_e32 v6, v120
	s_and_saveexec_b64 s[2:3], s[0:1]
	v_add_f32_e32 v6, v6, v120
	v_mov_b32_e32 v120, s17
	ds_write_b32 v120, v6 offset:120
	s_or_b64 exec, exec, s[2:3]
	v_mov_b32_e32 v6, s89
	s_waitcnt lgkmcnt(12)
	v_mul_f32_e32 v220, v15, v157
	v_fmac_f32_e32 v220, v14, v156
	v_fmac_f32_e32 v220, v16, v158
	v_fmac_f32_e32 v220, v17, v159
	ds_read_b128 v[204:207], v6 offset:192
	s_waitcnt lgkmcnt(12)
	v_fmac_f32_e32 v220, v19, v161
	v_fmac_f32_e32 v220, v18, v160
	v_fmac_f32_e32 v220, v20, v162
	v_fmac_f32_e32 v220, v21, v163
	ds_read_b128 v[208:211], v6 offset:208
	s_waitcnt lgkmcnt(12)
	v_fmac_f32_e32 v220, v23, v165
	v_fmac_f32_e32 v220, v22, v164
	v_fmac_f32_e32 v220, v24, v166
	v_fmac_f32_e32 v220, v25, v167
	ds_read_b128 v[212:215], v6 offset:224
	s_waitcnt lgkmcnt(12)
	v_fmac_f32_e32 v220, v27, v169
	v_fmac_f32_e32 v220, v26, v168
	v_fmac_f32_e32 v220, v28, v170
	v_fmac_f32_e32 v220, v29, v171
	ds_read_b128 v[216:219], v6 offset:240
	s_waitcnt lgkmcnt(12)
	v_fmac_f32_e32 v220, v31, v173
	v_fmac_f32_e32 v220, v30, v172
	v_fmac_f32_e32 v220, v32, v174
	v_fmac_f32_e32 v220, v33, v175
	s_waitcnt lgkmcnt(11)
	v_fmac_f32_e32 v220, v35, v177
	v_fmac_f32_e32 v220, v34, v176
	v_fmac_f32_e32 v220, v36, v178
	v_fmac_f32_e32 v220, v37, v179
	s_waitcnt lgkmcnt(10)
	v_fmac_f32_e32 v220, v39, v181
	v_fmac_f32_e32 v220, v38, v180
	v_fmac_f32_e32 v220, v40, v182
	v_fmac_f32_e32 v220, v41, v183
	s_waitcnt lgkmcnt(9)
	v_fmac_f32_e32 v220, v43, v185
	v_fmac_f32_e32 v220, v42, v184
	v_fmac_f32_e32 v220, v44, v186
	v_fmac_f32_e32 v220, v45, v187
	s_waitcnt lgkmcnt(8)
	v_fmac_f32_e32 v220, v47, v189
	v_fmac_f32_e32 v220, v46, v188
	v_fmac_f32_e32 v220, v48, v190
	v_fmac_f32_e32 v220, v49, v191
	s_waitcnt lgkmcnt(7)
	v_fmac_f32_e32 v220, v51, v193
	v_fmac_f32_e32 v220, v50, v192
	v_fmac_f32_e32 v220, v52, v194
	v_fmac_f32_e32 v220, v53, v195
	s_waitcnt lgkmcnt(6)
	v_fmac_f32_e32 v220, v55, v197
	v_fmac_f32_e32 v220, v54, v196
	v_fmac_f32_e32 v220, v56, v198
	v_fmac_f32_e32 v220, v57, v199
	s_waitcnt lgkmcnt(5)
	v_fmac_f32_e32 v220, v59, v201
	v_fmac_f32_e32 v220, v58, v200
	v_fmac_f32_e32 v220, v60, v202
	v_fmac_f32_e32 v220, v61, v203
	s_waitcnt lgkmcnt(3)
	v_fmac_f32_e32 v220, v63, v205
	v_fmac_f32_e32 v220, v62, v204
	v_fmac_f32_e32 v220, v64, v206
	v_fmac_f32_e32 v220, v65, v207
	s_waitcnt lgkmcnt(2)
	v_fmac_f32_e32 v220, v67, v209
	v_fmac_f32_e32 v220, v66, v208
	v_fmac_f32_e32 v220, v68, v210
	v_fmac_f32_e32 v220, v69, v211
	s_waitcnt lgkmcnt(1)
	v_fmac_f32_e32 v220, v71, v213
	v_fmac_f32_e32 v220, v70, v212
	v_fmac_f32_e32 v220, v72, v214
	v_fmac_f32_e32 v220, v73, v215
	s_waitcnt lgkmcnt(0)
	v_fmac_f32_e32 v220, v75, v217
	v_fmac_f32_e32 v220, v74, v216
	v_fmac_f32_e32 v220, v76, v218
	v_fmac_f32_e32 v220, v77, v219
	v_mul_f32_e32 v6, v78, v220
	v_mul_f32_e32 v120, v6, v6
	s_nop 1
	v_mov_b32_dpp v120, v120 quad_perm:[1,0,3,2] row_mask:0xf bank_mask:0xf bound_ctrl:1
	v_fmac_f32_e32 v120, v6, v6
	s_nop 1
	v_add_f32_dpp v120, v120, v120 quad_perm:[2,3,0,1] row_mask:0xf bank_mask:0xf bound_ctrl:1
	s_nop 1
	v_add_f32_dpp v120, v120, v120 row_half_mirror row_mask:0xf bank_mask:0xf bound_ctrl:1
	s_nop 1
	v_add_f32_dpp v120, v120, v120 row_mirror row_mask:0xf bank_mask:0xf bound_ctrl:1
	v_mov_b32_e32 v121, v120
	s_nop 1
	v_permlane16_swap_b32_e32 v120, v121
	v_add_f32_e32 v120, v120, v121
	v_mov_b32_e32 v121, v120
	s_nop 1
	v_permlane32_swap_b32_e32 v120, v121
	s_and_saveexec_b64 s[2:3], s[0:1]
	s_cbranch_execz .LBB0_630
	v_readlane_b32 s8, v248, 25
	v_add_f32_e32 v120, v120, v121
	s_nop 0
	v_mov_b32_e32 v121, s8
	ds_write_b32 v121, v120
	s_branch .LBB0_630
